# acc zeroing via v_mov_b64; K-loop: pre-MFMA barrier moved below first 4 MFMAs of each phase (all 7 GEMM loops)
# speedup vs baseline: 1.0105x; 1.0063x over previous
;     __device__ __forceinline__ const char* aptr(const Unit& u) const { return (u.kind == 1 ? A1 : A0) + (size_t)u.pm * tstep; }
;     __device__ __forceinline__ const char* bptr(const Unit& u) const { return (u.kind == 1 ? B1 : B0) + (size_t)u.pn * tstep; }
; #define PG8_STAGE(bufoff, gbase, voff) do { _Pragma("unroll") for (int _i = 0; _i < 2; ++_i) \
;         __builtin_amdgcn_global_load_lds((const unsigned*)((const char*)(gbase) + (voff)[_i]), (LAS unsigned*)(lds + (bufoff) + ldsw + _i * 8192), 16, 0, 0); } while (0)
; #define PG8_LDA(dst, b, h) do { _Pragma("unroll") for (int m = 0; m < 4; ++m) _Pragma("unroll") for (int k = 0; k < 2; ++k) dst[m][k] = *(const LAS bf16x8*)(lds + PG8_SA(b, h) + aoff + m * 2048 + k * 1024); } while (0)
; #define PG8_LDB(dst, b, h) do { _Pragma("unroll") for (int n = 0; n < 2; ++n) _Pragma("unroll") for (int k = 0; k < 2; ++k) dst[n][k] = *(const LAS bf16x8*)(lds + PG8_SB(b, h) + boff + n * 2048 + k * 1024); } while (0)
; #define PG8_WAIT_V(n) asm volatile("s_waitcnt vmcnt(" #n ")" ::: "memory")
; template <class Epi, bool ALIGN_EPI, bool SP2>
; __device__ __forceinline__ void gemm_phase(LAS unsigned char* lds, const int K, const Sched& S, const Epi& E) {
;     ...
;     for (;;) {
;         const bool has_next = S.next(ui + 1, nxt);
;         const char* nA = has_next ? S.aptr(nxt) : cA; const char* nB = has_next ? S.bptr(nxt) : cB;
;         for (int t = 0; t < nt; t += 2) {
;             const bool last = (t == nt - 2);
;             const char* a1 = cA + (size_t)(t + 1) * kstep;
;             const char* a2 = last ? nA : cA + (size_t)(t + 2) * kstep; const char* b2 = last ? nB : cB + (size_t)(t + 2) * kstep;
;             const char* a3 = a2 + kstep; const char* b3 = b2 + kstep;
;             if constexpr (SP2) {
;             PG8_LDB(B0, 0, 0); PG8_LDB(B1, 0, 1); PG8_SCHED; PG8_LDA(At, 0, 0); PG8_STAGE(PG8_SA(1, 1), a1 + hstep, voffA);
;             PG8_WAIT_V(8); PG8_WAIT_L(0); PG8_BAR; PG8_MMA(0, 0, At, B0); PG8_MMA(0, 1, At, B1); PG8_BAR; PG8_SCHED;
;     ...
; #pragma unroll
;         for (int a = 0; a < 2; ++a)
; #pragma unroll
;             for (int b = 0; b < 2; ++b)
; #pragma unroll
;                 for (int m = 0; m < 4; ++m)
; #pragma unroll
;                     for (int n = 0; n < 2; ++n) acc[a][b][m][n] = (f32x4){0.f, 0.f, 0.f, 0.f};
;         cur = nxt; cA = nA; cB = nB; ++ui;
.LBB0_171:
	s_add_u32 s4, s4, 0x40080
	s_addc_u32 s5, s5, 0
	s_add_u32 s12, s70, 0x100
	v_mov_b64_e32 v[0:1], 0
	v_mov_b64_e32 v[2:3], 0
	v_mov_b64_e32 v[4:5], 0
	v_mov_b64_e32 v[6:7], 0
	v_mov_b64_e32 v[8:9], 0
	v_mov_b64_e32 v[10:11], 0
	v_mov_b64_e32 v[12:13], 0
	v_mov_b64_e32 v[14:15], 0
	v_mov_b64_e32 v[16:17], 0
	v_mov_b64_e32 v[18:19], 0
	v_mov_b64_e32 v[20:21], 0
	v_mov_b64_e32 v[22:23], 0
	v_mov_b64_e32 v[24:25], 0
	v_mov_b64_e32 v[26:27], 0
	v_mov_b64_e32 v[28:29], 0
	v_mov_b64_e32 v[30:31], 0
	v_mov_b64_e32 v[32:33], 0
	v_mov_b64_e32 v[34:35], 0
	v_mov_b64_e32 v[36:37], 0
	v_mov_b64_e32 v[38:39], 0
	v_mov_b64_e32 v[40:41], 0
	v_mov_b64_e32 v[42:43], 0
	v_mov_b64_e32 v[44:45], 0
	v_mov_b64_e32 v[46:47], 0
	v_mov_b64_e32 v[48:49], 0
	v_mov_b64_e32 v[50:51], 0
	v_mov_b64_e32 v[52:53], 0
	v_mov_b64_e32 v[54:55], 0
	v_mov_b64_e32 v[56:57], 0
	v_mov_b64_e32 v[58:59], 0
	v_mov_b64_e32 v[60:61], 0
	v_mov_b64_e32 v[62:63], 0
	v_mov_b64_e32 v[64:65], 0
	v_mov_b64_e32 v[66:67], 0
	v_mov_b64_e32 v[68:69], 0
	v_mov_b64_e32 v[70:71], 0
	v_mov_b64_e32 v[72:73], 0
	v_mov_b64_e32 v[74:75], 0
	v_mov_b64_e32 v[76:77], 0
	v_mov_b64_e32 v[78:79], 0
	v_mov_b64_e32 v[80:81], 0
	v_mov_b64_e32 v[82:83], 0
	v_mov_b64_e32 v[84:85], 0
	v_mov_b64_e32 v[86:87], 0
	v_mov_b64_e32 v[88:89], 0
	v_mov_b64_e32 v[90:91], 0
	v_mov_b64_e32 v[92:93], 0
	v_mov_b64_e32 v[94:95], 0
	v_mov_b64_e32 v[96:97], 0
	v_mov_b64_e32 v[98:99], 0
	v_mov_b64_e32 v[100:101], 0
	v_mov_b64_e32 v[102:103], 0
	v_mov_b64_e32 v[104:105], 0
	v_mov_b64_e32 v[106:107], 0
	v_mov_b64_e32 v[108:109], 0
	v_mov_b64_e32 v[110:111], 0
	v_mov_b64_e32 v[112:113], 0
	v_mov_b64_e32 v[114:115], 0
	v_mov_b64_e32 v[116:117], 0
	v_mov_b64_e32 v[118:119], 0
	v_mov_b64_e32 v[120:121], 0
	v_mov_b64_e32 v[122:123], 0
	v_mov_b64_e32 v[124:125], 0
	v_mov_b64_e32 v[126:127], 0
	s_addc_u32 s43, s71, 0
	s_mov_b32 s45, -2
	s_waitcnt lgkmcnt(0)
.LBB0_172:
	ds_read_b128 v[128:131], v212
	ds_read_b128 v[132:135], v212 offset:1024
	ds_read_b128 v[136:139], v212 offset:2048
	ds_read_b128 v[140:143], v212 offset:3072
	ds_read_b128 v[144:147], v213
	ds_read_b128 v[148:151], v213 offset:1024
	ds_read_b128 v[152:155], v213 offset:2048
	ds_read_b128 v[156:159], v213 offset:3072
	s_add_u32 s48, s4, 0xfffc0080
	s_addc_u32 s49, s5, -1
	s_cmp_eq_u32 s45, 12
	s_cselect_b32 s81, s47, s49
	s_cselect_b32 s80, s46, s48
	s_cselect_b32 s71, s83, s43
	s_cselect_b32 s70, s82, s12
	v_lshl_add_u64 v[204:205], s[4:5], 0, v[168:169]
	s_add_i32 m0, s9, 0xc000
	ds_read_b128 v[172:175], v214
	ds_read_b128 v[176:179], v214 offset:1024
	ds_read_b128 v[180:183], v214 offset:2048
	ds_read_b128 v[184:187], v214 offset:3072
	ds_read_b128 v[188:191], v214 offset:4096
	ds_read_b128 v[192:195], v214 offset:5120
	ds_read_b128 v[196:199], v214 offset:6144
	ds_read_b128 v[200:203], v214 offset:7168
	global_load_lds_dwordx4 v[204:205], off
	v_lshl_add_u64 v[204:205], s[4:5], 0, v[170:171]
	s_add_i32 m0, s9, 0xe000
	s_nop 0
	global_load_lds_dwordx4 v[204:205], off
	s_waitcnt vmcnt(8)
	s_waitcnt lgkmcnt(0)
	s_setprio 1
	s_waitcnt lgkmcnt(0)
	v_mfma_f32_16x16x32_bf16 v[124:127], v[128:131], v[172:175], v[124:127]
	v_mfma_f32_16x16x32_bf16 v[120:123], v[136:139], v[172:175], v[120:123]
	v_mfma_f32_16x16x32_bf16 v[116:119], v[128:131], v[180:183], v[116:119]
	v_mfma_f32_16x16x32_bf16 v[108:111], v[136:139], v[180:183], v[108:111]
	s_barrier
	v_mfma_f32_16x16x32_bf16 v[100:103], v[128:131], v[188:191], v[100:103]
	v_mfma_f32_16x16x32_bf16 v[92:95], v[136:139], v[188:191], v[92:95]
	v_mfma_f32_16x16x32_bf16 v[84:87], v[128:131], v[196:199], v[84:87]
	v_mfma_f32_16x16x32_bf16 v[76:79], v[136:139], v[196:199], v[76:79]
	v_mfma_f32_16x16x32_bf16 v[124:127], v[132:135], v[176:179], v[124:127]
	v_mfma_f32_16x16x32_bf16 v[120:123], v[140:143], v[176:179], v[120:123]
	v_mfma_f32_16x16x32_bf16 v[116:119], v[132:135], v[184:187], v[116:119]
	v_mfma_f32_16x16x32_bf16 v[108:111], v[140:143], v[184:187], v[108:111]
	v_mfma_f32_16x16x32_bf16 v[100:103], v[132:135], v[192:195], v[100:103]
	v_mfma_f32_16x16x32_bf16 v[92:95], v[140:143], v[192:195], v[92:95]
	v_mfma_f32_16x16x32_bf16 v[84:87], v[132:135], v[200:203], v[84:87]
	v_mfma_f32_16x16x32_bf16 v[76:79], v[140:143], v[200:203], v[76:79]
	s_setprio 0
	s_setprio 1
	v_mfma_f32_16x16x32_bf16 v[112:115], v[144:147], v[172:175], v[112:115]
	v_mfma_f32_16x16x32_bf16 v[104:107], v[152:155], v[172:175], v[104:107]
	v_mfma_f32_16x16x32_bf16 v[96:99], v[144:147], v[180:183], v[96:99]
	v_mfma_f32_16x16x32_bf16 v[88:91], v[152:155], v[180:183], v[88:91]
	v_mfma_f32_16x16x32_bf16 v[80:83], v[144:147], v[188:191], v[80:83]
	v_mfma_f32_16x16x32_bf16 v[72:75], v[152:155], v[188:191], v[72:75]
	v_mfma_f32_16x16x32_bf16 v[68:71], v[144:147], v[196:199], v[68:71]
	v_mfma_f32_16x16x32_bf16 v[64:67], v[152:155], v[196:199], v[64:67]
	v_mfma_f32_16x16x32_bf16 v[112:115], v[148:151], v[176:179], v[112:115]
	v_mfma_f32_16x16x32_bf16 v[104:107], v[156:159], v[176:179], v[104:107]
	v_mfma_f32_16x16x32_bf16 v[96:99], v[148:151], v[184:187], v[96:99]
	v_mfma_f32_16x16x32_bf16 v[88:91], v[156:159], v[184:187], v[88:91]
	v_mfma_f32_16x16x32_bf16 v[80:83], v[148:151], v[192:195], v[80:83]
	v_mfma_f32_16x16x32_bf16 v[72:75], v[156:159], v[192:195], v[72:75]
	v_mfma_f32_16x16x32_bf16 v[68:71], v[148:151], v[200:203], v[68:71]
	v_mfma_f32_16x16x32_bf16 v[64:67], v[156:159], v[200:203], v[64:67]
	s_setprio 0
	s_barrier
; #define PG8_STAGE(bufoff, gbase, voff) do { _Pragma("unroll") for (int _i = 0; _i < 2; ++_i) \
;         __builtin_amdgcn_global_load_lds((const unsigned*)((const char*)(gbase) + (voff)[_i]), (LAS unsigned*)(lds + (bufoff) + ldsw + _i * 8192), 16, 0, 0); } while (0)
; #define PG8_LDA(dst, b, h) do { _Pragma("unroll") for (int m = 0; m < 4; ++m) _Pragma("unroll") for (int k = 0; k < 2; ++k) dst[m][k] = *(const LAS bf16x8*)(lds + PG8_SA(b, h) + aoff + m * 2048 + k * 1024); } while (0)
; #define PG8_LDB(dst, b, h) do { _Pragma("unroll") for (int n = 0; n < 2; ++n) _Pragma("unroll") for (int k = 0; k < 2; ++k) dst[n][k] = *(const LAS bf16x8*)(lds + PG8_SB(b, h) + boff + n * 2048 + k * 1024); } while (0)
; #define PG8_MMA(ai, bj, At, Bt) do { __builtin_amdgcn_s_setprio(1); _Pragma("unroll") for (int m = 0; m < 4; ++m) _Pragma("unroll") for (int n = 0; n < 2; ++n) _Pragma("unroll") for (int k = 0; k < 2; ++k) \
;         acc[ai][bj][m][n] = __builtin_amdgcn_mfma_f32_16x16x32_bf16(Bt[n][k], At[m][k], acc[ai][bj][m][n], 0, 0, 0); __builtin_amdgcn_s_setprio(0); } while (0)
; #define PG8_WAIT_V(n) asm volatile("s_waitcnt vmcnt(" #n ")" ::: "memory")
; #define PG8_WAIT_L(n) asm volatile("s_waitcnt lgkmcnt(" #n ")" ::: "memory")
; #define PG8_BAR __builtin_amdgcn_s_barrier()
; template <class Epi, bool ALIGN_EPI, bool SP2>
; __device__ __forceinline__ void gemm_phase(LAS unsigned char* lds, const int K, const Sched& S, const Epi& E) {
;     ...
;             PG8_WAIT_V(8); PG8_WAIT_L(0); PG8_BAR; PG8_MMA(0, 0, At, B0); PG8_MMA(0, 1, At, B1); PG8_BAR; PG8_SCHED;
;             PG8_LDA(At, 0, 1); PG8_STAGE(PG8_SB(0, 0), b2, voffB); PG8_STAGE(PG8_SB(0, 1), b2 + hstep, voffB); PG8_STAGE(PG8_SA(0, 0), a2, voffA);
;             PG8_WAIT_V(8); PG8_WAIT_L(0); PG8_BAR; PG8_MMA(1, 0, At, B0); PG8_MMA(1, 1, At, B1); PG8_BAR; PG8_SCHED;
;             PG8_LDB(B0, 1, 0); PG8_LDB(B1, 1, 1); PG8_SCHED; PG8_LDA(At, 1, 0); PG8_STAGE(PG8_SA(0, 1), a2 + hstep, voffA);
;             PG8_WAIT_V(8); PG8_WAIT_L(0); PG8_BAR; PG8_MMA(0, 0, At, B0); PG8_MMA(0, 1, At, B1); PG8_BAR; PG8_SCHED;
;             PG8_LDA(At, 1, 1); PG8_STAGE(PG8_SB(1, 0), b3, voffB); PG8_STAGE(PG8_SB(1, 1), b3 + hstep, voffB); PG8_STAGE(PG8_SA(1, 0), a3, voffA);
;             PG8_WAIT_V(8); PG8_WAIT_L(0); PG8_BAR; PG8_MMA(1, 0, At, B0); PG8_MMA(1, 1, At, B1); PG8_BAR; PG8_SCHED;
	s_add_i32 s48, s34, s8
	v_lshl_add_u64 v[204:205], s[70:71], 0, v[162:163]
	s_mov_b32 m0, s48
	ds_read_b128 v[172:175], v214 offset:16384
	ds_read_b128 v[176:179], v214 offset:17408
	ds_read_b128 v[180:183], v214 offset:18432
	ds_read_b128 v[184:187], v214 offset:19456
	ds_read_b128 v[188:191], v214 offset:20480
	ds_read_b128 v[192:195], v214 offset:21504
	ds_read_b128 v[196:199], v214 offset:22528
	ds_read_b128 v[200:203], v214 offset:23552
	global_load_lds_dwordx4 v[204:205], off
	s_add_i32 m0, s48, 0x2000
	s_add_u32 s48, s70, 0x40000
	v_lshl_add_u64 v[206:207], s[70:71], 0, v[166:167]
	s_addc_u32 s49, s71, 0
	s_add_i32 s50, s35, s8
	global_load_lds_dwordx4 v[206:207], off
	v_lshl_add_u64 v[220:221], s[48:49], 0, v[162:163]
	s_mov_b32 m0, s50
	v_lshl_add_u64 v[222:223], s[80:81], 0, v[164:165]
	global_load_lds_dwordx4 v[220:221], off
	v_lshl_add_u64 v[220:221], s[48:49], 0, v[166:167]
	s_add_i32 m0, s50, 0x2000
	s_nop 0
	global_load_lds_dwordx4 v[220:221], off
	v_lshl_add_u64 v[220:221], s[80:81], 0, v[160:161]
	s_mov_b32 m0, s9
	s_nop 0
	global_load_lds_dwordx4 v[220:221], off
	s_mov_b32 m0, s41
	s_nop 0
	global_load_lds_dwordx4 v[222:223], off
	s_waitcnt vmcnt(8)
	s_waitcnt lgkmcnt(0)
	s_setprio 1
	s_waitcnt lgkmcnt(0)
	v_mfma_f32_16x16x32_bf16 v[60:63], v[128:131], v[172:175], v[60:63]
	v_mfma_f32_16x16x32_bf16 v[56:59], v[136:139], v[172:175], v[56:59]
	v_mfma_f32_16x16x32_bf16 v[52:55], v[128:131], v[180:183], v[52:55]
	v_mfma_f32_16x16x32_bf16 v[44:47], v[136:139], v[180:183], v[44:47]
	s_barrier
	v_mfma_f32_16x16x32_bf16 v[36:39], v[128:131], v[188:191], v[36:39]
	v_mfma_f32_16x16x32_bf16 v[28:31], v[136:139], v[188:191], v[28:31]
	v_mfma_f32_16x16x32_bf16 v[20:23], v[128:131], v[196:199], v[20:23]
	v_mfma_f32_16x16x32_bf16 v[12:15], v[136:139], v[196:199], v[12:15]
	v_mfma_f32_16x16x32_bf16 v[60:63], v[132:135], v[176:179], v[60:63]
	v_mfma_f32_16x16x32_bf16 v[56:59], v[140:143], v[176:179], v[56:59]
	v_mfma_f32_16x16x32_bf16 v[52:55], v[132:135], v[184:187], v[52:55]
	v_mfma_f32_16x16x32_bf16 v[44:47], v[140:143], v[184:187], v[44:47]
	v_mfma_f32_16x16x32_bf16 v[36:39], v[132:135], v[192:195], v[36:39]
	v_mfma_f32_16x16x32_bf16 v[28:31], v[140:143], v[192:195], v[28:31]
	v_mfma_f32_16x16x32_bf16 v[20:23], v[132:135], v[200:203], v[20:23]
	v_mfma_f32_16x16x32_bf16 v[12:15], v[140:143], v[200:203], v[12:15]
	s_setprio 0
	s_setprio 1
	v_mfma_f32_16x16x32_bf16 v[48:51], v[144:147], v[172:175], v[48:51]
	v_mfma_f32_16x16x32_bf16 v[40:43], v[152:155], v[172:175], v[40:43]
	v_mfma_f32_16x16x32_bf16 v[32:35], v[144:147], v[180:183], v[32:35]
	v_mfma_f32_16x16x32_bf16 v[24:27], v[152:155], v[180:183], v[24:27]
	v_mfma_f32_16x16x32_bf16 v[16:19], v[144:147], v[188:191], v[16:19]
	v_mfma_f32_16x16x32_bf16 v[8:11], v[152:155], v[188:191], v[8:11]
	v_mfma_f32_16x16x32_bf16 v[4:7], v[144:147], v[196:199], v[4:7]
	v_mfma_f32_16x16x32_bf16 v[0:3], v[152:155], v[196:199], v[0:3]
	v_mfma_f32_16x16x32_bf16 v[48:51], v[148:151], v[176:179], v[48:51]
	v_mfma_f32_16x16x32_bf16 v[40:43], v[156:159], v[176:179], v[40:43]
	v_mfma_f32_16x16x32_bf16 v[32:35], v[148:151], v[184:187], v[32:35]
	v_mfma_f32_16x16x32_bf16 v[24:27], v[156:159], v[184:187], v[24:27]
	v_mfma_f32_16x16x32_bf16 v[16:19], v[148:151], v[192:195], v[16:19]
	v_mfma_f32_16x16x32_bf16 v[8:11], v[156:159], v[192:195], v[8:11]
	v_mfma_f32_16x16x32_bf16 v[4:7], v[148:151], v[200:203], v[4:7]
	v_mfma_f32_16x16x32_bf16 v[0:3], v[156:159], v[200:203], v[0:3]
	s_setprio 0
	s_barrier
	s_add_i32 s50, 0, 0x18000
	s_add_i32 s51, 0, 0x1c000
	v_add_u32_e32 v140, s50, v211
	v_add_u32_e32 v156, s51, v211
	ds_read_b128 v[128:131], v140
	ds_read_b128 v[132:135], v140 offset:1024
	ds_read_b128 v[136:139], v140 offset:2048
	ds_read_b128 v[140:143], v140 offset:3072
	ds_read_b128 v[144:147], v156
	ds_read_b128 v[148:151], v156 offset:1024
	ds_read_b128 v[152:155], v156 offset:2048
	ds_read_b128 v[156:159], v156 offset:3072
	s_add_u32 s48, s80, 0x40000
	s_addc_u32 s49, s81, 0
	s_mov_b32 m0, s85
	v_lshl_add_u64 v[224:225], s[48:49], 0, v[160:161]
	ds_read_b128 v[172:175], v214 offset:32768
	ds_read_b128 v[176:179], v214 offset:33792
	ds_read_b128 v[180:183], v214 offset:34816
	ds_read_b128 v[184:187], v214 offset:35840
	ds_read_b128 v[188:191], v214 offset:36864
	ds_read_b128 v[192:195], v214 offset:37888
	ds_read_b128 v[196:199], v214 offset:38912
	ds_read_b128 v[200:203], v214 offset:39936
	global_load_lds_dwordx4 v[224:225], off
	v_lshl_add_u64 v[224:225], s[48:49], 0, v[164:165]
	s_mov_b32 m0, s26
	s_nop 0
	global_load_lds_dwordx4 v[224:225], off
	s_waitcnt vmcnt(8)
	s_waitcnt lgkmcnt(0)
	s_setprio 1
	s_waitcnt lgkmcnt(0)
	v_mfma_f32_16x16x32_bf16 v[124:127], v[128:131], v[172:175], v[124:127]
	v_mfma_f32_16x16x32_bf16 v[120:123], v[136:139], v[172:175], v[120:123]
	v_mfma_f32_16x16x32_bf16 v[116:119], v[128:131], v[180:183], v[116:119]
	v_mfma_f32_16x16x32_bf16 v[108:111], v[136:139], v[180:183], v[108:111]
	s_barrier
; #define PG8_STAGE(bufoff, gbase, voff) do { _Pragma("unroll") for (int _i = 0; _i < 2; ++_i) \
;         __builtin_amdgcn_global_load_lds((const unsigned*)((const char*)(gbase) + (voff)[_i]), (LAS unsigned*)(lds + (bufoff) + ldsw + _i * 8192), 16, 0, 0); } while (0)
; #define PG8_LDA(dst, b, h) do { _Pragma("unroll") for (int m = 0; m < 4; ++m) _Pragma("unroll") for (int k = 0; k < 2; ++k) dst[m][k] = *(const LAS bf16x8*)(lds + PG8_SA(b, h) + aoff + m * 2048 + k * 1024); } while (0)
; template <class Epi, bool ALIGN_EPI, bool SP2>
; __device__ __forceinline__ void gemm_phase(LAS unsigned char* lds, const int K, const Sched& S, const Epi& E) {
;     ...
;             PG8_WAIT_V(8); PG8_WAIT_L(0); PG8_BAR; PG8_MMA(0, 0, At, B0); PG8_MMA(0, 1, At, B1); PG8_BAR; PG8_SCHED;
;             PG8_LDA(At, 1, 1); PG8_STAGE(PG8_SB(1, 0), b3, voffB); PG8_STAGE(PG8_SB(1, 1), b3 + hstep, voffB); PG8_STAGE(PG8_SA(1, 0), a3, voffA);
;             PG8_WAIT_V(8); PG8_WAIT_L(0); PG8_BAR; PG8_MMA(1, 0, At, B0); PG8_MMA(1, 1, At, B1); PG8_BAR; PG8_SCHED;
;             } else {
;             PG8_LDB(B0, 0, 0); PG8_SCHED; PG8_LDA(At, 0, 0); PG8_STAGE(PG8_SA(1, 1), a1 + hstep, voffA);
;             PG8_WAIT_L(8); PG8_BAR; PG8_WAIT_L(0); PG8_MMA(0, 0, At, B0); PG8_BAR; PG8_SCHED;
;             PG8_LDB(B1, 0, 1); PG8_STAGE(PG8_SB(0, 0), b2, voffB);
;             PG8_BAR; PG8_WAIT_L(0); PG8_MMA(0, 1, At, B1); PG8_BAR;
;             PG8_LDA(At, 0, 1); PG8_STAGE(PG8_SA(0, 0), a2, voffA);
;             PG8_BAR; PG8_WAIT_L(0); PG8_MMA(1, 0, At, B0); PG8_BAR; PG8_SCHED;
;             PG8_STAGE(PG8_SB(0, 1), b2 + hstep, voffB);
;             PG8_WAIT_V(6); PG8_BAR; PG8_MMA(1, 1, At, B1); PG8_BAR;
;             PG8_LDB(B0, 1, 0); PG8_SCHED; PG8_LDA(At, 1, 0); PG8_STAGE(PG8_SA(0, 1), a2 + hstep, voffA);
;             PG8_WAIT_L(8); PG8_BAR; PG8_WAIT_L(0); PG8_MMA(0, 0, At, B0); PG8_BAR; PG8_SCHED;
;             PG8_LDB(B1, 1, 1); PG8_STAGE(PG8_SB(1, 0), b3, voffB);
;             PG8_BAR; PG8_WAIT_L(0); PG8_MMA(0, 1, At, B1); PG8_BAR;
;             PG8_LDA(At, 1, 1); PG8_STAGE(PG8_SA(1, 0), a3, voffA);
;             PG8_BAR; PG8_WAIT_L(0); PG8_MMA(1, 0, At, B0); PG8_BAR; PG8_SCHED;
;             PG8_STAGE(PG8_SB(1, 1), b3 + hstep, voffB);
;             PG8_WAIT_V(6); PG8_BAR; PG8_MMA(1, 1, At, B1); PG8_BAR;
;             }
;         }
;         if constexpr (ALIGN_EPI) { if (wr == 0) PG8_BAR; }
	v_mfma_f32_16x16x32_bf16 v[100:103], v[128:131], v[188:191], v[100:103]
	v_mfma_f32_16x16x32_bf16 v[92:95], v[136:139], v[188:191], v[92:95]
	v_mfma_f32_16x16x32_bf16 v[84:87], v[128:131], v[196:199], v[84:87]
	v_mfma_f32_16x16x32_bf16 v[76:79], v[136:139], v[196:199], v[76:79]
	v_mfma_f32_16x16x32_bf16 v[124:127], v[132:135], v[176:179], v[124:127]
	v_mfma_f32_16x16x32_bf16 v[120:123], v[140:143], v[176:179], v[120:123]
	v_mfma_f32_16x16x32_bf16 v[116:119], v[132:135], v[184:187], v[116:119]
	v_mfma_f32_16x16x32_bf16 v[108:111], v[140:143], v[184:187], v[108:111]
	v_mfma_f32_16x16x32_bf16 v[100:103], v[132:135], v[192:195], v[100:103]
	v_mfma_f32_16x16x32_bf16 v[92:95], v[140:143], v[192:195], v[92:95]
	v_mfma_f32_16x16x32_bf16 v[84:87], v[132:135], v[200:203], v[84:87]
	v_mfma_f32_16x16x32_bf16 v[76:79], v[140:143], v[200:203], v[76:79]
	s_setprio 0
	s_setprio 1
	v_mfma_f32_16x16x32_bf16 v[112:115], v[144:147], v[172:175], v[112:115]
	v_mfma_f32_16x16x32_bf16 v[104:107], v[152:155], v[172:175], v[104:107]
	v_mfma_f32_16x16x32_bf16 v[96:99], v[144:147], v[180:183], v[96:99]
	v_mfma_f32_16x16x32_bf16 v[88:91], v[152:155], v[180:183], v[88:91]
	v_mfma_f32_16x16x32_bf16 v[80:83], v[144:147], v[188:191], v[80:83]
	v_mfma_f32_16x16x32_bf16 v[72:75], v[152:155], v[188:191], v[72:75]
	v_mfma_f32_16x16x32_bf16 v[68:71], v[144:147], v[196:199], v[68:71]
	v_mfma_f32_16x16x32_bf16 v[64:67], v[152:155], v[196:199], v[64:67]
	v_mfma_f32_16x16x32_bf16 v[112:115], v[148:151], v[176:179], v[112:115]
	v_mfma_f32_16x16x32_bf16 v[104:107], v[156:159], v[176:179], v[104:107]
	v_mfma_f32_16x16x32_bf16 v[96:99], v[148:151], v[184:187], v[96:99]
	v_mfma_f32_16x16x32_bf16 v[88:91], v[156:159], v[184:187], v[88:91]
	v_mfma_f32_16x16x32_bf16 v[80:83], v[148:151], v[192:195], v[80:83]
	v_mfma_f32_16x16x32_bf16 v[72:75], v[156:159], v[192:195], v[72:75]
	v_mfma_f32_16x16x32_bf16 v[68:71], v[148:151], v[200:203], v[68:71]
	v_mfma_f32_16x16x32_bf16 v[64:67], v[156:159], v[200:203], v[64:67]
	s_setprio 0
	s_barrier
	s_add_i32 s48, s50, s8
	v_lshl_add_u64 v[204:205], v[204:205], 0, s[16:17]
	s_mov_b32 m0, s48
	ds_read_b128 v[172:175], v214 offset:49152
	ds_read_b128 v[176:179], v214 offset:50176
	ds_read_b128 v[180:183], v214 offset:51200
	ds_read_b128 v[184:187], v214 offset:52224
	ds_read_b128 v[188:191], v214 offset:53248
	ds_read_b128 v[192:195], v214 offset:54272
	ds_read_b128 v[196:199], v214 offset:55296
	ds_read_b128 v[200:203], v214 offset:56320
	global_load_lds_dwordx4 v[204:205], off
	s_add_i32 m0, s48, 0x2000
	s_add_u32 s48, s70, 0x40080
	v_lshl_add_u64 v[204:205], v[206:207], 0, s[16:17]
	s_addc_u32 s49, s71, 0
	s_add_i32 s50, s51, s8
	global_load_lds_dwordx4 v[204:205], off
	v_lshl_add_u64 v[204:205], s[48:49], 0, v[162:163]
	s_mov_b32 m0, s50
	s_nop 0
	global_load_lds_dwordx4 v[204:205], off
	v_lshl_add_u64 v[204:205], s[48:49], 0, v[166:167]
	s_add_i32 m0, s50, 0x2000
	s_nop 0
	global_load_lds_dwordx4 v[204:205], off
	v_lshl_add_u64 v[204:205], v[220:221], 0, s[16:17]
	s_mov_b32 m0, s29
	s_nop 0
	global_load_lds_dwordx4 v[204:205], off
	v_lshl_add_u64 v[204:205], v[222:223], 0, s[16:17]
	s_mov_b32 m0, s30
	s_nop 0
	global_load_lds_dwordx4 v[204:205], off
	s_waitcnt vmcnt(8)
	s_waitcnt lgkmcnt(0)
	s_setprio 1
	s_waitcnt lgkmcnt(0)
	v_mfma_f32_16x16x32_bf16 v[60:63], v[128:131], v[172:175], v[60:63]
	v_mfma_f32_16x16x32_bf16 v[56:59], v[136:139], v[172:175], v[56:59]
	v_mfma_f32_16x16x32_bf16 v[52:55], v[128:131], v[180:183], v[52:55]
	v_mfma_f32_16x16x32_bf16 v[44:47], v[136:139], v[180:183], v[44:47]
	s_barrier
	v_mfma_f32_16x16x32_bf16 v[36:39], v[128:131], v[188:191], v[36:39]
	v_mfma_f32_16x16x32_bf16 v[28:31], v[136:139], v[188:191], v[28:31]
	v_mfma_f32_16x16x32_bf16 v[20:23], v[128:131], v[196:199], v[20:23]
	v_mfma_f32_16x16x32_bf16 v[12:15], v[136:139], v[196:199], v[12:15]
	v_mfma_f32_16x16x32_bf16 v[60:63], v[132:135], v[176:179], v[60:63]
	v_mfma_f32_16x16x32_bf16 v[56:59], v[140:143], v[176:179], v[56:59]
	v_mfma_f32_16x16x32_bf16 v[52:55], v[132:135], v[184:187], v[52:55]
	v_mfma_f32_16x16x32_bf16 v[44:47], v[140:143], v[184:187], v[44:47]
	v_mfma_f32_16x16x32_bf16 v[36:39], v[132:135], v[192:195], v[36:39]
	v_mfma_f32_16x16x32_bf16 v[28:31], v[140:143], v[192:195], v[28:31]
	v_mfma_f32_16x16x32_bf16 v[20:23], v[132:135], v[200:203], v[20:23]
	v_mfma_f32_16x16x32_bf16 v[12:15], v[140:143], v[200:203], v[12:15]
	s_setprio 0
	s_setprio 1
	v_mfma_f32_16x16x32_bf16 v[48:51], v[144:147], v[172:175], v[48:51]
	v_mfma_f32_16x16x32_bf16 v[40:43], v[152:155], v[172:175], v[40:43]
	v_mfma_f32_16x16x32_bf16 v[32:35], v[144:147], v[180:183], v[32:35]
	v_mfma_f32_16x16x32_bf16 v[24:27], v[152:155], v[180:183], v[24:27]
	v_mfma_f32_16x16x32_bf16 v[16:19], v[144:147], v[188:191], v[16:19]
	v_mfma_f32_16x16x32_bf16 v[8:11], v[152:155], v[188:191], v[8:11]
	v_mfma_f32_16x16x32_bf16 v[4:7], v[144:147], v[196:199], v[4:7]
	v_mfma_f32_16x16x32_bf16 v[0:3], v[152:155], v[196:199], v[0:3]
	v_mfma_f32_16x16x32_bf16 v[48:51], v[148:151], v[176:179], v[48:51]
	v_mfma_f32_16x16x32_bf16 v[40:43], v[156:159], v[176:179], v[40:43]
	v_mfma_f32_16x16x32_bf16 v[32:35], v[148:151], v[184:187], v[32:35]
	v_mfma_f32_16x16x32_bf16 v[24:27], v[156:159], v[184:187], v[24:27]
	v_mfma_f32_16x16x32_bf16 v[16:19], v[148:151], v[192:195], v[16:19]
	v_mfma_f32_16x16x32_bf16 v[8:11], v[156:159], v[192:195], v[8:11]
	v_mfma_f32_16x16x32_bf16 v[4:7], v[148:151], v[200:203], v[4:7]
	v_mfma_f32_16x16x32_bf16 v[0:3], v[156:159], v[200:203], v[0:3]
	s_setprio 0
	s_barrier
	s_add_i32 s45, s45, 2
	s_add_u32 s4, s4, 0x100
	s_addc_u32 s5, s5, 0
	s_add_u32 s12, s12, 0x100
	s_addc_u32 s43, s43, 0
	s_cmp_gt_u32 s45, 13
	s_cbranch_scc0 .LBB0_172
	s_and_b64 vcc, exec, s[18:19]
	s_cbranch_vccz .LBB0_175
	s_barrier

;     __device__ __forceinline__ const char* aptr(const Unit& u) const { return (u.kind == 1 ? A1 : A0) + (size_t)u.pm * tstep; }
;     __device__ __forceinline__ const char* bptr(const Unit& u) const { return (u.kind == 1 ? B1 : B0) + (size_t)u.pn * tstep; }
; #define PG8_STAGE(bufoff, gbase, voff) do { _Pragma("unroll") for (int _i = 0; _i < 2; ++_i) \
;         __builtin_amdgcn_global_load_lds((const unsigned*)((const char*)(gbase) + (voff)[_i]), (LAS unsigned*)(lds + (bufoff) + ldsw + _i * 8192), 16, 0, 0); } while (0)
; #define PG8_LDA(dst, b, h) do { _Pragma("unroll") for (int m = 0; m < 4; ++m) _Pragma("unroll") for (int k = 0; k < 2; ++k) dst[m][k] = *(const LAS bf16x8*)(lds + PG8_SA(b, h) + aoff + m * 2048 + k * 1024); } while (0)
; #define PG8_LDB(dst, b, h) do { _Pragma("unroll") for (int n = 0; n < 2; ++n) _Pragma("unroll") for (int k = 0; k < 2; ++k) dst[n][k] = *(const LAS bf16x8*)(lds + PG8_SB(b, h) + boff + n * 2048 + k * 1024); } while (0)
; #define PG8_WAIT_V(n) asm volatile("s_waitcnt vmcnt(" #n ")" ::: "memory")
; template <class Epi, bool ALIGN_EPI, bool SP2>
; __device__ __forceinline__ void gemm_phase(LAS unsigned char* lds, const int K, const Sched& S, const Epi& E) {
;     ...
;     for (;;) {
;         const bool has_next = S.next(ui + 1, nxt);
;         const char* nA = has_next ? S.aptr(nxt) : cA; const char* nB = has_next ? S.bptr(nxt) : cB;
;         for (int t = 0; t < nt; t += 2) {
;             const bool last = (t == nt - 2);
;             const char* a1 = cA + (size_t)(t + 1) * kstep;
;             const char* a2 = last ? nA : cA + (size_t)(t + 2) * kstep; const char* b2 = last ? nB : cB + (size_t)(t + 2) * kstep;
;             const char* a3 = a2 + kstep; const char* b3 = b2 + kstep;
;             if constexpr (SP2) {
;             PG8_LDB(B0, 0, 0); PG8_LDB(B1, 0, 1); PG8_SCHED; PG8_LDA(At, 0, 0); PG8_STAGE(PG8_SA(1, 1), a1 + hstep, voffA);
;             PG8_WAIT_V(8); PG8_WAIT_L(0); PG8_BAR; PG8_MMA(0, 0, At, B0); PG8_MMA(0, 1, At, B1); PG8_BAR; PG8_SCHED;
;     ...
; #pragma unroll
;         for (int a = 0; a < 2; ++a)
; #pragma unroll
;             for (int b = 0; b < 2; ++b)
; #pragma unroll
;                 for (int m = 0; m < 4; ++m)
; #pragma unroll
;                     for (int n = 0; n < 2; ++n) acc[a][b][m][n] = (f32x4){0.f, 0.f, 0.f, 0.f};
;         cur = nxt; cA = nA; cB = nB; ++ui;
.LBB0_356:
	s_add_u32 s4, s4, 0x40080
	s_addc_u32 s5, s5, 0
	s_add_u32 s35, s70, 0x100
	v_mov_b64_e32 v[0:1], 0
	v_mov_b64_e32 v[2:3], 0
	v_mov_b64_e32 v[4:5], 0
	v_mov_b64_e32 v[6:7], 0
	v_mov_b64_e32 v[8:9], 0
	v_mov_b64_e32 v[10:11], 0
	v_mov_b64_e32 v[12:13], 0
	v_mov_b64_e32 v[14:15], 0
	v_mov_b64_e32 v[16:17], 0
	v_mov_b64_e32 v[18:19], 0
	v_mov_b64_e32 v[20:21], 0
	v_mov_b64_e32 v[22:23], 0
	v_mov_b64_e32 v[24:25], 0
	v_mov_b64_e32 v[26:27], 0
	v_mov_b64_e32 v[28:29], 0
	v_mov_b64_e32 v[30:31], 0
	v_mov_b64_e32 v[32:33], 0
	v_mov_b64_e32 v[34:35], 0
	v_mov_b64_e32 v[36:37], 0
	v_mov_b64_e32 v[38:39], 0
	v_mov_b64_e32 v[40:41], 0
	v_mov_b64_e32 v[42:43], 0
	v_mov_b64_e32 v[44:45], 0
	v_mov_b64_e32 v[46:47], 0
	v_mov_b64_e32 v[48:49], 0
	v_mov_b64_e32 v[50:51], 0
	v_mov_b64_e32 v[52:53], 0
	v_mov_b64_e32 v[54:55], 0
	v_mov_b64_e32 v[56:57], 0
	v_mov_b64_e32 v[58:59], 0
	v_mov_b64_e32 v[60:61], 0
	v_mov_b64_e32 v[62:63], 0
	v_mov_b64_e32 v[64:65], 0
	v_mov_b64_e32 v[66:67], 0
	v_mov_b64_e32 v[68:69], 0
	v_mov_b64_e32 v[70:71], 0
	v_mov_b64_e32 v[72:73], 0
	v_mov_b64_e32 v[74:75], 0
	v_mov_b64_e32 v[76:77], 0
	v_mov_b64_e32 v[78:79], 0
	v_mov_b64_e32 v[80:81], 0
	v_mov_b64_e32 v[82:83], 0
	v_mov_b64_e32 v[84:85], 0
	v_mov_b64_e32 v[86:87], 0
	v_mov_b64_e32 v[88:89], 0
	v_mov_b64_e32 v[90:91], 0
	v_mov_b64_e32 v[92:93], 0
	v_mov_b64_e32 v[94:95], 0
	v_mov_b64_e32 v[96:97], 0
	v_mov_b64_e32 v[98:99], 0
	v_mov_b64_e32 v[100:101], 0
	v_mov_b64_e32 v[102:103], 0
	v_mov_b64_e32 v[104:105], 0
	v_mov_b64_e32 v[106:107], 0
	v_mov_b64_e32 v[108:109], 0
	v_mov_b64_e32 v[110:111], 0
	v_mov_b64_e32 v[112:113], 0
	v_mov_b64_e32 v[114:115], 0
	v_mov_b64_e32 v[116:117], 0
	v_mov_b64_e32 v[118:119], 0
	v_mov_b64_e32 v[120:121], 0
	v_mov_b64_e32 v[122:123], 0
	v_mov_b64_e32 v[124:125], 0
	v_mov_b64_e32 v[126:127], 0
	s_addc_u32 s43, s71, 0
	s_mov_b32 s45, -2
.LBB0_357:
	ds_read_b128 v[128:131], v212
	ds_read_b128 v[132:135], v212 offset:1024
	ds_read_b128 v[136:139], v212 offset:2048
	ds_read_b128 v[140:143], v212 offset:3072
	ds_read_b128 v[144:147], v213
	ds_read_b128 v[148:151], v213 offset:1024
	ds_read_b128 v[152:155], v213 offset:2048
	ds_read_b128 v[156:159], v213 offset:3072
	s_add_u32 s48, s4, 0xfffc0080
	s_addc_u32 s49, s5, -1
	s_cmp_eq_u32 s45, 12
	s_cselect_b32 s81, s47, s49
	s_cselect_b32 s80, s46, s48
	s_cselect_b32 s71, s83, s43
	s_cselect_b32 s70, s82, s35
	v_lshl_add_u64 v[204:205], s[4:5], 0, v[168:169]
	s_add_i32 m0, s41, 0xc000
	ds_read_b128 v[172:175], v214
	ds_read_b128 v[176:179], v214 offset:1024
	ds_read_b128 v[180:183], v214 offset:2048
	ds_read_b128 v[184:187], v214 offset:3072
	ds_read_b128 v[188:191], v214 offset:4096
	ds_read_b128 v[192:195], v214 offset:5120
	ds_read_b128 v[196:199], v214 offset:6144
	ds_read_b128 v[200:203], v214 offset:7168
	global_load_lds_dwordx4 v[204:205], off
	v_lshl_add_u64 v[204:205], s[4:5], 0, v[170:171]
	s_add_i32 m0, s41, 0xe000
	s_nop 0
	global_load_lds_dwordx4 v[204:205], off
	s_waitcnt vmcnt(8)
	s_waitcnt lgkmcnt(0)
	s_setprio 1
	s_waitcnt lgkmcnt(0)
	v_mfma_f32_16x16x32_bf16 v[124:127], v[128:131], v[172:175], v[124:127]
	v_mfma_f32_16x16x32_bf16 v[120:123], v[136:139], v[172:175], v[120:123]
	v_mfma_f32_16x16x32_bf16 v[116:119], v[128:131], v[180:183], v[116:119]
	v_mfma_f32_16x16x32_bf16 v[108:111], v[136:139], v[180:183], v[108:111]
	s_barrier
	v_mfma_f32_16x16x32_bf16 v[100:103], v[128:131], v[188:191], v[100:103]
	v_mfma_f32_16x16x32_bf16 v[92:95], v[136:139], v[188:191], v[92:95]
	v_mfma_f32_16x16x32_bf16 v[84:87], v[128:131], v[196:199], v[84:87]
	v_mfma_f32_16x16x32_bf16 v[76:79], v[136:139], v[196:199], v[76:79]
	v_mfma_f32_16x16x32_bf16 v[124:127], v[132:135], v[176:179], v[124:127]
	v_mfma_f32_16x16x32_bf16 v[120:123], v[140:143], v[176:179], v[120:123]
	v_mfma_f32_16x16x32_bf16 v[116:119], v[132:135], v[184:187], v[116:119]
	v_mfma_f32_16x16x32_bf16 v[108:111], v[140:143], v[184:187], v[108:111]
	v_mfma_f32_16x16x32_bf16 v[100:103], v[132:135], v[192:195], v[100:103]
	v_mfma_f32_16x16x32_bf16 v[92:95], v[140:143], v[192:195], v[92:95]
	v_mfma_f32_16x16x32_bf16 v[84:87], v[132:135], v[200:203], v[84:87]
	v_mfma_f32_16x16x32_bf16 v[76:79], v[140:143], v[200:203], v[76:79]
	s_setprio 0
	s_setprio 1
	v_mfma_f32_16x16x32_bf16 v[112:115], v[144:147], v[172:175], v[112:115]
	v_mfma_f32_16x16x32_bf16 v[104:107], v[152:155], v[172:175], v[104:107]
	v_mfma_f32_16x16x32_bf16 v[96:99], v[144:147], v[180:183], v[96:99]
	v_mfma_f32_16x16x32_bf16 v[88:91], v[152:155], v[180:183], v[88:91]
	v_mfma_f32_16x16x32_bf16 v[80:83], v[144:147], v[188:191], v[80:83]
	v_mfma_f32_16x16x32_bf16 v[72:75], v[152:155], v[188:191], v[72:75]
	v_mfma_f32_16x16x32_bf16 v[68:71], v[144:147], v[196:199], v[68:71]
	v_mfma_f32_16x16x32_bf16 v[64:67], v[152:155], v[196:199], v[64:67]
	v_mfma_f32_16x16x32_bf16 v[112:115], v[148:151], v[176:179], v[112:115]
	v_mfma_f32_16x16x32_bf16 v[104:107], v[156:159], v[176:179], v[104:107]
	v_mfma_f32_16x16x32_bf16 v[96:99], v[148:151], v[184:187], v[96:99]
	v_mfma_f32_16x16x32_bf16 v[88:91], v[156:159], v[184:187], v[88:91]
	v_mfma_f32_16x16x32_bf16 v[80:83], v[148:151], v[192:195], v[80:83]
	v_mfma_f32_16x16x32_bf16 v[72:75], v[156:159], v[192:195], v[72:75]
	v_mfma_f32_16x16x32_bf16 v[68:71], v[148:151], v[200:203], v[68:71]
	v_mfma_f32_16x16x32_bf16 v[64:67], v[156:159], v[200:203], v[64:67]
	s_setprio 0
	s_barrier
; #define PG8_STAGE(bufoff, gbase, voff) do { _Pragma("unroll") for (int _i = 0; _i < 2; ++_i) \
;         __builtin_amdgcn_global_load_lds((const unsigned*)((const char*)(gbase) + (voff)[_i]), (LAS unsigned*)(lds + (bufoff) + ldsw + _i * 8192), 16, 0, 0); } while (0)
; #define PG8_LDA(dst, b, h) do { _Pragma("unroll") for (int m = 0; m < 4; ++m) _Pragma("unroll") for (int k = 0; k < 2; ++k) dst[m][k] = *(const LAS bf16x8*)(lds + PG8_SA(b, h) + aoff + m * 2048 + k * 1024); } while (0)
; #define PG8_LDB(dst, b, h) do { _Pragma("unroll") for (int n = 0; n < 2; ++n) _Pragma("unroll") for (int k = 0; k < 2; ++k) dst[n][k] = *(const LAS bf16x8*)(lds + PG8_SB(b, h) + boff + n * 2048 + k * 1024); } while (0)
; #define PG8_MMA(ai, bj, At, Bt) do { __builtin_amdgcn_s_setprio(1); _Pragma("unroll") for (int m = 0; m < 4; ++m) _Pragma("unroll") for (int n = 0; n < 2; ++n) _Pragma("unroll") for (int k = 0; k < 2; ++k) \
;         acc[ai][bj][m][n] = __builtin_amdgcn_mfma_f32_16x16x32_bf16(Bt[n][k], At[m][k], acc[ai][bj][m][n], 0, 0, 0); __builtin_amdgcn_s_setprio(0); } while (0)
; #define PG8_WAIT_V(n) asm volatile("s_waitcnt vmcnt(" #n ")" ::: "memory")
; #define PG8_WAIT_L(n) asm volatile("s_waitcnt lgkmcnt(" #n ")" ::: "memory")
; #define PG8_BAR __builtin_amdgcn_s_barrier()
; template <class Epi, bool ALIGN_EPI, bool SP2>
; __device__ __forceinline__ void gemm_phase(LAS unsigned char* lds, const int K, const Sched& S, const Epi& E) {
;     ...
;             PG8_WAIT_V(8); PG8_WAIT_L(0); PG8_BAR; PG8_MMA(0, 0, At, B0); PG8_MMA(0, 1, At, B1); PG8_BAR; PG8_SCHED;
;             PG8_LDA(At, 0, 1); PG8_STAGE(PG8_SB(0, 0), b2, voffB); PG8_STAGE(PG8_SB(0, 1), b2 + hstep, voffB); PG8_STAGE(PG8_SA(0, 0), a2, voffA);
;             PG8_WAIT_V(8); PG8_WAIT_L(0); PG8_BAR; PG8_MMA(1, 0, At, B0); PG8_MMA(1, 1, At, B1); PG8_BAR; PG8_SCHED;
;             PG8_LDB(B0, 1, 0); PG8_LDB(B1, 1, 1); PG8_SCHED; PG8_LDA(At, 1, 0); PG8_STAGE(PG8_SA(0, 1), a2 + hstep, voffA);
;             PG8_WAIT_V(8); PG8_WAIT_L(0); PG8_BAR; PG8_MMA(0, 0, At, B0); PG8_MMA(0, 1, At, B1); PG8_BAR; PG8_SCHED;
;             PG8_LDA(At, 1, 1); PG8_STAGE(PG8_SB(1, 0), b3, voffB); PG8_STAGE(PG8_SB(1, 1), b3 + hstep, voffB); PG8_STAGE(PG8_SA(1, 0), a3, voffA);
;             PG8_WAIT_V(8); PG8_WAIT_L(0); PG8_BAR; PG8_MMA(1, 0, At, B0); PG8_MMA(1, 1, At, B1); PG8_BAR; PG8_SCHED;
	s_add_i32 s48, s28, s97
	v_lshl_add_u64 v[204:205], s[70:71], 0, v[162:163]
	s_mov_b32 m0, s48
	ds_read_b128 v[172:175], v214 offset:16384
	ds_read_b128 v[176:179], v214 offset:17408
	ds_read_b128 v[180:183], v214 offset:18432
	ds_read_b128 v[184:187], v214 offset:19456
	ds_read_b128 v[188:191], v214 offset:20480
	ds_read_b128 v[192:195], v214 offset:21504
	ds_read_b128 v[196:199], v214 offset:22528
	ds_read_b128 v[200:203], v214 offset:23552
	global_load_lds_dwordx4 v[204:205], off
	s_add_i32 m0, s48, 0x2000
	s_add_u32 s48, s70, 0x40000
	v_lshl_add_u64 v[206:207], s[70:71], 0, v[166:167]
	s_addc_u32 s49, s71, 0
	s_add_i32 s50, s29, s97
	global_load_lds_dwordx4 v[206:207], off
	v_lshl_add_u64 v[220:221], s[48:49], 0, v[162:163]
	s_mov_b32 m0, s50
	v_lshl_add_u64 v[222:223], s[80:81], 0, v[164:165]
	global_load_lds_dwordx4 v[220:221], off
	v_lshl_add_u64 v[220:221], s[48:49], 0, v[166:167]
	s_add_i32 m0, s50, 0x2000
	s_nop 0
	global_load_lds_dwordx4 v[220:221], off
	v_lshl_add_u64 v[220:221], s[80:81], 0, v[160:161]
	s_mov_b32 m0, s41
	s_nop 0
	global_load_lds_dwordx4 v[220:221], off
	s_mov_b32 m0, s85
	s_nop 0
	global_load_lds_dwordx4 v[222:223], off
	s_waitcnt vmcnt(8)
	s_waitcnt lgkmcnt(0)
	s_setprio 1
	s_waitcnt lgkmcnt(0)
	v_mfma_f32_16x16x32_bf16 v[60:63], v[128:131], v[172:175], v[60:63]
	v_mfma_f32_16x16x32_bf16 v[56:59], v[136:139], v[172:175], v[56:59]
	v_mfma_f32_16x16x32_bf16 v[52:55], v[128:131], v[180:183], v[52:55]
	v_mfma_f32_16x16x32_bf16 v[44:47], v[136:139], v[180:183], v[44:47]
	s_barrier
	v_mfma_f32_16x16x32_bf16 v[36:39], v[128:131], v[188:191], v[36:39]
	v_mfma_f32_16x16x32_bf16 v[28:31], v[136:139], v[188:191], v[28:31]
	v_mfma_f32_16x16x32_bf16 v[20:23], v[128:131], v[196:199], v[20:23]
	v_mfma_f32_16x16x32_bf16 v[12:15], v[136:139], v[196:199], v[12:15]
	v_mfma_f32_16x16x32_bf16 v[60:63], v[132:135], v[176:179], v[60:63]
	v_mfma_f32_16x16x32_bf16 v[56:59], v[140:143], v[176:179], v[56:59]
	v_mfma_f32_16x16x32_bf16 v[52:55], v[132:135], v[184:187], v[52:55]
	v_mfma_f32_16x16x32_bf16 v[44:47], v[140:143], v[184:187], v[44:47]
	v_mfma_f32_16x16x32_bf16 v[36:39], v[132:135], v[192:195], v[36:39]
	v_mfma_f32_16x16x32_bf16 v[28:31], v[140:143], v[192:195], v[28:31]
	v_mfma_f32_16x16x32_bf16 v[20:23], v[132:135], v[200:203], v[20:23]
	v_mfma_f32_16x16x32_bf16 v[12:15], v[140:143], v[200:203], v[12:15]
	s_setprio 0
	s_setprio 1
	v_mfma_f32_16x16x32_bf16 v[48:51], v[144:147], v[172:175], v[48:51]
	v_mfma_f32_16x16x32_bf16 v[40:43], v[152:155], v[172:175], v[40:43]
	v_mfma_f32_16x16x32_bf16 v[32:35], v[144:147], v[180:183], v[32:35]
	v_mfma_f32_16x16x32_bf16 v[24:27], v[152:155], v[180:183], v[24:27]
	v_mfma_f32_16x16x32_bf16 v[16:19], v[144:147], v[188:191], v[16:19]
	v_mfma_f32_16x16x32_bf16 v[8:11], v[152:155], v[188:191], v[8:11]
	v_mfma_f32_16x16x32_bf16 v[4:7], v[144:147], v[196:199], v[4:7]
	v_mfma_f32_16x16x32_bf16 v[0:3], v[152:155], v[196:199], v[0:3]
	v_mfma_f32_16x16x32_bf16 v[48:51], v[148:151], v[176:179], v[48:51]
	v_mfma_f32_16x16x32_bf16 v[40:43], v[156:159], v[176:179], v[40:43]
	v_mfma_f32_16x16x32_bf16 v[32:35], v[148:151], v[184:187], v[32:35]
	v_mfma_f32_16x16x32_bf16 v[24:27], v[156:159], v[184:187], v[24:27]
	v_mfma_f32_16x16x32_bf16 v[16:19], v[148:151], v[192:195], v[16:19]
	v_mfma_f32_16x16x32_bf16 v[8:11], v[156:159], v[192:195], v[8:11]
	v_mfma_f32_16x16x32_bf16 v[4:7], v[148:151], v[200:203], v[4:7]
	v_mfma_f32_16x16x32_bf16 v[0:3], v[156:159], v[200:203], v[0:3]
	s_setprio 0
	s_barrier
	s_add_i32 s50, 0, 0x18000
	s_add_i32 s51, 0, 0x1c000
	v_add_u32_e32 v140, s50, v211
	v_add_u32_e32 v156, s51, v211
	ds_read_b128 v[128:131], v140
	ds_read_b128 v[132:135], v140 offset:1024
	ds_read_b128 v[136:139], v140 offset:2048
	ds_read_b128 v[140:143], v140 offset:3072
	ds_read_b128 v[144:147], v156
	ds_read_b128 v[148:151], v156 offset:1024
	ds_read_b128 v[152:155], v156 offset:2048
	ds_read_b128 v[156:159], v156 offset:3072
	s_add_u32 s48, s80, 0x40000
	s_addc_u32 s49, s81, 0
	s_mov_b32 m0, s20
	v_lshl_add_u64 v[224:225], s[48:49], 0, v[160:161]
	ds_read_b128 v[172:175], v214 offset:32768
	ds_read_b128 v[176:179], v214 offset:33792
	ds_read_b128 v[180:183], v214 offset:34816
	ds_read_b128 v[184:187], v214 offset:35840
	ds_read_b128 v[188:191], v214 offset:36864
	ds_read_b128 v[192:195], v214 offset:37888
	ds_read_b128 v[196:199], v214 offset:38912
	ds_read_b128 v[200:203], v214 offset:39936
	global_load_lds_dwordx4 v[224:225], off
	v_lshl_add_u64 v[224:225], s[48:49], 0, v[164:165]
	s_mov_b32 m0, s21
	s_nop 0
	global_load_lds_dwordx4 v[224:225], off
	s_waitcnt vmcnt(8)
	s_waitcnt lgkmcnt(0)
	s_setprio 1
	s_waitcnt lgkmcnt(0)
	v_mfma_f32_16x16x32_bf16 v[124:127], v[128:131], v[172:175], v[124:127]
	v_mfma_f32_16x16x32_bf16 v[120:123], v[136:139], v[172:175], v[120:123]
	v_mfma_f32_16x16x32_bf16 v[116:119], v[128:131], v[180:183], v[116:119]
	v_mfma_f32_16x16x32_bf16 v[108:111], v[136:139], v[180:183], v[108:111]
	s_barrier
; #define PG8_STAGE(bufoff, gbase, voff) do { _Pragma("unroll") for (int _i = 0; _i < 2; ++_i) \
;         __builtin_amdgcn_global_load_lds((const unsigned*)((const char*)(gbase) + (voff)[_i]), (LAS unsigned*)(lds + (bufoff) + ldsw + _i * 8192), 16, 0, 0); } while (0)
; #define PG8_LDA(dst, b, h) do { _Pragma("unroll") for (int m = 0; m < 4; ++m) _Pragma("unroll") for (int k = 0; k < 2; ++k) dst[m][k] = *(const LAS bf16x8*)(lds + PG8_SA(b, h) + aoff + m * 2048 + k * 1024); } while (0)
; template <class Epi, bool ALIGN_EPI, bool SP2>
; __device__ __forceinline__ void gemm_phase(LAS unsigned char* lds, const int K, const Sched& S, const Epi& E) {
;     ...
;             PG8_WAIT_V(8); PG8_WAIT_L(0); PG8_BAR; PG8_MMA(0, 0, At, B0); PG8_MMA(0, 1, At, B1); PG8_BAR; PG8_SCHED;
;             PG8_LDA(At, 1, 1); PG8_STAGE(PG8_SB(1, 0), b3, voffB); PG8_STAGE(PG8_SB(1, 1), b3 + hstep, voffB); PG8_STAGE(PG8_SA(1, 0), a3, voffA);
;             PG8_WAIT_V(8); PG8_WAIT_L(0); PG8_BAR; PG8_MMA(1, 0, At, B0); PG8_MMA(1, 1, At, B1); PG8_BAR; PG8_SCHED;
;             } else {
;             PG8_LDB(B0, 0, 0); PG8_SCHED; PG8_LDA(At, 0, 0); PG8_STAGE(PG8_SA(1, 1), a1 + hstep, voffA);
;             PG8_WAIT_L(8); PG8_BAR; PG8_WAIT_L(0); PG8_MMA(0, 0, At, B0); PG8_BAR; PG8_SCHED;
;             PG8_LDB(B1, 0, 1); PG8_STAGE(PG8_SB(0, 0), b2, voffB);
;             PG8_BAR; PG8_WAIT_L(0); PG8_MMA(0, 1, At, B1); PG8_BAR;
;             PG8_LDA(At, 0, 1); PG8_STAGE(PG8_SA(0, 0), a2, voffA);
;             PG8_BAR; PG8_WAIT_L(0); PG8_MMA(1, 0, At, B0); PG8_BAR; PG8_SCHED;
;             PG8_STAGE(PG8_SB(0, 1), b2 + hstep, voffB);
;             PG8_WAIT_V(6); PG8_BAR; PG8_MMA(1, 1, At, B1); PG8_BAR;
;             PG8_LDB(B0, 1, 0); PG8_SCHED; PG8_LDA(At, 1, 0); PG8_STAGE(PG8_SA(0, 1), a2 + hstep, voffA);
;             PG8_WAIT_L(8); PG8_BAR; PG8_WAIT_L(0); PG8_MMA(0, 0, At, B0); PG8_BAR; PG8_SCHED;
;             PG8_LDB(B1, 1, 1); PG8_STAGE(PG8_SB(1, 0), b3, voffB);
;             PG8_BAR; PG8_WAIT_L(0); PG8_MMA(0, 1, At, B1); PG8_BAR;
;             PG8_LDA(At, 1, 1); PG8_STAGE(PG8_SA(1, 0), a3, voffA);
;             PG8_BAR; PG8_WAIT_L(0); PG8_MMA(1, 0, At, B0); PG8_BAR; PG8_SCHED;
;             PG8_STAGE(PG8_SB(1, 1), b3 + hstep, voffB);
;             PG8_WAIT_V(6); PG8_BAR; PG8_MMA(1, 1, At, B1); PG8_BAR;
;             }
;         }
;         if constexpr (ALIGN_EPI) { if (wr == 0) PG8_BAR; }
	v_mfma_f32_16x16x32_bf16 v[100:103], v[128:131], v[188:191], v[100:103]
	v_mfma_f32_16x16x32_bf16 v[92:95], v[136:139], v[188:191], v[92:95]
	v_mfma_f32_16x16x32_bf16 v[84:87], v[128:131], v[196:199], v[84:87]
	v_mfma_f32_16x16x32_bf16 v[76:79], v[136:139], v[196:199], v[76:79]
	v_mfma_f32_16x16x32_bf16 v[124:127], v[132:135], v[176:179], v[124:127]
	v_mfma_f32_16x16x32_bf16 v[120:123], v[140:143], v[176:179], v[120:123]
	v_mfma_f32_16x16x32_bf16 v[116:119], v[132:135], v[184:187], v[116:119]
	v_mfma_f32_16x16x32_bf16 v[108:111], v[140:143], v[184:187], v[108:111]
	v_mfma_f32_16x16x32_bf16 v[100:103], v[132:135], v[192:195], v[100:103]
	v_mfma_f32_16x16x32_bf16 v[92:95], v[140:143], v[192:195], v[92:95]
	v_mfma_f32_16x16x32_bf16 v[84:87], v[132:135], v[200:203], v[84:87]
	v_mfma_f32_16x16x32_bf16 v[76:79], v[140:143], v[200:203], v[76:79]
	s_setprio 0
	s_setprio 1
	v_mfma_f32_16x16x32_bf16 v[112:115], v[144:147], v[172:175], v[112:115]
	v_mfma_f32_16x16x32_bf16 v[104:107], v[152:155], v[172:175], v[104:107]
	v_mfma_f32_16x16x32_bf16 v[96:99], v[144:147], v[180:183], v[96:99]
	v_mfma_f32_16x16x32_bf16 v[88:91], v[152:155], v[180:183], v[88:91]
	v_mfma_f32_16x16x32_bf16 v[80:83], v[144:147], v[188:191], v[80:83]
	v_mfma_f32_16x16x32_bf16 v[72:75], v[152:155], v[188:191], v[72:75]
	v_mfma_f32_16x16x32_bf16 v[68:71], v[144:147], v[196:199], v[68:71]
	v_mfma_f32_16x16x32_bf16 v[64:67], v[152:155], v[196:199], v[64:67]
	v_mfma_f32_16x16x32_bf16 v[112:115], v[148:151], v[176:179], v[112:115]
	v_mfma_f32_16x16x32_bf16 v[104:107], v[156:159], v[176:179], v[104:107]
	v_mfma_f32_16x16x32_bf16 v[96:99], v[148:151], v[184:187], v[96:99]
	v_mfma_f32_16x16x32_bf16 v[88:91], v[156:159], v[184:187], v[88:91]
	v_mfma_f32_16x16x32_bf16 v[80:83], v[148:151], v[192:195], v[80:83]
	v_mfma_f32_16x16x32_bf16 v[72:75], v[156:159], v[192:195], v[72:75]
	v_mfma_f32_16x16x32_bf16 v[68:71], v[148:151], v[200:203], v[68:71]
	v_mfma_f32_16x16x32_bf16 v[64:67], v[156:159], v[200:203], v[64:67]
	s_setprio 0
	s_barrier
	s_add_i32 s48, s50, s97
	v_lshl_add_u64 v[204:205], v[204:205], 0, s[16:17]
	s_mov_b32 m0, s48
	ds_read_b128 v[172:175], v214 offset:49152
	ds_read_b128 v[176:179], v214 offset:50176
	ds_read_b128 v[180:183], v214 offset:51200
	ds_read_b128 v[184:187], v214 offset:52224
	ds_read_b128 v[188:191], v214 offset:53248
	ds_read_b128 v[192:195], v214 offset:54272
	ds_read_b128 v[196:199], v214 offset:55296
	ds_read_b128 v[200:203], v214 offset:56320
	global_load_lds_dwordx4 v[204:205], off
	s_add_i32 m0, s48, 0x2000
	s_add_u32 s48, s70, 0x40080
	v_lshl_add_u64 v[204:205], v[206:207], 0, s[16:17]
	s_addc_u32 s49, s71, 0
	s_add_i32 s50, s51, s97
	global_load_lds_dwordx4 v[204:205], off
	v_lshl_add_u64 v[204:205], s[48:49], 0, v[162:163]
	s_mov_b32 m0, s50
	s_nop 0
	global_load_lds_dwordx4 v[204:205], off
	v_lshl_add_u64 v[204:205], s[48:49], 0, v[166:167]
	s_add_i32 m0, s50, 0x2000
	s_nop 0
	global_load_lds_dwordx4 v[204:205], off
	v_lshl_add_u64 v[204:205], v[220:221], 0, s[16:17]
	s_mov_b32 m0, s26
	s_nop 0
	global_load_lds_dwordx4 v[204:205], off
	v_lshl_add_u64 v[204:205], v[222:223], 0, s[16:17]
	s_mov_b32 m0, s27
	s_nop 0
	global_load_lds_dwordx4 v[204:205], off
	s_waitcnt vmcnt(8)
	s_waitcnt lgkmcnt(0)
	s_setprio 1
	s_waitcnt lgkmcnt(0)
	v_mfma_f32_16x16x32_bf16 v[60:63], v[128:131], v[172:175], v[60:63]
	v_mfma_f32_16x16x32_bf16 v[56:59], v[136:139], v[172:175], v[56:59]
	v_mfma_f32_16x16x32_bf16 v[52:55], v[128:131], v[180:183], v[52:55]
	v_mfma_f32_16x16x32_bf16 v[44:47], v[136:139], v[180:183], v[44:47]
	s_barrier
	v_mfma_f32_16x16x32_bf16 v[36:39], v[128:131], v[188:191], v[36:39]
	v_mfma_f32_16x16x32_bf16 v[28:31], v[136:139], v[188:191], v[28:31]
	v_mfma_f32_16x16x32_bf16 v[20:23], v[128:131], v[196:199], v[20:23]
	v_mfma_f32_16x16x32_bf16 v[12:15], v[136:139], v[196:199], v[12:15]
	v_mfma_f32_16x16x32_bf16 v[60:63], v[132:135], v[176:179], v[60:63]
	v_mfma_f32_16x16x32_bf16 v[56:59], v[140:143], v[176:179], v[56:59]
	v_mfma_f32_16x16x32_bf16 v[52:55], v[132:135], v[184:187], v[52:55]
	v_mfma_f32_16x16x32_bf16 v[44:47], v[140:143], v[184:187], v[44:47]
	v_mfma_f32_16x16x32_bf16 v[36:39], v[132:135], v[192:195], v[36:39]
	v_mfma_f32_16x16x32_bf16 v[28:31], v[140:143], v[192:195], v[28:31]
	v_mfma_f32_16x16x32_bf16 v[20:23], v[132:135], v[200:203], v[20:23]
	v_mfma_f32_16x16x32_bf16 v[12:15], v[140:143], v[200:203], v[12:15]
	s_setprio 0
	s_setprio 1
	v_mfma_f32_16x16x32_bf16 v[48:51], v[144:147], v[172:175], v[48:51]
	v_mfma_f32_16x16x32_bf16 v[40:43], v[152:155], v[172:175], v[40:43]
	v_mfma_f32_16x16x32_bf16 v[32:35], v[144:147], v[180:183], v[32:35]
	v_mfma_f32_16x16x32_bf16 v[24:27], v[152:155], v[180:183], v[24:27]
	v_mfma_f32_16x16x32_bf16 v[16:19], v[144:147], v[188:191], v[16:19]
	v_mfma_f32_16x16x32_bf16 v[8:11], v[152:155], v[188:191], v[8:11]
	v_mfma_f32_16x16x32_bf16 v[4:7], v[144:147], v[196:199], v[4:7]
	v_mfma_f32_16x16x32_bf16 v[0:3], v[152:155], v[196:199], v[0:3]
	v_mfma_f32_16x16x32_bf16 v[48:51], v[148:151], v[176:179], v[48:51]
	v_mfma_f32_16x16x32_bf16 v[40:43], v[156:159], v[176:179], v[40:43]
	v_mfma_f32_16x16x32_bf16 v[32:35], v[148:151], v[184:187], v[32:35]
	v_mfma_f32_16x16x32_bf16 v[24:27], v[156:159], v[184:187], v[24:27]
	v_mfma_f32_16x16x32_bf16 v[16:19], v[148:151], v[192:195], v[16:19]
	v_mfma_f32_16x16x32_bf16 v[8:11], v[156:159], v[192:195], v[8:11]
	v_mfma_f32_16x16x32_bf16 v[4:7], v[148:151], v[200:203], v[4:7]
	v_mfma_f32_16x16x32_bf16 v[0:3], v[156:159], v[200:203], v[0:3]
	s_setprio 0
	s_barrier
	s_add_i32 s45, s45, 2
	s_add_u32 s4, s4, 0x100
	s_addc_u32 s5, s5, 0
	s_add_u32 s35, s35, 0x100
	s_addc_u32 s43, s43, 0
	s_cmp_gt_u32 s45, 13
	s_cbranch_scc0 .LBB0_357
	s_and_b64 vcc, exec, s[18:19]
	s_cbranch_vccz .LBB0_360
	s_barrier

;     __device__ __forceinline__ const char* aptr(const Unit& u) const { return (u.kind == 1 ? A1 : A0) + (size_t)u.pm * tstep; }
;     __device__ __forceinline__ const char* bptr(const Unit& u) const { return (u.kind == 1 ? B1 : B0) + (size_t)u.pn * tstep; }
; #define PG8_STAGE(bufoff, gbase, voff) do { _Pragma("unroll") for (int _i = 0; _i < 2; ++_i) \
;         __builtin_amdgcn_global_load_lds((const unsigned*)((const char*)(gbase) + (voff)[_i]), (LAS unsigned*)(lds + (bufoff) + ldsw + _i * 8192), 16, 0, 0); } while (0)
; #define PG8_LDA(dst, b, h) do { _Pragma("unroll") for (int m = 0; m < 4; ++m) _Pragma("unroll") for (int k = 0; k < 2; ++k) dst[m][k] = *(const LAS bf16x8*)(lds + PG8_SA(b, h) + aoff + m * 2048 + k * 1024); } while (0)
; #define PG8_LDB(dst, b, h) do { _Pragma("unroll") for (int n = 0; n < 2; ++n) _Pragma("unroll") for (int k = 0; k < 2; ++k) dst[n][k] = *(const LAS bf16x8*)(lds + PG8_SB(b, h) + boff + n * 2048 + k * 1024); } while (0)
; #define PG8_WAIT_V(n) asm volatile("s_waitcnt vmcnt(" #n ")" ::: "memory")
; template <class Epi, bool ALIGN_EPI, bool SP2>
; __device__ __forceinline__ void gemm_phase(LAS unsigned char* lds, const int K, const Sched& S, const Epi& E) {
;     ...
;     for (;;) {
;         const bool has_next = S.next(ui + 1, nxt);
;         const char* nA = has_next ? S.aptr(nxt) : cA; const char* nB = has_next ? S.bptr(nxt) : cB;
;         for (int t = 0; t < nt; t += 2) {
;             const bool last = (t == nt - 2);
;             const char* a1 = cA + (size_t)(t + 1) * kstep;
;             const char* a2 = last ? nA : cA + (size_t)(t + 2) * kstep; const char* b2 = last ? nB : cB + (size_t)(t + 2) * kstep;
;             const char* a3 = a2 + kstep; const char* b3 = b2 + kstep;
;             if constexpr (SP2) {
;             PG8_LDB(B0, 0, 0); PG8_LDB(B1, 0, 1); PG8_SCHED; PG8_LDA(At, 0, 0); PG8_STAGE(PG8_SA(1, 1), a1 + hstep, voffA);
;             PG8_WAIT_V(8); PG8_WAIT_L(0); PG8_BAR; PG8_MMA(0, 0, At, B0); PG8_MMA(0, 1, At, B1); PG8_BAR; PG8_SCHED;
;     ...
; #pragma unroll
;         for (int a = 0; a < 2; ++a)
; #pragma unroll
;             for (int b = 0; b < 2; ++b)
; #pragma unroll
;                 for (int m = 0; m < 4; ++m)
; #pragma unroll
;                     for (int n = 0; n < 2; ++n) acc[a][b][m][n] = (f32x4){0.f, 0.f, 0.f, 0.f};
;         cur = nxt; cA = nA; cB = nB; ++ui;
.LBB0_694:
	s_ashr_i32 s19, s18, 31
	s_lshl_b64 s[22:23], s[18:19], 19
	s_add_u32 s22, s38, s22
	s_addc_u32 s23, s39, s23
	s_and_b64 s[26:27], s[24:25], exec
	s_cselect_b32 s7, s23, s31
	s_cselect_b32 s19, s22, s30
	s_ashr_i32 s21, s20, 31
	s_lshl_b64 s[26:27], s[20:21], 19
	s_add_u32 s26, s40, s26
	s_addc_u32 s27, s41, s27
	s_and_b64 s[36:37], s[24:25], exec
	s_cselect_b32 s21, s27, s35
	s_cselect_b32 s56, s26, s34
	s_add_u32 s30, s30, 0x40080
	s_addc_u32 s31, s31, 0
	s_add_u32 s57, s34, 0x100
	v_mov_b64_e32 v[0:1], 0
	v_mov_b64_e32 v[2:3], 0
	v_mov_b64_e32 v[4:5], 0
	v_mov_b64_e32 v[6:7], 0
	v_mov_b64_e32 v[8:9], 0
	v_mov_b64_e32 v[10:11], 0
	v_mov_b64_e32 v[12:13], 0
	v_mov_b64_e32 v[14:15], 0
	v_mov_b64_e32 v[16:17], 0
	v_mov_b64_e32 v[18:19], 0
	v_mov_b64_e32 v[20:21], 0
	v_mov_b64_e32 v[22:23], 0
	v_mov_b64_e32 v[24:25], 0
	v_mov_b64_e32 v[26:27], 0
	v_mov_b64_e32 v[28:29], 0
	v_mov_b64_e32 v[30:31], 0
	v_mov_b64_e32 v[32:33], 0
	v_mov_b64_e32 v[34:35], 0
	v_mov_b64_e32 v[36:37], 0
	v_mov_b64_e32 v[38:39], 0
	v_mov_b64_e32 v[40:41], 0
	v_mov_b64_e32 v[42:43], 0
	v_mov_b64_e32 v[44:45], 0
	v_mov_b64_e32 v[46:47], 0
	v_mov_b64_e32 v[48:49], 0
	v_mov_b64_e32 v[50:51], 0
	v_mov_b64_e32 v[52:53], 0
	v_mov_b64_e32 v[54:55], 0
	v_mov_b64_e32 v[56:57], 0
	v_mov_b64_e32 v[58:59], 0
	v_mov_b64_e32 v[60:61], 0
	v_mov_b64_e32 v[62:63], 0
	v_mov_b64_e32 v[64:65], 0
	v_mov_b64_e32 v[66:67], 0
	v_mov_b64_e32 v[68:69], 0
	v_mov_b64_e32 v[70:71], 0
	v_mov_b64_e32 v[72:73], 0
	v_mov_b64_e32 v[74:75], 0
	v_mov_b64_e32 v[76:77], 0
	v_mov_b64_e32 v[78:79], 0
	v_mov_b64_e32 v[80:81], 0
	v_mov_b64_e32 v[82:83], 0
	v_mov_b64_e32 v[84:85], 0
	v_mov_b64_e32 v[86:87], 0
	v_mov_b64_e32 v[88:89], 0
	v_mov_b64_e32 v[90:91], 0
	v_mov_b64_e32 v[92:93], 0
	v_mov_b64_e32 v[94:95], 0
	v_mov_b64_e32 v[96:97], 0
	v_mov_b64_e32 v[98:99], 0
	v_mov_b64_e32 v[100:101], 0
	v_mov_b64_e32 v[102:103], 0
	v_mov_b64_e32 v[104:105], 0
	v_mov_b64_e32 v[106:107], 0
	v_mov_b64_e32 v[108:109], 0
	v_mov_b64_e32 v[110:111], 0
	v_mov_b64_e32 v[112:113], 0
	v_mov_b64_e32 v[114:115], 0
	v_mov_b64_e32 v[116:117], 0
	v_mov_b64_e32 v[118:119], 0
	v_mov_b64_e32 v[120:121], 0
	v_mov_b64_e32 v[122:123], 0
	v_mov_b64_e32 v[124:125], 0
	v_mov_b64_e32 v[126:127], 0
	s_addc_u32 s58, s35, 0
	s_mov_b32 s59, -2
	s_waitcnt lgkmcnt(0)
.LBB0_695:
	ds_read_b128 v[128:131], v203
	ds_read_b128 v[132:135], v203 offset:1024
	ds_read_b128 v[136:139], v203 offset:2048
	ds_read_b128 v[140:143], v203 offset:3072
	ds_read_b128 v[144:147], v204
	ds_read_b128 v[148:151], v204 offset:1024
	ds_read_b128 v[152:155], v204 offset:2048
	ds_read_b128 v[156:159], v204 offset:3072
	s_add_u32 s34, s30, 0xfffc0080
	s_addc_u32 s35, s31, -1
	s_cmp_eq_u32 s59, 12
	s_cselect_b32 s37, s7, s35
	s_cselect_b32 s36, s19, s34
	s_cselect_b32 s35, s21, s58
	s_cselect_b32 s34, s56, s57
	s_mov_b32 m0, s53
	v_lshl_add_u64 v[214:215], s[30:31], 0, v[184:185]
	ds_read_b128 v[160:163], v205
	ds_read_b128 v[164:167], v205 offset:1024
	ds_read_b128 v[168:171], v205 offset:2048
	ds_read_b128 v[172:175], v205 offset:3072
	ds_read_b128 v[188:191], v205 offset:4096
	ds_read_b128 v[192:195], v205 offset:5120
	ds_read_b128 v[196:199], v205 offset:6144
	ds_read_b128 v[210:213], v205 offset:7168
	global_load_lds_dwordx4 v[214:215], off
	v_lshl_add_u64 v[214:215], s[30:31], 0, v[186:187]
	s_mov_b32 m0, s54
	s_nop 0
	global_load_lds_dwordx4 v[214:215], off
	s_waitcnt vmcnt(8)
	s_waitcnt lgkmcnt(0)
	s_setprio 1
	s_waitcnt lgkmcnt(0)
	v_mfma_f32_16x16x32_bf16 v[124:127], v[128:131], v[160:163], v[124:127]
	v_mfma_f32_16x16x32_bf16 v[120:123], v[136:139], v[160:163], v[120:123]
	v_mfma_f32_16x16x32_bf16 v[108:111], v[128:131], v[168:171], v[108:111]
	v_mfma_f32_16x16x32_bf16 v[104:107], v[136:139], v[168:171], v[104:107]
	s_barrier
	v_mfma_f32_16x16x32_bf16 v[92:95], v[128:131], v[188:191], v[92:95]
	v_mfma_f32_16x16x32_bf16 v[88:91], v[136:139], v[188:191], v[88:91]
	v_mfma_f32_16x16x32_bf16 v[76:79], v[128:131], v[196:199], v[76:79]
	v_mfma_f32_16x16x32_bf16 v[72:75], v[136:139], v[196:199], v[72:75]
	v_mfma_f32_16x16x32_bf16 v[124:127], v[132:135], v[164:167], v[124:127]
	v_mfma_f32_16x16x32_bf16 v[120:123], v[140:143], v[164:167], v[120:123]
	v_mfma_f32_16x16x32_bf16 v[108:111], v[132:135], v[172:175], v[108:111]
	v_mfma_f32_16x16x32_bf16 v[104:107], v[140:143], v[172:175], v[104:107]
	v_mfma_f32_16x16x32_bf16 v[92:95], v[132:135], v[192:195], v[92:95]
	v_mfma_f32_16x16x32_bf16 v[88:91], v[140:143], v[192:195], v[88:91]
	v_mfma_f32_16x16x32_bf16 v[76:79], v[132:135], v[210:213], v[76:79]
	v_mfma_f32_16x16x32_bf16 v[72:75], v[140:143], v[210:213], v[72:75]
	s_setprio 0
	s_setprio 1
	v_mfma_f32_16x16x32_bf16 v[116:119], v[144:147], v[160:163], v[116:119]
	v_mfma_f32_16x16x32_bf16 v[112:115], v[152:155], v[160:163], v[112:115]
	v_mfma_f32_16x16x32_bf16 v[100:103], v[144:147], v[168:171], v[100:103]
	v_mfma_f32_16x16x32_bf16 v[96:99], v[152:155], v[168:171], v[96:99]
	v_mfma_f32_16x16x32_bf16 v[84:87], v[144:147], v[188:191], v[84:87]
	v_mfma_f32_16x16x32_bf16 v[80:83], v[152:155], v[188:191], v[80:83]
	v_mfma_f32_16x16x32_bf16 v[68:71], v[144:147], v[196:199], v[68:71]
	v_mfma_f32_16x16x32_bf16 v[64:67], v[152:155], v[196:199], v[64:67]
	v_mfma_f32_16x16x32_bf16 v[116:119], v[148:151], v[164:167], v[116:119]
	v_mfma_f32_16x16x32_bf16 v[112:115], v[156:159], v[164:167], v[112:115]
	v_mfma_f32_16x16x32_bf16 v[100:103], v[148:151], v[172:175], v[100:103]
	v_mfma_f32_16x16x32_bf16 v[96:99], v[156:159], v[172:175], v[96:99]
	v_mfma_f32_16x16x32_bf16 v[84:87], v[148:151], v[192:195], v[84:87]
	v_mfma_f32_16x16x32_bf16 v[80:83], v[156:159], v[192:195], v[80:83]
	v_mfma_f32_16x16x32_bf16 v[68:71], v[148:151], v[210:213], v[68:71]
	v_mfma_f32_16x16x32_bf16 v[64:67], v[156:159], v[210:213], v[64:67]
	s_setprio 0
	s_barrier
; #define PG8_STAGE(bufoff, gbase, voff) do { _Pragma("unroll") for (int _i = 0; _i < 2; ++_i) \
;         __builtin_amdgcn_global_load_lds((const unsigned*)((const char*)(gbase) + (voff)[_i]), (LAS unsigned*)(lds + (bufoff) + ldsw + _i * 8192), 16, 0, 0); } while (0)
; #define PG8_LDA(dst, b, h) do { _Pragma("unroll") for (int m = 0; m < 4; ++m) _Pragma("unroll") for (int k = 0; k < 2; ++k) dst[m][k] = *(const LAS bf16x8*)(lds + PG8_SA(b, h) + aoff + m * 2048 + k * 1024); } while (0)
; #define PG8_LDB(dst, b, h) do { _Pragma("unroll") for (int n = 0; n < 2; ++n) _Pragma("unroll") for (int k = 0; k < 2; ++k) dst[n][k] = *(const LAS bf16x8*)(lds + PG8_SB(b, h) + boff + n * 2048 + k * 1024); } while (0)
; #define PG8_MMA(ai, bj, At, Bt) do { __builtin_amdgcn_s_setprio(1); _Pragma("unroll") for (int m = 0; m < 4; ++m) _Pragma("unroll") for (int n = 0; n < 2; ++n) _Pragma("unroll") for (int k = 0; k < 2; ++k) \
;         acc[ai][bj][m][n] = __builtin_amdgcn_mfma_f32_16x16x32_bf16(Bt[n][k], At[m][k], acc[ai][bj][m][n], 0, 0, 0); __builtin_amdgcn_s_setprio(0); } while (0)
; #define PG8_WAIT_V(n) asm volatile("s_waitcnt vmcnt(" #n ")" ::: "memory")
; #define PG8_WAIT_L(n) asm volatile("s_waitcnt lgkmcnt(" #n ")" ::: "memory")
; #define PG8_BAR __builtin_amdgcn_s_barrier()
; template <class Epi, bool ALIGN_EPI, bool SP2>
; __device__ __forceinline__ void gemm_phase(LAS unsigned char* lds, const int K, const Sched& S, const Epi& E) {
;     ...
;             PG8_WAIT_V(8); PG8_WAIT_L(0); PG8_BAR; PG8_MMA(0, 0, At, B0); PG8_MMA(0, 1, At, B1); PG8_BAR; PG8_SCHED;
;             PG8_LDA(At, 0, 1); PG8_STAGE(PG8_SB(0, 0), b2, voffB); PG8_STAGE(PG8_SB(0, 1), b2 + hstep, voffB); PG8_STAGE(PG8_SA(0, 0), a2, voffA);
;             PG8_WAIT_V(8); PG8_WAIT_L(0); PG8_BAR; PG8_MMA(1, 0, At, B0); PG8_MMA(1, 1, At, B1); PG8_BAR; PG8_SCHED;
;             PG8_LDB(B0, 1, 0); PG8_LDB(B1, 1, 1); PG8_SCHED; PG8_LDA(At, 1, 0); PG8_STAGE(PG8_SA(0, 1), a2 + hstep, voffA);
;             PG8_WAIT_V(8); PG8_WAIT_L(0); PG8_BAR; PG8_MMA(0, 0, At, B0); PG8_MMA(0, 1, At, B1); PG8_BAR; PG8_SCHED;
;             PG8_LDA(At, 1, 1); PG8_STAGE(PG8_SB(1, 0), b3, voffB); PG8_STAGE(PG8_SB(1, 1), b3 + hstep, voffB); PG8_STAGE(PG8_SA(1, 0), a3, voffA);
;             PG8_WAIT_V(8); PG8_WAIT_L(0); PG8_BAR; PG8_MMA(1, 0, At, B0); PG8_MMA(1, 1, At, B1); PG8_BAR; PG8_SCHED;
	s_mov_b32 m0, s55
	v_lshl_add_u64 v[214:215], s[34:35], 0, v[178:179]
	ds_read_b128 v[160:163], v205 offset:16384
	ds_read_b128 v[164:167], v205 offset:17408
	ds_read_b128 v[168:171], v205 offset:18432
	ds_read_b128 v[172:175], v205 offset:19456
	ds_read_b128 v[188:191], v205 offset:20480
	ds_read_b128 v[192:195], v205 offset:21504
	ds_read_b128 v[196:199], v205 offset:22528
	ds_read_b128 v[210:213], v205 offset:23552
	global_load_lds_dwordx4 v[214:215], off
	s_add_i32 m0, s55, 0x2000
	s_add_u32 s60, s34, 0x40000
	v_lshl_add_u64 v[216:217], s[34:35], 0, v[182:183]
	s_addc_u32 s61, s35, 0
	s_add_i32 s62, s51, s42
	global_load_lds_dwordx4 v[216:217], off
	v_lshl_add_u64 v[218:219], s[60:61], 0, v[178:179]
	s_mov_b32 m0, s62
	v_lshl_add_u64 v[220:221], s[36:37], 0, v[180:181]
	global_load_lds_dwordx4 v[218:219], off
	v_lshl_add_u64 v[218:219], s[60:61], 0, v[182:183]
	s_add_i32 m0, s62, 0x2000
	s_nop 0
	global_load_lds_dwordx4 v[218:219], off
	v_lshl_add_u64 v[218:219], s[36:37], 0, v[176:177]
	s_mov_b32 m0, s29
	s_nop 0
	global_load_lds_dwordx4 v[218:219], off
	s_mov_b32 m0, s43
	s_nop 0
	global_load_lds_dwordx4 v[220:221], off
	s_waitcnt vmcnt(8)
	s_waitcnt lgkmcnt(0)
	s_setprio 1
	s_waitcnt lgkmcnt(0)
	v_mfma_f32_16x16x32_bf16 v[60:63], v[128:131], v[160:163], v[60:63]
	v_mfma_f32_16x16x32_bf16 v[56:59], v[136:139], v[160:163], v[56:59]
	v_mfma_f32_16x16x32_bf16 v[44:47], v[128:131], v[168:171], v[44:47]
	v_mfma_f32_16x16x32_bf16 v[40:43], v[136:139], v[168:171], v[40:43]
	s_barrier
	v_mfma_f32_16x16x32_bf16 v[28:31], v[128:131], v[188:191], v[28:31]
	v_mfma_f32_16x16x32_bf16 v[24:27], v[136:139], v[188:191], v[24:27]
	v_mfma_f32_16x16x32_bf16 v[12:15], v[128:131], v[196:199], v[12:15]
	v_mfma_f32_16x16x32_bf16 v[8:11], v[136:139], v[196:199], v[8:11]
	v_mfma_f32_16x16x32_bf16 v[60:63], v[132:135], v[164:167], v[60:63]
	v_mfma_f32_16x16x32_bf16 v[56:59], v[140:143], v[164:167], v[56:59]
	v_mfma_f32_16x16x32_bf16 v[44:47], v[132:135], v[172:175], v[44:47]
	v_mfma_f32_16x16x32_bf16 v[40:43], v[140:143], v[172:175], v[40:43]
	v_mfma_f32_16x16x32_bf16 v[28:31], v[132:135], v[192:195], v[28:31]
	v_mfma_f32_16x16x32_bf16 v[24:27], v[140:143], v[192:195], v[24:27]
	v_mfma_f32_16x16x32_bf16 v[12:15], v[132:135], v[210:213], v[12:15]
	v_mfma_f32_16x16x32_bf16 v[8:11], v[140:143], v[210:213], v[8:11]
	s_setprio 0
	s_setprio 1
	v_mfma_f32_16x16x32_bf16 v[52:55], v[144:147], v[160:163], v[52:55]
	v_mfma_f32_16x16x32_bf16 v[48:51], v[152:155], v[160:163], v[48:51]
	v_mfma_f32_16x16x32_bf16 v[36:39], v[144:147], v[168:171], v[36:39]
	v_mfma_f32_16x16x32_bf16 v[32:35], v[152:155], v[168:171], v[32:35]
	v_mfma_f32_16x16x32_bf16 v[20:23], v[144:147], v[188:191], v[20:23]
	v_mfma_f32_16x16x32_bf16 v[16:19], v[152:155], v[188:191], v[16:19]
	v_mfma_f32_16x16x32_bf16 v[4:7], v[144:147], v[196:199], v[4:7]
	v_mfma_f32_16x16x32_bf16 v[0:3], v[152:155], v[196:199], v[0:3]
	v_mfma_f32_16x16x32_bf16 v[52:55], v[148:151], v[164:167], v[52:55]
	v_mfma_f32_16x16x32_bf16 v[48:51], v[156:159], v[164:167], v[48:51]
	v_mfma_f32_16x16x32_bf16 v[36:39], v[148:151], v[172:175], v[36:39]
	v_mfma_f32_16x16x32_bf16 v[32:35], v[156:159], v[172:175], v[32:35]
	v_mfma_f32_16x16x32_bf16 v[20:23], v[148:151], v[192:195], v[20:23]
	v_mfma_f32_16x16x32_bf16 v[16:19], v[156:159], v[192:195], v[16:19]
	v_mfma_f32_16x16x32_bf16 v[4:7], v[148:151], v[210:213], v[4:7]
	v_mfma_f32_16x16x32_bf16 v[0:3], v[156:159], v[210:213], v[0:3]
	s_setprio 0
	s_barrier
	s_add_i32 s60, 0, 0x18000
	s_add_i32 s61, 0, 0x1c000
	v_add_u32_e32 v140, s60, v202
	v_add_u32_e32 v156, s61, v202
	ds_read_b128 v[128:131], v140
	ds_read_b128 v[132:135], v140 offset:1024
	ds_read_b128 v[136:139], v140 offset:2048
	ds_read_b128 v[140:143], v140 offset:3072
	ds_read_b128 v[144:147], v156
	ds_read_b128 v[148:151], v156 offset:1024
	ds_read_b128 v[152:155], v156 offset:2048
	ds_read_b128 v[156:159], v156 offset:3072
	s_add_u32 s36, s36, 0x40000
	s_addc_u32 s37, s37, 0
	s_mov_b32 m0, s44
	v_lshl_add_u64 v[222:223], s[36:37], 0, v[176:177]
	ds_read_b128 v[160:163], v205 offset:32768
	ds_read_b128 v[164:167], v205 offset:33792
	ds_read_b128 v[168:171], v205 offset:34816
	ds_read_b128 v[172:175], v205 offset:35840
	ds_read_b128 v[188:191], v205 offset:36864
	ds_read_b128 v[192:195], v205 offset:37888
	ds_read_b128 v[196:199], v205 offset:38912
	ds_read_b128 v[210:213], v205 offset:39936
	global_load_lds_dwordx4 v[222:223], off
	v_lshl_add_u64 v[222:223], s[36:37], 0, v[180:181]
	s_mov_b32 m0, s45
	s_nop 0
	global_load_lds_dwordx4 v[222:223], off
	s_waitcnt vmcnt(8)
	s_waitcnt lgkmcnt(0)
	s_setprio 1
	s_waitcnt lgkmcnt(0)
	v_mfma_f32_16x16x32_bf16 v[124:127], v[128:131], v[160:163], v[124:127]
	v_mfma_f32_16x16x32_bf16 v[120:123], v[136:139], v[160:163], v[120:123]
	v_mfma_f32_16x16x32_bf16 v[108:111], v[128:131], v[168:171], v[108:111]
	v_mfma_f32_16x16x32_bf16 v[104:107], v[136:139], v[168:171], v[104:107]
	s_barrier
; #define PG8_STAGE(bufoff, gbase, voff) do { _Pragma("unroll") for (int _i = 0; _i < 2; ++_i) \
;         __builtin_amdgcn_global_load_lds((const unsigned*)((const char*)(gbase) + (voff)[_i]), (LAS unsigned*)(lds + (bufoff) + ldsw + _i * 8192), 16, 0, 0); } while (0)
; #define PG8_LDA(dst, b, h) do { _Pragma("unroll") for (int m = 0; m < 4; ++m) _Pragma("unroll") for (int k = 0; k < 2; ++k) dst[m][k] = *(const LAS bf16x8*)(lds + PG8_SA(b, h) + aoff + m * 2048 + k * 1024); } while (0)
; template <class Epi, bool ALIGN_EPI, bool SP2>
; __device__ __forceinline__ void gemm_phase(LAS unsigned char* lds, const int K, const Sched& S, const Epi& E) {
;     ...
;             PG8_WAIT_V(8); PG8_WAIT_L(0); PG8_BAR; PG8_MMA(0, 0, At, B0); PG8_MMA(0, 1, At, B1); PG8_BAR; PG8_SCHED;
;             PG8_LDA(At, 1, 1); PG8_STAGE(PG8_SB(1, 0), b3, voffB); PG8_STAGE(PG8_SB(1, 1), b3 + hstep, voffB); PG8_STAGE(PG8_SA(1, 0), a3, voffA);
;             PG8_WAIT_V(8); PG8_WAIT_L(0); PG8_BAR; PG8_MMA(1, 0, At, B0); PG8_MMA(1, 1, At, B1); PG8_BAR; PG8_SCHED;
;             } else {
;             PG8_LDB(B0, 0, 0); PG8_SCHED; PG8_LDA(At, 0, 0); PG8_STAGE(PG8_SA(1, 1), a1 + hstep, voffA);
;             PG8_WAIT_L(8); PG8_BAR; PG8_WAIT_L(0); PG8_MMA(0, 0, At, B0); PG8_BAR; PG8_SCHED;
;             PG8_LDB(B1, 0, 1); PG8_STAGE(PG8_SB(0, 0), b2, voffB);
;             PG8_BAR; PG8_WAIT_L(0); PG8_MMA(0, 1, At, B1); PG8_BAR;
;             PG8_LDA(At, 0, 1); PG8_STAGE(PG8_SA(0, 0), a2, voffA);
;             PG8_BAR; PG8_WAIT_L(0); PG8_MMA(1, 0, At, B0); PG8_BAR; PG8_SCHED;
;             PG8_STAGE(PG8_SB(0, 1), b2 + hstep, voffB);
;             PG8_WAIT_V(6); PG8_BAR; PG8_MMA(1, 1, At, B1); PG8_BAR;
;             PG8_LDB(B0, 1, 0); PG8_SCHED; PG8_LDA(At, 1, 0); PG8_STAGE(PG8_SA(0, 1), a2 + hstep, voffA);
;             PG8_WAIT_L(8); PG8_BAR; PG8_WAIT_L(0); PG8_MMA(0, 0, At, B0); PG8_BAR; PG8_SCHED;
;             PG8_LDB(B1, 1, 1); PG8_STAGE(PG8_SB(1, 0), b3, voffB);
;             PG8_BAR; PG8_WAIT_L(0); PG8_MMA(0, 1, At, B1); PG8_BAR;
;             PG8_LDA(At, 1, 1); PG8_STAGE(PG8_SA(1, 0), a3, voffA);
;             PG8_BAR; PG8_WAIT_L(0); PG8_MMA(1, 0, At, B0); PG8_BAR; PG8_SCHED;
;             PG8_STAGE(PG8_SB(1, 1), b3 + hstep, voffB);
;             PG8_WAIT_V(6); PG8_BAR; PG8_MMA(1, 1, At, B1); PG8_BAR;
;             }
;         }
;         if constexpr (ALIGN_EPI) { if (wr == 0) PG8_BAR; }
	v_mfma_f32_16x16x32_bf16 v[92:95], v[128:131], v[188:191], v[92:95]
	v_mfma_f32_16x16x32_bf16 v[88:91], v[136:139], v[188:191], v[88:91]
	v_mfma_f32_16x16x32_bf16 v[76:79], v[128:131], v[196:199], v[76:79]
	v_mfma_f32_16x16x32_bf16 v[72:75], v[136:139], v[196:199], v[72:75]
	v_mfma_f32_16x16x32_bf16 v[124:127], v[132:135], v[164:167], v[124:127]
	v_mfma_f32_16x16x32_bf16 v[120:123], v[140:143], v[164:167], v[120:123]
	v_mfma_f32_16x16x32_bf16 v[108:111], v[132:135], v[172:175], v[108:111]
	v_mfma_f32_16x16x32_bf16 v[104:107], v[140:143], v[172:175], v[104:107]
	v_mfma_f32_16x16x32_bf16 v[92:95], v[132:135], v[192:195], v[92:95]
	v_mfma_f32_16x16x32_bf16 v[88:91], v[140:143], v[192:195], v[88:91]
	v_mfma_f32_16x16x32_bf16 v[76:79], v[132:135], v[210:213], v[76:79]
	v_mfma_f32_16x16x32_bf16 v[72:75], v[140:143], v[210:213], v[72:75]
	s_setprio 0
	s_setprio 1
	v_mfma_f32_16x16x32_bf16 v[116:119], v[144:147], v[160:163], v[116:119]
	v_mfma_f32_16x16x32_bf16 v[112:115], v[152:155], v[160:163], v[112:115]
	v_mfma_f32_16x16x32_bf16 v[100:103], v[144:147], v[168:171], v[100:103]
	v_mfma_f32_16x16x32_bf16 v[96:99], v[152:155], v[168:171], v[96:99]
	v_mfma_f32_16x16x32_bf16 v[84:87], v[144:147], v[188:191], v[84:87]
	v_mfma_f32_16x16x32_bf16 v[80:83], v[152:155], v[188:191], v[80:83]
	v_mfma_f32_16x16x32_bf16 v[68:71], v[144:147], v[196:199], v[68:71]
	v_mfma_f32_16x16x32_bf16 v[64:67], v[152:155], v[196:199], v[64:67]
	v_mfma_f32_16x16x32_bf16 v[116:119], v[148:151], v[164:167], v[116:119]
	v_mfma_f32_16x16x32_bf16 v[112:115], v[156:159], v[164:167], v[112:115]
	v_mfma_f32_16x16x32_bf16 v[100:103], v[148:151], v[172:175], v[100:103]
	v_mfma_f32_16x16x32_bf16 v[96:99], v[156:159], v[172:175], v[96:99]
	v_mfma_f32_16x16x32_bf16 v[84:87], v[148:151], v[192:195], v[84:87]
	v_mfma_f32_16x16x32_bf16 v[80:83], v[156:159], v[192:195], v[80:83]
	v_mfma_f32_16x16x32_bf16 v[68:71], v[148:151], v[210:213], v[68:71]
	v_mfma_f32_16x16x32_bf16 v[64:67], v[156:159], v[210:213], v[64:67]
	s_setprio 0
	s_barrier
	s_add_i32 s36, s60, s42
	v_lshl_add_u64 v[214:215], v[214:215], 0, s[14:15]
	s_mov_b32 m0, s36
	ds_read_b128 v[160:163], v205 offset:49152
	ds_read_b128 v[164:167], v205 offset:50176
	ds_read_b128 v[168:171], v205 offset:51200
	ds_read_b128 v[172:175], v205 offset:52224
	ds_read_b128 v[188:191], v205 offset:53248
	ds_read_b128 v[192:195], v205 offset:54272
	ds_read_b128 v[196:199], v205 offset:55296
	ds_read_b128 v[210:213], v205 offset:56320
	global_load_lds_dwordx4 v[214:215], off
	s_add_i32 m0, s36, 0x2000
	s_add_u32 s34, s34, 0x40080
	v_lshl_add_u64 v[214:215], v[216:217], 0, s[14:15]
	s_addc_u32 s35, s35, 0
	s_add_i32 s36, s61, s42
	global_load_lds_dwordx4 v[214:215], off
	v_lshl_add_u64 v[214:215], s[34:35], 0, v[178:179]
	s_mov_b32 m0, s36
	s_nop 0
	global_load_lds_dwordx4 v[214:215], off
	v_lshl_add_u64 v[214:215], s[34:35], 0, v[182:183]
	s_add_i32 m0, s36, 0x2000
	s_nop 0
	global_load_lds_dwordx4 v[214:215], off
	v_lshl_add_u64 v[214:215], v[218:219], 0, s[14:15]
	s_mov_b32 m0, s49
	s_nop 0
	global_load_lds_dwordx4 v[214:215], off
	v_lshl_add_u64 v[214:215], v[220:221], 0, s[14:15]
	s_mov_b32 m0, s50
	s_nop 0
	global_load_lds_dwordx4 v[214:215], off
	s_waitcnt vmcnt(8)
	s_waitcnt lgkmcnt(0)
	s_setprio 1
	s_waitcnt lgkmcnt(0)
	v_mfma_f32_16x16x32_bf16 v[60:63], v[128:131], v[160:163], v[60:63]
	v_mfma_f32_16x16x32_bf16 v[56:59], v[136:139], v[160:163], v[56:59]
	v_mfma_f32_16x16x32_bf16 v[44:47], v[128:131], v[168:171], v[44:47]
	v_mfma_f32_16x16x32_bf16 v[40:43], v[136:139], v[168:171], v[40:43]
	s_barrier
	v_mfma_f32_16x16x32_bf16 v[28:31], v[128:131], v[188:191], v[28:31]
	v_mfma_f32_16x16x32_bf16 v[24:27], v[136:139], v[188:191], v[24:27]
	v_mfma_f32_16x16x32_bf16 v[12:15], v[128:131], v[196:199], v[12:15]
	v_mfma_f32_16x16x32_bf16 v[8:11], v[136:139], v[196:199], v[8:11]
	v_mfma_f32_16x16x32_bf16 v[60:63], v[132:135], v[164:167], v[60:63]
	v_mfma_f32_16x16x32_bf16 v[56:59], v[140:143], v[164:167], v[56:59]
	v_mfma_f32_16x16x32_bf16 v[44:47], v[132:135], v[172:175], v[44:47]
	v_mfma_f32_16x16x32_bf16 v[40:43], v[140:143], v[172:175], v[40:43]
	v_mfma_f32_16x16x32_bf16 v[28:31], v[132:135], v[192:195], v[28:31]
	v_mfma_f32_16x16x32_bf16 v[24:27], v[140:143], v[192:195], v[24:27]
	v_mfma_f32_16x16x32_bf16 v[12:15], v[132:135], v[210:213], v[12:15]
	v_mfma_f32_16x16x32_bf16 v[8:11], v[140:143], v[210:213], v[8:11]
	s_setprio 0
	s_setprio 1
	v_mfma_f32_16x16x32_bf16 v[52:55], v[144:147], v[160:163], v[52:55]
	v_mfma_f32_16x16x32_bf16 v[48:51], v[152:155], v[160:163], v[48:51]
	v_mfma_f32_16x16x32_bf16 v[36:39], v[144:147], v[168:171], v[36:39]
	v_mfma_f32_16x16x32_bf16 v[32:35], v[152:155], v[168:171], v[32:35]
	v_mfma_f32_16x16x32_bf16 v[20:23], v[144:147], v[188:191], v[20:23]
	v_mfma_f32_16x16x32_bf16 v[16:19], v[152:155], v[188:191], v[16:19]
	v_mfma_f32_16x16x32_bf16 v[4:7], v[144:147], v[196:199], v[4:7]
	v_mfma_f32_16x16x32_bf16 v[0:3], v[152:155], v[196:199], v[0:3]
	v_mfma_f32_16x16x32_bf16 v[52:55], v[148:151], v[164:167], v[52:55]
	v_mfma_f32_16x16x32_bf16 v[48:51], v[156:159], v[164:167], v[48:51]
	v_mfma_f32_16x16x32_bf16 v[36:39], v[148:151], v[172:175], v[36:39]
	v_mfma_f32_16x16x32_bf16 v[32:35], v[156:159], v[172:175], v[32:35]
	v_mfma_f32_16x16x32_bf16 v[20:23], v[148:151], v[192:195], v[20:23]
	v_mfma_f32_16x16x32_bf16 v[16:19], v[156:159], v[192:195], v[16:19]
	v_mfma_f32_16x16x32_bf16 v[4:7], v[148:151], v[210:213], v[4:7]
	v_mfma_f32_16x16x32_bf16 v[0:3], v[156:159], v[210:213], v[0:3]
	s_setprio 0
	s_barrier
	s_add_i32 s59, s59, 2
	s_add_u32 s30, s30, 0x100
	s_addc_u32 s31, s31, 0
	s_add_u32 s57, s57, 0x100
	s_addc_u32 s58, s58, 0
	s_cmp_gt_u32 s59, 13
	s_cbranch_scc0 .LBB0_695
	s_and_b64 vcc, exec, s[16:17]
	s_cbranch_vccz .LBB0_698
	s_barrier

;     __device__ __forceinline__ const char* aptr(const Unit& u) const { return (u.kind == 1 ? A1 : A0) + (size_t)u.pm * tstep; }
;     __device__ __forceinline__ const char* bptr(const Unit& u) const { return (u.kind == 1 ? B1 : B0) + (size_t)u.pn * tstep; }
; #define PG8_STAGE(bufoff, gbase, voff) do { _Pragma("unroll") for (int _i = 0; _i < 2; ++_i) \
;         __builtin_amdgcn_global_load_lds((const unsigned*)((const char*)(gbase) + (voff)[_i]), (LAS unsigned*)(lds + (bufoff) + ldsw + _i * 8192), 16, 0, 0); } while (0)
; #define PG8_LDA(dst, b, h) do { _Pragma("unroll") for (int m = 0; m < 4; ++m) _Pragma("unroll") for (int k = 0; k < 2; ++k) dst[m][k] = *(const LAS bf16x8*)(lds + PG8_SA(b, h) + aoff + m * 2048 + k * 1024); } while (0)
; #define PG8_LDB(dst, b, h) do { _Pragma("unroll") for (int n = 0; n < 2; ++n) _Pragma("unroll") for (int k = 0; k < 2; ++k) dst[n][k] = *(const LAS bf16x8*)(lds + PG8_SB(b, h) + boff + n * 2048 + k * 1024); } while (0)
; #define PG8_WAIT_V(n) asm volatile("s_waitcnt vmcnt(" #n ")" ::: "memory")
; template <class Epi, bool ALIGN_EPI, bool SP2>
; __device__ __forceinline__ void gemm_phase(LAS unsigned char* lds, const int K, const Sched& S, const Epi& E) {
;     ...
;     for (;;) {
;         const bool has_next = S.next(ui + 1, nxt);
;         const char* nA = has_next ? S.aptr(nxt) : cA; const char* nB = has_next ? S.bptr(nxt) : cB;
;         for (int t = 0; t < nt; t += 2) {
;             const bool last = (t == nt - 2);
;             const char* a1 = cA + (size_t)(t + 1) * kstep;
;             const char* a2 = last ? nA : cA + (size_t)(t + 2) * kstep; const char* b2 = last ? nB : cB + (size_t)(t + 2) * kstep;
;             const char* a3 = a2 + kstep; const char* b3 = b2 + kstep;
;             if constexpr (SP2) {
;             PG8_LDB(B0, 0, 0); PG8_LDB(B1, 0, 1); PG8_SCHED; PG8_LDA(At, 0, 0); PG8_STAGE(PG8_SA(1, 1), a1 + hstep, voffA);
;             PG8_WAIT_V(8); PG8_WAIT_L(0); PG8_BAR; PG8_MMA(0, 0, At, B0); PG8_MMA(0, 1, At, B1); PG8_BAR; PG8_SCHED;
;     ...
; #pragma unroll
;         for (int a = 0; a < 2; ++a)
; #pragma unroll
;             for (int b = 0; b < 2; ++b)
; #pragma unroll
;                 for (int m = 0; m < 4; ++m)
; #pragma unroll
;                     for (int n = 0; n < 2; ++n) acc[a][b][m][n] = (f32x4){0.f, 0.f, 0.f, 0.f};
;         cur = nxt; cA = nA; cB = nB; ++ui;
.LBB0_805:
	s_ashr_i32 s35, s34, 31
	s_lshl_b64 s[38:39], s[34:35], 19
	s_add_u32 s38, s50, s38
	s_addc_u32 s39, s51, s39
	s_and_b64 s[42:43], s[40:41], exec
	s_cselect_b32 s35, s39, s45
	s_cselect_b32 s74, s38, s44
	s_ashr_i32 s37, s36, 31
	s_lshl_b64 s[42:43], s[36:37], 19
	s_add_u32 s42, s53, s42
	s_addc_u32 s43, s54, s43
	s_and_b64 s[48:49], s[40:41], exec
	s_cselect_b32 s37, s43, s47
	s_cselect_b32 s75, s42, s46
	s_add_u32 s44, s44, 0x40080
	s_addc_u32 s45, s45, 0
	s_add_u32 s76, s46, 0x100
	v_mov_b64_e32 v[0:1], 0
	v_mov_b64_e32 v[2:3], 0
	v_mov_b64_e32 v[4:5], 0
	v_mov_b64_e32 v[6:7], 0
	v_mov_b64_e32 v[8:9], 0
	v_mov_b64_e32 v[10:11], 0
	v_mov_b64_e32 v[12:13], 0
	v_mov_b64_e32 v[14:15], 0
	v_mov_b64_e32 v[16:17], 0
	v_mov_b64_e32 v[18:19], 0
	v_mov_b64_e32 v[20:21], 0
	v_mov_b64_e32 v[22:23], 0
	v_mov_b64_e32 v[24:25], 0
	v_mov_b64_e32 v[26:27], 0
	v_mov_b64_e32 v[28:29], 0
	v_mov_b64_e32 v[30:31], 0
	v_mov_b64_e32 v[32:33], 0
	v_mov_b64_e32 v[34:35], 0
	v_mov_b64_e32 v[36:37], 0
	v_mov_b64_e32 v[38:39], 0
	v_mov_b64_e32 v[40:41], 0
	v_mov_b64_e32 v[42:43], 0
	v_mov_b64_e32 v[44:45], 0
	v_mov_b64_e32 v[46:47], 0
	v_mov_b64_e32 v[48:49], 0
	v_mov_b64_e32 v[50:51], 0
	v_mov_b64_e32 v[52:53], 0
	v_mov_b64_e32 v[54:55], 0
	v_mov_b64_e32 v[56:57], 0
	v_mov_b64_e32 v[58:59], 0
	v_mov_b64_e32 v[60:61], 0
	v_mov_b64_e32 v[62:63], 0
	v_mov_b64_e32 v[64:65], 0
	v_mov_b64_e32 v[66:67], 0
	v_mov_b64_e32 v[68:69], 0
	v_mov_b64_e32 v[70:71], 0
	v_mov_b64_e32 v[72:73], 0
	v_mov_b64_e32 v[74:75], 0
	v_mov_b64_e32 v[76:77], 0
	v_mov_b64_e32 v[78:79], 0
	v_mov_b64_e32 v[80:81], 0
	v_mov_b64_e32 v[82:83], 0
	v_mov_b64_e32 v[84:85], 0
	v_mov_b64_e32 v[86:87], 0
	v_mov_b64_e32 v[88:89], 0
	v_mov_b64_e32 v[90:91], 0
	v_mov_b64_e32 v[92:93], 0
	v_mov_b64_e32 v[94:95], 0
	v_mov_b64_e32 v[96:97], 0
	v_mov_b64_e32 v[98:99], 0
	v_mov_b64_e32 v[100:101], 0
	v_mov_b64_e32 v[102:103], 0
	v_mov_b64_e32 v[104:105], 0
	v_mov_b64_e32 v[106:107], 0
	v_mov_b64_e32 v[108:109], 0
	v_mov_b64_e32 v[110:111], 0
	v_mov_b64_e32 v[112:113], 0
	v_mov_b64_e32 v[114:115], 0
	v_mov_b64_e32 v[116:117], 0
	v_mov_b64_e32 v[118:119], 0
	v_mov_b64_e32 v[120:121], 0
	v_mov_b64_e32 v[122:123], 0
	v_mov_b64_e32 v[124:125], 0
	v_mov_b64_e32 v[126:127], 0
	s_addc_u32 s77, s47, 0
	s_mov_b32 s78, -2
.LBB0_806:
	ds_read_b128 v[148:151], v143
	ds_read_b128 v[152:155], v143 offset:1024
	ds_read_b128 v[156:159], v143 offset:2048
	ds_read_b128 v[160:163], v143 offset:3072
	ds_read_b128 v[164:167], v144
	ds_read_b128 v[168:171], v144 offset:1024
	ds_read_b128 v[172:175], v144 offset:2048
	ds_read_b128 v[176:179], v144 offset:3072
	s_add_u32 s46, s44, 0xfffc0080
	s_addc_u32 s47, s45, -1
	s_cmp_eq_u32 s78, 12
	s_cselect_b32 s49, s35, s47
	s_cselect_b32 s48, s74, s46
	s_cselect_b32 s47, s37, s77
	s_cselect_b32 s46, s75, s76
	v_lshl_add_u64 v[214:215], s[44:45], 0, v[136:137]
	s_add_i32 m0, s56, 0xc000
	ds_read_b128 v[180:183], v145
	ds_read_b128 v[184:187], v145 offset:1024
	ds_read_b128 v[188:191], v145 offset:2048
	ds_read_b128 v[192:195], v145 offset:3072
	ds_read_b128 v[196:199], v145 offset:4096
	ds_read_b128 v[200:203], v145 offset:5120
	ds_read_b128 v[204:207], v145 offset:6144
	ds_read_b128 v[210:213], v145 offset:7168
	global_load_lds_dwordx4 v[214:215], off
	v_lshl_add_u64 v[214:215], s[44:45], 0, v[138:139]
	s_add_i32 m0, s56, 0xe000
	s_nop 0
	global_load_lds_dwordx4 v[214:215], off
	s_waitcnt vmcnt(8)
	s_waitcnt lgkmcnt(0)
	s_setprio 1
	s_waitcnt lgkmcnt(0)
	v_mfma_f32_16x16x32_bf16 v[124:127], v[148:151], v[180:183], v[124:127]
	v_mfma_f32_16x16x32_bf16 v[120:123], v[156:159], v[180:183], v[120:123]
	v_mfma_f32_16x16x32_bf16 v[112:115], v[148:151], v[188:191], v[112:115]
	v_mfma_f32_16x16x32_bf16 v[104:107], v[156:159], v[188:191], v[104:107]
	s_barrier
	v_mfma_f32_16x16x32_bf16 v[96:99], v[148:151], v[196:199], v[96:99]
	v_mfma_f32_16x16x32_bf16 v[88:91], v[156:159], v[196:199], v[88:91]
	v_mfma_f32_16x16x32_bf16 v[80:83], v[148:151], v[204:207], v[80:83]
	v_mfma_f32_16x16x32_bf16 v[72:75], v[156:159], v[204:207], v[72:75]
	v_mfma_f32_16x16x32_bf16 v[124:127], v[152:155], v[184:187], v[124:127]
	v_mfma_f32_16x16x32_bf16 v[120:123], v[160:163], v[184:187], v[120:123]
	v_mfma_f32_16x16x32_bf16 v[112:115], v[152:155], v[192:195], v[112:115]
	v_mfma_f32_16x16x32_bf16 v[104:107], v[160:163], v[192:195], v[104:107]
	v_mfma_f32_16x16x32_bf16 v[96:99], v[152:155], v[200:203], v[96:99]
	v_mfma_f32_16x16x32_bf16 v[88:91], v[160:163], v[200:203], v[88:91]
	v_mfma_f32_16x16x32_bf16 v[80:83], v[152:155], v[210:213], v[80:83]
	v_mfma_f32_16x16x32_bf16 v[72:75], v[160:163], v[210:213], v[72:75]
	s_setprio 0
	s_setprio 1
	v_mfma_f32_16x16x32_bf16 v[116:119], v[164:167], v[180:183], v[116:119]
	v_mfma_f32_16x16x32_bf16 v[108:111], v[172:175], v[180:183], v[108:111]
	v_mfma_f32_16x16x32_bf16 v[100:103], v[164:167], v[188:191], v[100:103]
	v_mfma_f32_16x16x32_bf16 v[92:95], v[172:175], v[188:191], v[92:95]
	v_mfma_f32_16x16x32_bf16 v[84:87], v[164:167], v[196:199], v[84:87]
	v_mfma_f32_16x16x32_bf16 v[76:79], v[172:175], v[196:199], v[76:79]
	v_mfma_f32_16x16x32_bf16 v[68:71], v[164:167], v[204:207], v[68:71]
	v_mfma_f32_16x16x32_bf16 v[64:67], v[172:175], v[204:207], v[64:67]
	v_mfma_f32_16x16x32_bf16 v[116:119], v[168:171], v[184:187], v[116:119]
	v_mfma_f32_16x16x32_bf16 v[108:111], v[176:179], v[184:187], v[108:111]
	v_mfma_f32_16x16x32_bf16 v[100:103], v[168:171], v[192:195], v[100:103]
	v_mfma_f32_16x16x32_bf16 v[92:95], v[176:179], v[192:195], v[92:95]
	v_mfma_f32_16x16x32_bf16 v[84:87], v[168:171], v[200:203], v[84:87]
	v_mfma_f32_16x16x32_bf16 v[76:79], v[176:179], v[200:203], v[76:79]
	v_mfma_f32_16x16x32_bf16 v[68:71], v[168:171], v[210:213], v[68:71]
	v_mfma_f32_16x16x32_bf16 v[64:67], v[176:179], v[210:213], v[64:67]
	s_setprio 0
	s_barrier
; #define PG8_STAGE(bufoff, gbase, voff) do { _Pragma("unroll") for (int _i = 0; _i < 2; ++_i) \
;         __builtin_amdgcn_global_load_lds((const unsigned*)((const char*)(gbase) + (voff)[_i]), (LAS unsigned*)(lds + (bufoff) + ldsw + _i * 8192), 16, 0, 0); } while (0)
; #define PG8_LDA(dst, b, h) do { _Pragma("unroll") for (int m = 0; m < 4; ++m) _Pragma("unroll") for (int k = 0; k < 2; ++k) dst[m][k] = *(const LAS bf16x8*)(lds + PG8_SA(b, h) + aoff + m * 2048 + k * 1024); } while (0)
; #define PG8_LDB(dst, b, h) do { _Pragma("unroll") for (int n = 0; n < 2; ++n) _Pragma("unroll") for (int k = 0; k < 2; ++k) dst[n][k] = *(const LAS bf16x8*)(lds + PG8_SB(b, h) + boff + n * 2048 + k * 1024); } while (0)
; #define PG8_MMA(ai, bj, At, Bt) do { __builtin_amdgcn_s_setprio(1); _Pragma("unroll") for (int m = 0; m < 4; ++m) _Pragma("unroll") for (int n = 0; n < 2; ++n) _Pragma("unroll") for (int k = 0; k < 2; ++k) \
;         acc[ai][bj][m][n] = __builtin_amdgcn_mfma_f32_16x16x32_bf16(Bt[n][k], At[m][k], acc[ai][bj][m][n], 0, 0, 0); __builtin_amdgcn_s_setprio(0); } while (0)
; #define PG8_WAIT_V(n) asm volatile("s_waitcnt vmcnt(" #n ")" ::: "memory")
; #define PG8_WAIT_L(n) asm volatile("s_waitcnt lgkmcnt(" #n ")" ::: "memory")
; #define PG8_BAR __builtin_amdgcn_s_barrier()
; template <class Epi, bool ALIGN_EPI, bool SP2>
; __device__ __forceinline__ void gemm_phase(LAS unsigned char* lds, const int K, const Sched& S, const Epi& E) {
;     ...
;             PG8_WAIT_V(8); PG8_WAIT_L(0); PG8_BAR; PG8_MMA(0, 0, At, B0); PG8_MMA(0, 1, At, B1); PG8_BAR; PG8_SCHED;
;             PG8_LDA(At, 0, 1); PG8_STAGE(PG8_SB(0, 0), b2, voffB); PG8_STAGE(PG8_SB(0, 1), b2 + hstep, voffB); PG8_STAGE(PG8_SA(0, 0), a2, voffA);
;             PG8_WAIT_V(8); PG8_WAIT_L(0); PG8_BAR; PG8_MMA(1, 0, At, B0); PG8_MMA(1, 1, At, B1); PG8_BAR; PG8_SCHED;
;             PG8_LDB(B0, 1, 0); PG8_LDB(B1, 1, 1); PG8_SCHED; PG8_LDA(At, 1, 0); PG8_STAGE(PG8_SA(0, 1), a2 + hstep, voffA);
;             PG8_WAIT_V(8); PG8_WAIT_L(0); PG8_BAR; PG8_MMA(0, 0, At, B0); PG8_MMA(0, 1, At, B1); PG8_BAR; PG8_SCHED;
;             PG8_LDA(At, 1, 1); PG8_STAGE(PG8_SB(1, 0), b3, voffB); PG8_STAGE(PG8_SB(1, 1), b3 + hstep, voffB); PG8_STAGE(PG8_SA(1, 0), a3, voffA);
;             PG8_WAIT_V(8); PG8_WAIT_L(0); PG8_BAR; PG8_MMA(1, 0, At, B0); PG8_MMA(1, 1, At, B1); PG8_BAR; PG8_SCHED;
	s_add_i32 s79, s66, s55
	v_lshl_add_u64 v[214:215], s[46:47], 0, v[132:133]
	s_mov_b32 m0, s79
	ds_read_b128 v[180:183], v145 offset:16384
	ds_read_b128 v[184:187], v145 offset:17408
	ds_read_b128 v[188:191], v145 offset:18432
	ds_read_b128 v[192:195], v145 offset:19456
	ds_read_b128 v[196:199], v145 offset:20480
	ds_read_b128 v[200:203], v145 offset:21504
	ds_read_b128 v[204:207], v145 offset:22528
	ds_read_b128 v[210:213], v145 offset:23552
	global_load_lds_dwordx4 v[214:215], off
	s_add_i32 m0, s79, 0x2000
	s_add_u32 s80, s46, 0x40000
	v_lshl_add_u64 v[216:217], s[46:47], 0, v[128:129]
	s_addc_u32 s81, s47, 0
	s_add_i32 s79, s67, s55
	global_load_lds_dwordx4 v[216:217], off
	v_lshl_add_u64 v[218:219], s[80:81], 0, v[132:133]
	s_mov_b32 m0, s79
	v_lshl_add_u64 v[220:221], s[48:49], 0, v[130:131]
	global_load_lds_dwordx4 v[218:219], off
	v_lshl_add_u64 v[218:219], s[80:81], 0, v[128:129]
	s_add_i32 m0, s79, 0x2000
	s_nop 0
	global_load_lds_dwordx4 v[218:219], off
	v_lshl_add_u64 v[218:219], s[48:49], 0, v[134:135]
	s_mov_b32 m0, s56
	s_nop 0
	global_load_lds_dwordx4 v[218:219], off
	s_mov_b32 m0, s57
	s_nop 0
	global_load_lds_dwordx4 v[220:221], off
	s_waitcnt vmcnt(8)
	s_waitcnt lgkmcnt(0)
	s_setprio 1
	s_waitcnt lgkmcnt(0)
	v_mfma_f32_16x16x32_bf16 v[60:63], v[148:151], v[180:183], v[60:63]
	v_mfma_f32_16x16x32_bf16 v[56:59], v[156:159], v[180:183], v[56:59]
	v_mfma_f32_16x16x32_bf16 v[48:51], v[148:151], v[188:191], v[48:51]
	v_mfma_f32_16x16x32_bf16 v[40:43], v[156:159], v[188:191], v[40:43]
	s_barrier
	v_mfma_f32_16x16x32_bf16 v[32:35], v[148:151], v[196:199], v[32:35]
	v_mfma_f32_16x16x32_bf16 v[24:27], v[156:159], v[196:199], v[24:27]
	v_mfma_f32_16x16x32_bf16 v[16:19], v[148:151], v[204:207], v[16:19]
	v_mfma_f32_16x16x32_bf16 v[8:11], v[156:159], v[204:207], v[8:11]
	v_mfma_f32_16x16x32_bf16 v[60:63], v[152:155], v[184:187], v[60:63]
	v_mfma_f32_16x16x32_bf16 v[56:59], v[160:163], v[184:187], v[56:59]
	v_mfma_f32_16x16x32_bf16 v[48:51], v[152:155], v[192:195], v[48:51]
	v_mfma_f32_16x16x32_bf16 v[40:43], v[160:163], v[192:195], v[40:43]
	v_mfma_f32_16x16x32_bf16 v[32:35], v[152:155], v[200:203], v[32:35]
	v_mfma_f32_16x16x32_bf16 v[24:27], v[160:163], v[200:203], v[24:27]
	v_mfma_f32_16x16x32_bf16 v[16:19], v[152:155], v[210:213], v[16:19]
	v_mfma_f32_16x16x32_bf16 v[8:11], v[160:163], v[210:213], v[8:11]
	s_setprio 0
	s_setprio 1
	v_mfma_f32_16x16x32_bf16 v[52:55], v[164:167], v[180:183], v[52:55]
	v_mfma_f32_16x16x32_bf16 v[44:47], v[172:175], v[180:183], v[44:47]
	v_mfma_f32_16x16x32_bf16 v[36:39], v[164:167], v[188:191], v[36:39]
	v_mfma_f32_16x16x32_bf16 v[28:31], v[172:175], v[188:191], v[28:31]
	v_mfma_f32_16x16x32_bf16 v[20:23], v[164:167], v[196:199], v[20:23]
	v_mfma_f32_16x16x32_bf16 v[12:15], v[172:175], v[196:199], v[12:15]
	v_mfma_f32_16x16x32_bf16 v[4:7], v[164:167], v[204:207], v[4:7]
	v_mfma_f32_16x16x32_bf16 v[0:3], v[172:175], v[204:207], v[0:3]
	v_mfma_f32_16x16x32_bf16 v[52:55], v[168:171], v[184:187], v[52:55]
	v_mfma_f32_16x16x32_bf16 v[44:47], v[176:179], v[184:187], v[44:47]
	v_mfma_f32_16x16x32_bf16 v[36:39], v[168:171], v[192:195], v[36:39]
	v_mfma_f32_16x16x32_bf16 v[28:31], v[176:179], v[192:195], v[28:31]
	v_mfma_f32_16x16x32_bf16 v[20:23], v[168:171], v[200:203], v[20:23]
	v_mfma_f32_16x16x32_bf16 v[12:15], v[176:179], v[200:203], v[12:15]
	v_mfma_f32_16x16x32_bf16 v[4:7], v[168:171], v[210:213], v[4:7]
	v_mfma_f32_16x16x32_bf16 v[0:3], v[176:179], v[210:213], v[0:3]
	s_setprio 0
	s_barrier
	s_add_i32 s79, 0, 0x18000
	v_add_u32_e32 v147, s79, v142
	s_add_i32 s80, 0, 0x1c000
	ds_read_b128 v[148:151], v147
	ds_read_b128 v[152:155], v147 offset:1024
	ds_read_b128 v[156:159], v147 offset:2048
	ds_read_b128 v[160:163], v147 offset:3072
	v_add_u32_e32 v147, s80, v142
	ds_read_b128 v[164:167], v147
	ds_read_b128 v[168:171], v147 offset:1024
	ds_read_b128 v[172:175], v147 offset:2048
	ds_read_b128 v[176:179], v147 offset:3072
	s_add_u32 s48, s48, 0x40000
	s_addc_u32 s49, s49, 0
	s_mov_b32 m0, s58
	v_lshl_add_u64 v[222:223], s[48:49], 0, v[134:135]
	ds_read_b128 v[180:183], v145 offset:32768
	ds_read_b128 v[184:187], v145 offset:33792
	ds_read_b128 v[188:191], v145 offset:34816
	ds_read_b128 v[192:195], v145 offset:35840
	ds_read_b128 v[196:199], v145 offset:36864
	ds_read_b128 v[200:203], v145 offset:37888
	ds_read_b128 v[204:207], v145 offset:38912
	ds_read_b128 v[210:213], v145 offset:39936
	global_load_lds_dwordx4 v[222:223], off
	v_lshl_add_u64 v[222:223], s[48:49], 0, v[130:131]
	s_mov_b32 m0, s59
	s_nop 0
	global_load_lds_dwordx4 v[222:223], off
	s_waitcnt vmcnt(8)
	s_waitcnt lgkmcnt(0)
	s_setprio 1
	s_waitcnt lgkmcnt(0)
	v_mfma_f32_16x16x32_bf16 v[124:127], v[148:151], v[180:183], v[124:127]
	v_mfma_f32_16x16x32_bf16 v[120:123], v[156:159], v[180:183], v[120:123]
	v_mfma_f32_16x16x32_bf16 v[112:115], v[148:151], v[188:191], v[112:115]
	v_mfma_f32_16x16x32_bf16 v[104:107], v[156:159], v[188:191], v[104:107]
	s_barrier
; #define PG8_STAGE(bufoff, gbase, voff) do { _Pragma("unroll") for (int _i = 0; _i < 2; ++_i) \
;         __builtin_amdgcn_global_load_lds((const unsigned*)((const char*)(gbase) + (voff)[_i]), (LAS unsigned*)(lds + (bufoff) + ldsw + _i * 8192), 16, 0, 0); } while (0)
; #define PG8_LDA(dst, b, h) do { _Pragma("unroll") for (int m = 0; m < 4; ++m) _Pragma("unroll") for (int k = 0; k < 2; ++k) dst[m][k] = *(const LAS bf16x8*)(lds + PG8_SA(b, h) + aoff + m * 2048 + k * 1024); } while (0)
; template <class Epi, bool ALIGN_EPI, bool SP2>
; __device__ __forceinline__ void gemm_phase(LAS unsigned char* lds, const int K, const Sched& S, const Epi& E) {
;     ...
;             PG8_WAIT_V(8); PG8_WAIT_L(0); PG8_BAR; PG8_MMA(0, 0, At, B0); PG8_MMA(0, 1, At, B1); PG8_BAR; PG8_SCHED;
;             PG8_LDA(At, 1, 1); PG8_STAGE(PG8_SB(1, 0), b3, voffB); PG8_STAGE(PG8_SB(1, 1), b3 + hstep, voffB); PG8_STAGE(PG8_SA(1, 0), a3, voffA);
;             PG8_WAIT_V(8); PG8_WAIT_L(0); PG8_BAR; PG8_MMA(1, 0, At, B0); PG8_MMA(1, 1, At, B1); PG8_BAR; PG8_SCHED;
;             } else {
;             PG8_LDB(B0, 0, 0); PG8_SCHED; PG8_LDA(At, 0, 0); PG8_STAGE(PG8_SA(1, 1), a1 + hstep, voffA);
;             PG8_WAIT_L(8); PG8_BAR; PG8_WAIT_L(0); PG8_MMA(0, 0, At, B0); PG8_BAR; PG8_SCHED;
;             PG8_LDB(B1, 0, 1); PG8_STAGE(PG8_SB(0, 0), b2, voffB);
;             PG8_BAR; PG8_WAIT_L(0); PG8_MMA(0, 1, At, B1); PG8_BAR;
;             PG8_LDA(At, 0, 1); PG8_STAGE(PG8_SA(0, 0), a2, voffA);
;             PG8_BAR; PG8_WAIT_L(0); PG8_MMA(1, 0, At, B0); PG8_BAR; PG8_SCHED;
;             PG8_STAGE(PG8_SB(0, 1), b2 + hstep, voffB);
;             PG8_WAIT_V(6); PG8_BAR; PG8_MMA(1, 1, At, B1); PG8_BAR;
;             PG8_LDB(B0, 1, 0); PG8_SCHED; PG8_LDA(At, 1, 0); PG8_STAGE(PG8_SA(0, 1), a2 + hstep, voffA);
;             PG8_WAIT_L(8); PG8_BAR; PG8_WAIT_L(0); PG8_MMA(0, 0, At, B0); PG8_BAR; PG8_SCHED;
;             PG8_LDB(B1, 1, 1); PG8_STAGE(PG8_SB(1, 0), b3, voffB);
;             PG8_BAR; PG8_WAIT_L(0); PG8_MMA(0, 1, At, B1); PG8_BAR;
;             PG8_LDA(At, 1, 1); PG8_STAGE(PG8_SA(1, 0), a3, voffA);
;             PG8_BAR; PG8_WAIT_L(0); PG8_MMA(1, 0, At, B0); PG8_BAR; PG8_SCHED;
;             PG8_STAGE(PG8_SB(1, 1), b3 + hstep, voffB);
;             PG8_WAIT_V(6); PG8_BAR; PG8_MMA(1, 1, At, B1); PG8_BAR;
;             }
;         }
;         if constexpr (ALIGN_EPI) { if (wr == 0) PG8_BAR; }
	v_mfma_f32_16x16x32_bf16 v[96:99], v[148:151], v[196:199], v[96:99]
	v_mfma_f32_16x16x32_bf16 v[88:91], v[156:159], v[196:199], v[88:91]
	v_mfma_f32_16x16x32_bf16 v[80:83], v[148:151], v[204:207], v[80:83]
	v_mfma_f32_16x16x32_bf16 v[72:75], v[156:159], v[204:207], v[72:75]
	v_mfma_f32_16x16x32_bf16 v[124:127], v[152:155], v[184:187], v[124:127]
	v_mfma_f32_16x16x32_bf16 v[120:123], v[160:163], v[184:187], v[120:123]
	v_mfma_f32_16x16x32_bf16 v[112:115], v[152:155], v[192:195], v[112:115]
	v_mfma_f32_16x16x32_bf16 v[104:107], v[160:163], v[192:195], v[104:107]
	v_mfma_f32_16x16x32_bf16 v[96:99], v[152:155], v[200:203], v[96:99]
	v_mfma_f32_16x16x32_bf16 v[88:91], v[160:163], v[200:203], v[88:91]
	v_mfma_f32_16x16x32_bf16 v[80:83], v[152:155], v[210:213], v[80:83]
	v_mfma_f32_16x16x32_bf16 v[72:75], v[160:163], v[210:213], v[72:75]
	s_setprio 0
	s_setprio 1
	v_mfma_f32_16x16x32_bf16 v[116:119], v[164:167], v[180:183], v[116:119]
	v_mfma_f32_16x16x32_bf16 v[108:111], v[172:175], v[180:183], v[108:111]
	v_mfma_f32_16x16x32_bf16 v[100:103], v[164:167], v[188:191], v[100:103]
	v_mfma_f32_16x16x32_bf16 v[92:95], v[172:175], v[188:191], v[92:95]
	v_mfma_f32_16x16x32_bf16 v[84:87], v[164:167], v[196:199], v[84:87]
	v_mfma_f32_16x16x32_bf16 v[76:79], v[172:175], v[196:199], v[76:79]
	v_mfma_f32_16x16x32_bf16 v[68:71], v[164:167], v[204:207], v[68:71]
	v_mfma_f32_16x16x32_bf16 v[64:67], v[172:175], v[204:207], v[64:67]
	v_mfma_f32_16x16x32_bf16 v[116:119], v[168:171], v[184:187], v[116:119]
	v_mfma_f32_16x16x32_bf16 v[108:111], v[176:179], v[184:187], v[108:111]
	v_mfma_f32_16x16x32_bf16 v[100:103], v[168:171], v[192:195], v[100:103]
	v_mfma_f32_16x16x32_bf16 v[92:95], v[176:179], v[192:195], v[92:95]
	v_mfma_f32_16x16x32_bf16 v[84:87], v[168:171], v[200:203], v[84:87]
	v_mfma_f32_16x16x32_bf16 v[76:79], v[176:179], v[200:203], v[76:79]
	v_mfma_f32_16x16x32_bf16 v[68:71], v[168:171], v[210:213], v[68:71]
	v_mfma_f32_16x16x32_bf16 v[64:67], v[176:179], v[210:213], v[64:67]
	s_setprio 0
	s_barrier
	s_add_i32 s48, s79, s55
	v_lshl_add_u64 v[214:215], v[214:215], 0, s[14:15]
	s_mov_b32 m0, s48
	ds_read_b128 v[180:183], v145 offset:49152
	ds_read_b128 v[184:187], v145 offset:50176
	ds_read_b128 v[188:191], v145 offset:51200
	ds_read_b128 v[192:195], v145 offset:52224
	ds_read_b128 v[196:199], v145 offset:53248
	ds_read_b128 v[200:203], v145 offset:54272
	ds_read_b128 v[204:207], v145 offset:55296
	ds_read_b128 v[210:213], v145 offset:56320
	global_load_lds_dwordx4 v[214:215], off
	s_add_i32 m0, s48, 0x2000
	s_add_u32 s46, s46, 0x40080
	v_lshl_add_u64 v[214:215], v[216:217], 0, s[14:15]
	s_addc_u32 s47, s47, 0
	s_add_i32 s48, s80, s55
	global_load_lds_dwordx4 v[214:215], off
	v_lshl_add_u64 v[214:215], s[46:47], 0, v[132:133]
	s_mov_b32 m0, s48
	s_nop 0
	global_load_lds_dwordx4 v[214:215], off
	v_lshl_add_u64 v[214:215], s[46:47], 0, v[128:129]
	s_add_i32 m0, s48, 0x2000
	s_nop 0
	global_load_lds_dwordx4 v[214:215], off
	v_lshl_add_u64 v[214:215], v[218:219], 0, s[14:15]
	s_mov_b32 m0, s63
	s_nop 0
	global_load_lds_dwordx4 v[214:215], off
	v_lshl_add_u64 v[214:215], v[220:221], 0, s[14:15]
	s_mov_b32 m0, s64
	s_nop 0
	global_load_lds_dwordx4 v[214:215], off
	s_waitcnt vmcnt(8)
	s_waitcnt lgkmcnt(0)
	s_setprio 1
	s_waitcnt lgkmcnt(0)
	v_mfma_f32_16x16x32_bf16 v[60:63], v[148:151], v[180:183], v[60:63]
	v_mfma_f32_16x16x32_bf16 v[56:59], v[156:159], v[180:183], v[56:59]
	v_mfma_f32_16x16x32_bf16 v[48:51], v[148:151], v[188:191], v[48:51]
	v_mfma_f32_16x16x32_bf16 v[40:43], v[156:159], v[188:191], v[40:43]
	s_barrier
	v_mfma_f32_16x16x32_bf16 v[32:35], v[148:151], v[196:199], v[32:35]
	v_mfma_f32_16x16x32_bf16 v[24:27], v[156:159], v[196:199], v[24:27]
	v_mfma_f32_16x16x32_bf16 v[16:19], v[148:151], v[204:207], v[16:19]
	v_mfma_f32_16x16x32_bf16 v[8:11], v[156:159], v[204:207], v[8:11]
	v_mfma_f32_16x16x32_bf16 v[60:63], v[152:155], v[184:187], v[60:63]
	v_mfma_f32_16x16x32_bf16 v[56:59], v[160:163], v[184:187], v[56:59]
	v_mfma_f32_16x16x32_bf16 v[48:51], v[152:155], v[192:195], v[48:51]
	v_mfma_f32_16x16x32_bf16 v[40:43], v[160:163], v[192:195], v[40:43]
	v_mfma_f32_16x16x32_bf16 v[32:35], v[152:155], v[200:203], v[32:35]
	v_mfma_f32_16x16x32_bf16 v[24:27], v[160:163], v[200:203], v[24:27]
	v_mfma_f32_16x16x32_bf16 v[16:19], v[152:155], v[210:213], v[16:19]
	v_mfma_f32_16x16x32_bf16 v[8:11], v[160:163], v[210:213], v[8:11]
	s_setprio 0
	s_setprio 1
	v_mfma_f32_16x16x32_bf16 v[52:55], v[164:167], v[180:183], v[52:55]
	v_mfma_f32_16x16x32_bf16 v[44:47], v[172:175], v[180:183], v[44:47]
	v_mfma_f32_16x16x32_bf16 v[36:39], v[164:167], v[188:191], v[36:39]
	v_mfma_f32_16x16x32_bf16 v[28:31], v[172:175], v[188:191], v[28:31]
	v_mfma_f32_16x16x32_bf16 v[20:23], v[164:167], v[196:199], v[20:23]
	v_mfma_f32_16x16x32_bf16 v[12:15], v[172:175], v[196:199], v[12:15]
	v_mfma_f32_16x16x32_bf16 v[4:7], v[164:167], v[204:207], v[4:7]
	v_mfma_f32_16x16x32_bf16 v[0:3], v[172:175], v[204:207], v[0:3]
	v_mfma_f32_16x16x32_bf16 v[52:55], v[168:171], v[184:187], v[52:55]
	v_mfma_f32_16x16x32_bf16 v[44:47], v[176:179], v[184:187], v[44:47]
	v_mfma_f32_16x16x32_bf16 v[36:39], v[168:171], v[192:195], v[36:39]
	v_mfma_f32_16x16x32_bf16 v[28:31], v[176:179], v[192:195], v[28:31]
	v_mfma_f32_16x16x32_bf16 v[20:23], v[168:171], v[200:203], v[20:23]
	v_mfma_f32_16x16x32_bf16 v[12:15], v[176:179], v[200:203], v[12:15]
	v_mfma_f32_16x16x32_bf16 v[4:7], v[168:171], v[210:213], v[4:7]
	v_mfma_f32_16x16x32_bf16 v[0:3], v[176:179], v[210:213], v[0:3]
	s_setprio 0
	s_barrier
	s_add_i32 s78, s78, 2
	s_add_u32 s44, s44, 0x100
	s_addc_u32 s45, s45, 0
	s_add_u32 s76, s76, 0x100
	s_addc_u32 s77, s77, 0
	s_cmp_gt_u32 s78, 13
	s_cbranch_scc0 .LBB0_806
	s_and_b64 vcc, exec, s[16:17]
	s_cbranch_vccz .LBB0_809
	s_barrier

;     __device__ __forceinline__ const char* aptr(const Unit& u) const { return (u.kind == 1 ? A1 : A0) + (size_t)u.pm * tstep; }
;     __device__ __forceinline__ const char* bptr(const Unit& u) const { return (u.kind == 1 ? B1 : B0) + (size_t)u.pn * tstep; }
; #define PG8_STAGE(bufoff, gbase, voff) do { _Pragma("unroll") for (int _i = 0; _i < 2; ++_i) \
;         __builtin_amdgcn_global_load_lds((const unsigned*)((const char*)(gbase) + (voff)[_i]), (LAS unsigned*)(lds + (bufoff) + ldsw + _i * 8192), 16, 0, 0); } while (0)
; #define PG8_LDA(dst, b, h) do { _Pragma("unroll") for (int m = 0; m < 4; ++m) _Pragma("unroll") for (int k = 0; k < 2; ++k) dst[m][k] = *(const LAS bf16x8*)(lds + PG8_SA(b, h) + aoff + m * 2048 + k * 1024); } while (0)
; #define PG8_LDB(dst, b, h) do { _Pragma("unroll") for (int n = 0; n < 2; ++n) _Pragma("unroll") for (int k = 0; k < 2; ++k) dst[n][k] = *(const LAS bf16x8*)(lds + PG8_SB(b, h) + boff + n * 2048 + k * 1024); } while (0)
; #define PG8_WAIT_V(n) asm volatile("s_waitcnt vmcnt(" #n ")" ::: "memory")
; template <class Epi, bool ALIGN_EPI, bool SP2>
; __device__ __forceinline__ void gemm_phase(LAS unsigned char* lds, const int K, const Sched& S, const Epi& E) {
;     ...
;     for (;;) {
;         const bool has_next = S.next(ui + 1, nxt);
;         const char* nA = has_next ? S.aptr(nxt) : cA; const char* nB = has_next ? S.bptr(nxt) : cB;
;         for (int t = 0; t < nt; t += 2) {
;             const bool last = (t == nt - 2);
;             const char* a1 = cA + (size_t)(t + 1) * kstep;
;             const char* a2 = last ? nA : cA + (size_t)(t + 2) * kstep; const char* b2 = last ? nB : cB + (size_t)(t + 2) * kstep;
;             const char* a3 = a2 + kstep; const char* b3 = b2 + kstep;
;             if constexpr (SP2) {
;             PG8_LDB(B0, 0, 0); PG8_LDB(B1, 0, 1); PG8_SCHED; PG8_LDA(At, 0, 0); PG8_STAGE(PG8_SA(1, 1), a1 + hstep, voffA);
;             PG8_WAIT_V(8); PG8_WAIT_L(0); PG8_BAR; PG8_MMA(0, 0, At, B0); PG8_MMA(0, 1, At, B1); PG8_BAR; PG8_SCHED;
;     ...
; #pragma unroll
;         for (int a = 0; a < 2; ++a)
; #pragma unroll
;             for (int b = 0; b < 2; ++b)
; #pragma unroll
;                 for (int m = 0; m < 4; ++m)
; #pragma unroll
;                     for (int n = 0; n < 2; ++n) acc[a][b][m][n] = (f32x4){0.f, 0.f, 0.f, 0.f};
;         cur = nxt; cA = nA; cB = nB; ++ui;
.LBB0_980:
	s_ashr_i32 s17, s16, 31
	s_lshl_b64 s[20:21], s[16:17], 18
	s_add_u32 s20, s36, s20
	s_addc_u32 s21, s37, s21
	s_and_b64 s[24:25], s[22:23], exec
	s_cselect_b32 s3, s21, s29
	s_cselect_b32 s17, s20, s28
	s_ashr_i32 s19, s18, 31
	s_lshl_b64 s[24:25], s[18:19], 18
	s_add_u32 s24, s38, s24
	s_addc_u32 s25, s39, s25
	s_and_b64 s[34:35], s[22:23], exec
	s_cselect_b32 s19, s25, s31
	s_cselect_b32 s54, s24, s30
	s_add_u32 s28, s28, 0x20080
	s_addc_u32 s29, s29, 0
	s_add_u32 s55, s30, 0x100
	v_mov_b64_e32 v[0:1], 0
	v_mov_b64_e32 v[2:3], 0
	v_mov_b64_e32 v[4:5], 0
	v_mov_b64_e32 v[6:7], 0
	v_mov_b64_e32 v[8:9], 0
	v_mov_b64_e32 v[10:11], 0
	v_mov_b64_e32 v[12:13], 0
	v_mov_b64_e32 v[14:15], 0
	v_mov_b64_e32 v[16:17], 0
	v_mov_b64_e32 v[18:19], 0
	v_mov_b64_e32 v[20:21], 0
	v_mov_b64_e32 v[22:23], 0
	v_mov_b64_e32 v[24:25], 0
	v_mov_b64_e32 v[26:27], 0
	v_mov_b64_e32 v[28:29], 0
	v_mov_b64_e32 v[30:31], 0
	v_mov_b64_e32 v[32:33], 0
	v_mov_b64_e32 v[34:35], 0
	v_mov_b64_e32 v[36:37], 0
	v_mov_b64_e32 v[38:39], 0
	v_mov_b64_e32 v[40:41], 0
	v_mov_b64_e32 v[42:43], 0
	v_mov_b64_e32 v[44:45], 0
	v_mov_b64_e32 v[46:47], 0
	v_mov_b64_e32 v[48:49], 0
	v_mov_b64_e32 v[50:51], 0
	v_mov_b64_e32 v[52:53], 0
	v_mov_b64_e32 v[54:55], 0
	v_mov_b64_e32 v[56:57], 0
	v_mov_b64_e32 v[58:59], 0
	v_mov_b64_e32 v[60:61], 0
	v_mov_b64_e32 v[62:63], 0
	v_mov_b64_e32 v[64:65], 0
	v_mov_b64_e32 v[66:67], 0
	v_mov_b64_e32 v[68:69], 0
	v_mov_b64_e32 v[70:71], 0
	v_mov_b64_e32 v[72:73], 0
	v_mov_b64_e32 v[74:75], 0
	v_mov_b64_e32 v[76:77], 0
	v_mov_b64_e32 v[78:79], 0
	v_mov_b64_e32 v[80:81], 0
	v_mov_b64_e32 v[82:83], 0
	v_mov_b64_e32 v[84:85], 0
	v_mov_b64_e32 v[86:87], 0
	v_mov_b64_e32 v[88:89], 0
	v_mov_b64_e32 v[90:91], 0
	v_mov_b64_e32 v[92:93], 0
	v_mov_b64_e32 v[94:95], 0
	v_mov_b64_e32 v[96:97], 0
	v_mov_b64_e32 v[98:99], 0
	v_mov_b64_e32 v[104:105], 0
	v_mov_b64_e32 v[106:107], 0
	v_mov_b64_e32 v[112:113], 0
	v_mov_b64_e32 v[114:115], 0
	v_mov_b64_e32 v[116:117], 0
	v_mov_b64_e32 v[118:119], 0
	v_mov_b64_e32 v[124:125], 0
	v_mov_b64_e32 v[126:127], 0
	v_mov_b64_e32 v[128:129], 0
	v_mov_b64_e32 v[130:131], 0
	v_mov_b64_e32 v[136:137], 0
	v_mov_b64_e32 v[138:139], 0
	v_mov_b64_e32 v[140:141], 0
	v_mov_b64_e32 v[142:143], 0
	s_addc_u32 s56, s31, 0
	s_mov_b32 s57, -2
	s_waitcnt lgkmcnt(0)
.LBB0_981:
	ds_read_b128 v[100:103], v232
	ds_read_b128 v[108:111], v232 offset:1024
	ds_read_b128 v[120:123], v232 offset:2048
	ds_read_b128 v[132:135], v232 offset:3072
	ds_read_b128 v[144:147], v233
	ds_read_b128 v[148:151], v233 offset:1024
	ds_read_b128 v[152:155], v233 offset:2048
	ds_read_b128 v[156:159], v233 offset:3072
	s_add_u32 s30, s28, 0xfffe0080
	s_addc_u32 s31, s29, -1
	s_cmp_eq_u32 s57, 4
	s_cselect_b32 s35, s3, s31
	s_cselect_b32 s34, s17, s30
	s_cselect_b32 s31, s19, s56
	s_cselect_b32 s30, s54, s55
	s_mov_b32 m0, s51
	v_lshl_add_u64 v[204:205], s[28:29], 0, v[192:193]
	ds_read_b128 v[160:163], v234
	ds_read_b128 v[164:167], v234 offset:1024
	ds_read_b128 v[168:171], v234 offset:2048
	ds_read_b128 v[172:175], v234 offset:3072
	ds_read_b128 v[176:179], v234 offset:4096
	ds_read_b128 v[180:183], v234 offset:5120
	ds_read_b128 v[196:199], v234 offset:6144
	ds_read_b128 v[200:203], v234 offset:7168
	global_load_lds_dwordx4 v[204:205], off
	v_lshl_add_u64 v[204:205], s[28:29], 0, v[194:195]
	s_mov_b32 m0, s53
	s_nop 0
	global_load_lds_dwordx4 v[204:205], off
	s_waitcnt vmcnt(8)
	s_waitcnt lgkmcnt(0)
	s_setprio 1
	s_waitcnt lgkmcnt(0)
	v_mfma_f32_16x16x32_bf16 v[140:143], v[100:103], v[160:163], v[140:143]
	v_mfma_f32_16x16x32_bf16 v[136:139], v[120:123], v[160:163], v[136:139]
	v_mfma_f32_16x16x32_bf16 v[116:119], v[100:103], v[168:171], v[116:119]
	v_mfma_f32_16x16x32_bf16 v[112:115], v[120:123], v[168:171], v[112:115]
	s_barrier
	v_mfma_f32_16x16x32_bf16 v[92:95], v[100:103], v[176:179], v[92:95]
	v_mfma_f32_16x16x32_bf16 v[88:91], v[120:123], v[176:179], v[88:91]
	v_mfma_f32_16x16x32_bf16 v[76:79], v[100:103], v[196:199], v[76:79]
	v_mfma_f32_16x16x32_bf16 v[72:75], v[120:123], v[196:199], v[72:75]
	v_mfma_f32_16x16x32_bf16 v[140:143], v[108:111], v[164:167], v[140:143]
	v_mfma_f32_16x16x32_bf16 v[136:139], v[132:135], v[164:167], v[136:139]
	v_mfma_f32_16x16x32_bf16 v[116:119], v[108:111], v[172:175], v[116:119]
	v_mfma_f32_16x16x32_bf16 v[112:115], v[132:135], v[172:175], v[112:115]
	v_mfma_f32_16x16x32_bf16 v[92:95], v[108:111], v[180:183], v[92:95]
	v_mfma_f32_16x16x32_bf16 v[88:91], v[132:135], v[180:183], v[88:91]
	v_mfma_f32_16x16x32_bf16 v[76:79], v[108:111], v[200:203], v[76:79]
	v_mfma_f32_16x16x32_bf16 v[72:75], v[132:135], v[200:203], v[72:75]
	s_setprio 0
	s_setprio 1
	v_mfma_f32_16x16x32_bf16 v[128:131], v[144:147], v[160:163], v[128:131]
	v_mfma_f32_16x16x32_bf16 v[124:127], v[152:155], v[160:163], v[124:127]
	v_mfma_f32_16x16x32_bf16 v[104:107], v[144:147], v[168:171], v[104:107]
	v_mfma_f32_16x16x32_bf16 v[96:99], v[152:155], v[168:171], v[96:99]
	v_mfma_f32_16x16x32_bf16 v[84:87], v[144:147], v[176:179], v[84:87]
	v_mfma_f32_16x16x32_bf16 v[80:83], v[152:155], v[176:179], v[80:83]
	v_mfma_f32_16x16x32_bf16 v[68:71], v[144:147], v[196:199], v[68:71]
	v_mfma_f32_16x16x32_bf16 v[64:67], v[152:155], v[196:199], v[64:67]
	v_mfma_f32_16x16x32_bf16 v[128:131], v[148:151], v[164:167], v[128:131]
	v_mfma_f32_16x16x32_bf16 v[124:127], v[156:159], v[164:167], v[124:127]
	v_mfma_f32_16x16x32_bf16 v[104:107], v[148:151], v[172:175], v[104:107]
	v_mfma_f32_16x16x32_bf16 v[96:99], v[156:159], v[172:175], v[96:99]
	v_mfma_f32_16x16x32_bf16 v[84:87], v[148:151], v[180:183], v[84:87]
	v_mfma_f32_16x16x32_bf16 v[80:83], v[156:159], v[180:183], v[80:83]
	v_mfma_f32_16x16x32_bf16 v[68:71], v[148:151], v[200:203], v[68:71]
	v_mfma_f32_16x16x32_bf16 v[64:67], v[156:159], v[200:203], v[64:67]
	s_setprio 0
	s_barrier
; #define PG8_STAGE(bufoff, gbase, voff) do { _Pragma("unroll") for (int _i = 0; _i < 2; ++_i) \
;         __builtin_amdgcn_global_load_lds((const unsigned*)((const char*)(gbase) + (voff)[_i]), (LAS unsigned*)(lds + (bufoff) + ldsw + _i * 8192), 16, 0, 0); } while (0)
; #define PG8_LDA(dst, b, h) do { _Pragma("unroll") for (int m = 0; m < 4; ++m) _Pragma("unroll") for (int k = 0; k < 2; ++k) dst[m][k] = *(const LAS bf16x8*)(lds + PG8_SA(b, h) + aoff + m * 2048 + k * 1024); } while (0)
; #define PG8_LDB(dst, b, h) do { _Pragma("unroll") for (int n = 0; n < 2; ++n) _Pragma("unroll") for (int k = 0; k < 2; ++k) dst[n][k] = *(const LAS bf16x8*)(lds + PG8_SB(b, h) + boff + n * 2048 + k * 1024); } while (0)
; #define PG8_MMA(ai, bj, At, Bt) do { __builtin_amdgcn_s_setprio(1); _Pragma("unroll") for (int m = 0; m < 4; ++m) _Pragma("unroll") for (int n = 0; n < 2; ++n) _Pragma("unroll") for (int k = 0; k < 2; ++k) \
;         acc[ai][bj][m][n] = __builtin_amdgcn_mfma_f32_16x16x32_bf16(Bt[n][k], At[m][k], acc[ai][bj][m][n], 0, 0, 0); __builtin_amdgcn_s_setprio(0); } while (0)
; #define PG8_WAIT_V(n) asm volatile("s_waitcnt vmcnt(" #n ")" ::: "memory")
; #define PG8_WAIT_L(n) asm volatile("s_waitcnt lgkmcnt(" #n ")" ::: "memory")
; #define PG8_BAR __builtin_amdgcn_s_barrier()
; template <class Epi, bool ALIGN_EPI, bool SP2>
; __device__ __forceinline__ void gemm_phase(LAS unsigned char* lds, const int K, const Sched& S, const Epi& E) {
;     ...
;             PG8_WAIT_V(8); PG8_WAIT_L(0); PG8_BAR; PG8_MMA(0, 0, At, B0); PG8_MMA(0, 1, At, B1); PG8_BAR; PG8_SCHED;
;             PG8_LDA(At, 0, 1); PG8_STAGE(PG8_SB(0, 0), b2, voffB); PG8_STAGE(PG8_SB(0, 1), b2 + hstep, voffB); PG8_STAGE(PG8_SA(0, 0), a2, voffA);
;             PG8_WAIT_V(8); PG8_WAIT_L(0); PG8_BAR; PG8_MMA(1, 0, At, B0); PG8_MMA(1, 1, At, B1); PG8_BAR; PG8_SCHED;
;             PG8_LDB(B0, 1, 0); PG8_LDB(B1, 1, 1); PG8_SCHED; PG8_LDA(At, 1, 0); PG8_STAGE(PG8_SA(0, 1), a2 + hstep, voffA);
;             PG8_WAIT_V(8); PG8_WAIT_L(0); PG8_BAR; PG8_MMA(0, 0, At, B0); PG8_MMA(0, 1, At, B1); PG8_BAR; PG8_SCHED;
;             PG8_LDA(At, 1, 1); PG8_STAGE(PG8_SB(1, 0), b3, voffB); PG8_STAGE(PG8_SB(1, 1), b3 + hstep, voffB); PG8_STAGE(PG8_SA(1, 0), a3, voffA);
;             PG8_WAIT_V(8); PG8_WAIT_L(0); PG8_BAR; PG8_MMA(1, 0, At, B0); PG8_MMA(1, 1, At, B1); PG8_BAR; PG8_SCHED;
	s_add_i32 s58, s49, s40
	v_lshl_add_u64 v[204:205], s[30:31], 0, v[186:187]
	s_mov_b32 m0, s58
	ds_read_b128 v[160:163], v234 offset:16384
	ds_read_b128 v[164:167], v234 offset:17408
	ds_read_b128 v[168:171], v234 offset:18432
	ds_read_b128 v[172:175], v234 offset:19456
	ds_read_b128 v[176:179], v234 offset:20480
	ds_read_b128 v[180:183], v234 offset:21504
	ds_read_b128 v[196:199], v234 offset:22528
	ds_read_b128 v[200:203], v234 offset:23552
	global_load_lds_dwordx4 v[204:205], off
	s_add_i32 m0, s58, 0x2000
	s_add_u32 s58, s30, 0x20000
	v_lshl_add_u64 v[206:207], s[30:31], 0, v[190:191]
	s_addc_u32 s59, s31, 0
	s_add_i32 s60, s50, s40
	global_load_lds_dwordx4 v[206:207], off
	v_lshl_add_u64 v[208:209], s[58:59], 0, v[186:187]
	s_mov_b32 m0, s60
	v_lshl_add_u64 v[210:211], s[34:35], 0, v[188:189]
	global_load_lds_dwordx4 v[208:209], off
	v_lshl_add_u64 v[208:209], s[58:59], 0, v[190:191]
	s_add_i32 m0, s60, 0x2000
	s_nop 0
	global_load_lds_dwordx4 v[208:209], off
	v_lshl_add_u64 v[208:209], s[34:35], 0, v[184:185]
	s_mov_b32 m0, s27
	s_nop 0
	global_load_lds_dwordx4 v[208:209], off
	s_mov_b32 m0, s41
	s_nop 0
	global_load_lds_dwordx4 v[210:211], off
	s_waitcnt vmcnt(8)
	s_waitcnt lgkmcnt(0)
	s_setprio 1
	s_waitcnt lgkmcnt(0)
	v_mfma_f32_16x16x32_bf16 v[60:63], v[100:103], v[160:163], v[60:63]
	v_mfma_f32_16x16x32_bf16 v[56:59], v[120:123], v[160:163], v[56:59]
	v_mfma_f32_16x16x32_bf16 v[44:47], v[100:103], v[168:171], v[44:47]
	v_mfma_f32_16x16x32_bf16 v[40:43], v[120:123], v[168:171], v[40:43]
	s_barrier
	v_mfma_f32_16x16x32_bf16 v[28:31], v[100:103], v[176:179], v[28:31]
	v_mfma_f32_16x16x32_bf16 v[24:27], v[120:123], v[176:179], v[24:27]
	v_mfma_f32_16x16x32_bf16 v[12:15], v[100:103], v[196:199], v[12:15]
	v_mfma_f32_16x16x32_bf16 v[8:11], v[120:123], v[196:199], v[8:11]
	v_mfma_f32_16x16x32_bf16 v[60:63], v[108:111], v[164:167], v[60:63]
	v_mfma_f32_16x16x32_bf16 v[56:59], v[132:135], v[164:167], v[56:59]
	v_mfma_f32_16x16x32_bf16 v[44:47], v[108:111], v[172:175], v[44:47]
	v_mfma_f32_16x16x32_bf16 v[40:43], v[132:135], v[172:175], v[40:43]
	v_mfma_f32_16x16x32_bf16 v[28:31], v[108:111], v[180:183], v[28:31]
	v_mfma_f32_16x16x32_bf16 v[24:27], v[132:135], v[180:183], v[24:27]
	v_mfma_f32_16x16x32_bf16 v[12:15], v[108:111], v[200:203], v[12:15]
	v_mfma_f32_16x16x32_bf16 v[8:11], v[132:135], v[200:203], v[8:11]
	s_setprio 0
	s_setprio 1
	v_mfma_f32_16x16x32_bf16 v[52:55], v[144:147], v[160:163], v[52:55]
	v_mfma_f32_16x16x32_bf16 v[48:51], v[152:155], v[160:163], v[48:51]
	v_mfma_f32_16x16x32_bf16 v[36:39], v[144:147], v[168:171], v[36:39]
	v_mfma_f32_16x16x32_bf16 v[32:35], v[152:155], v[168:171], v[32:35]
	v_mfma_f32_16x16x32_bf16 v[20:23], v[144:147], v[176:179], v[20:23]
	v_mfma_f32_16x16x32_bf16 v[16:19], v[152:155], v[176:179], v[16:19]
	v_mfma_f32_16x16x32_bf16 v[4:7], v[144:147], v[196:199], v[4:7]
	v_mfma_f32_16x16x32_bf16 v[0:3], v[152:155], v[196:199], v[0:3]
	v_mfma_f32_16x16x32_bf16 v[52:55], v[148:151], v[164:167], v[52:55]
	v_mfma_f32_16x16x32_bf16 v[48:51], v[156:159], v[164:167], v[48:51]
	v_mfma_f32_16x16x32_bf16 v[36:39], v[148:151], v[172:175], v[36:39]
	v_mfma_f32_16x16x32_bf16 v[32:35], v[156:159], v[172:175], v[32:35]
	v_mfma_f32_16x16x32_bf16 v[20:23], v[148:151], v[180:183], v[20:23]
	v_mfma_f32_16x16x32_bf16 v[16:19], v[156:159], v[180:183], v[16:19]
	v_mfma_f32_16x16x32_bf16 v[4:7], v[148:151], v[200:203], v[4:7]
	v_mfma_f32_16x16x32_bf16 v[0:3], v[156:159], v[200:203], v[0:3]
	s_setprio 0
	s_barrier
	s_add_i32 s58, 0, 0x18000
	s_add_i32 s59, 0, 0x1c000
	v_add_u32_e32 v132, s58, v231
	v_add_u32_e32 v156, s59, v231
	ds_read_b128 v[100:103], v132
	ds_read_b128 v[108:111], v132 offset:1024
	ds_read_b128 v[120:123], v132 offset:2048
	ds_read_b128 v[132:135], v132 offset:3072
	ds_read_b128 v[144:147], v156
	ds_read_b128 v[148:151], v156 offset:1024
	ds_read_b128 v[152:155], v156 offset:2048
	ds_read_b128 v[156:159], v156 offset:3072
	s_add_u32 s34, s34, 0x20000
	s_addc_u32 s35, s35, 0
	s_mov_b32 m0, s42
	v_lshl_add_u64 v[212:213], s[34:35], 0, v[184:185]
	ds_read_b128 v[160:163], v234 offset:32768
	ds_read_b128 v[164:167], v234 offset:33792
	ds_read_b128 v[168:171], v234 offset:34816
	ds_read_b128 v[172:175], v234 offset:35840
	ds_read_b128 v[176:179], v234 offset:36864
	ds_read_b128 v[180:183], v234 offset:37888
	ds_read_b128 v[196:199], v234 offset:38912
	ds_read_b128 v[200:203], v234 offset:39936
	global_load_lds_dwordx4 v[212:213], off
	v_lshl_add_u64 v[212:213], s[34:35], 0, v[188:189]
	s_mov_b32 m0, s43
	s_nop 0
	global_load_lds_dwordx4 v[212:213], off
	s_waitcnt vmcnt(8)
	s_waitcnt lgkmcnt(0)
	s_setprio 1
	s_waitcnt lgkmcnt(0)
	v_mfma_f32_16x16x32_bf16 v[140:143], v[100:103], v[160:163], v[140:143]
	v_mfma_f32_16x16x32_bf16 v[136:139], v[120:123], v[160:163], v[136:139]
	v_mfma_f32_16x16x32_bf16 v[116:119], v[100:103], v[168:171], v[116:119]
	v_mfma_f32_16x16x32_bf16 v[112:115], v[120:123], v[168:171], v[112:115]
	s_barrier
; #define PG8_STAGE(bufoff, gbase, voff) do { _Pragma("unroll") for (int _i = 0; _i < 2; ++_i) \
;         __builtin_amdgcn_global_load_lds((const unsigned*)((const char*)(gbase) + (voff)[_i]), (LAS unsigned*)(lds + (bufoff) + ldsw + _i * 8192), 16, 0, 0); } while (0)
; #define PG8_LDA(dst, b, h) do { _Pragma("unroll") for (int m = 0; m < 4; ++m) _Pragma("unroll") for (int k = 0; k < 2; ++k) dst[m][k] = *(const LAS bf16x8*)(lds + PG8_SA(b, h) + aoff + m * 2048 + k * 1024); } while (0)
; template <class Epi, bool ALIGN_EPI, bool SP2>
; __device__ __forceinline__ void gemm_phase(LAS unsigned char* lds, const int K, const Sched& S, const Epi& E) {
;     ...
;             PG8_WAIT_V(8); PG8_WAIT_L(0); PG8_BAR; PG8_MMA(0, 0, At, B0); PG8_MMA(0, 1, At, B1); PG8_BAR; PG8_SCHED;
;             PG8_LDA(At, 1, 1); PG8_STAGE(PG8_SB(1, 0), b3, voffB); PG8_STAGE(PG8_SB(1, 1), b3 + hstep, voffB); PG8_STAGE(PG8_SA(1, 0), a3, voffA);
;             PG8_WAIT_V(8); PG8_WAIT_L(0); PG8_BAR; PG8_MMA(1, 0, At, B0); PG8_MMA(1, 1, At, B1); PG8_BAR; PG8_SCHED;
;             } else {
;             PG8_LDB(B0, 0, 0); PG8_SCHED; PG8_LDA(At, 0, 0); PG8_STAGE(PG8_SA(1, 1), a1 + hstep, voffA);
;             PG8_WAIT_L(8); PG8_BAR; PG8_WAIT_L(0); PG8_MMA(0, 0, At, B0); PG8_BAR; PG8_SCHED;
;             PG8_LDB(B1, 0, 1); PG8_STAGE(PG8_SB(0, 0), b2, voffB);
;             PG8_BAR; PG8_WAIT_L(0); PG8_MMA(0, 1, At, B1); PG8_BAR;
;             PG8_LDA(At, 0, 1); PG8_STAGE(PG8_SA(0, 0), a2, voffA);
;             PG8_BAR; PG8_WAIT_L(0); PG8_MMA(1, 0, At, B0); PG8_BAR; PG8_SCHED;
;             PG8_STAGE(PG8_SB(0, 1), b2 + hstep, voffB);
;             PG8_WAIT_V(6); PG8_BAR; PG8_MMA(1, 1, At, B1); PG8_BAR;
;             PG8_LDB(B0, 1, 0); PG8_SCHED; PG8_LDA(At, 1, 0); PG8_STAGE(PG8_SA(0, 1), a2 + hstep, voffA);
;             PG8_WAIT_L(8); PG8_BAR; PG8_WAIT_L(0); PG8_MMA(0, 0, At, B0); PG8_BAR; PG8_SCHED;
;             PG8_LDB(B1, 1, 1); PG8_STAGE(PG8_SB(1, 0), b3, voffB);
;             PG8_BAR; PG8_WAIT_L(0); PG8_MMA(0, 1, At, B1); PG8_BAR;
;             PG8_LDA(At, 1, 1); PG8_STAGE(PG8_SA(1, 0), a3, voffA);
;             PG8_BAR; PG8_WAIT_L(0); PG8_MMA(1, 0, At, B0); PG8_BAR; PG8_SCHED;
;             PG8_STAGE(PG8_SB(1, 1), b3 + hstep, voffB);
;             PG8_WAIT_V(6); PG8_BAR; PG8_MMA(1, 1, At, B1); PG8_BAR;
;             }
;         }
;         if constexpr (ALIGN_EPI) { if (wr == 0) PG8_BAR; }
	v_mfma_f32_16x16x32_bf16 v[92:95], v[100:103], v[176:179], v[92:95]
	v_mfma_f32_16x16x32_bf16 v[88:91], v[120:123], v[176:179], v[88:91]
	v_mfma_f32_16x16x32_bf16 v[76:79], v[100:103], v[196:199], v[76:79]
	v_mfma_f32_16x16x32_bf16 v[72:75], v[120:123], v[196:199], v[72:75]
	v_mfma_f32_16x16x32_bf16 v[140:143], v[108:111], v[164:167], v[140:143]
	v_mfma_f32_16x16x32_bf16 v[136:139], v[132:135], v[164:167], v[136:139]
	v_mfma_f32_16x16x32_bf16 v[116:119], v[108:111], v[172:175], v[116:119]
	v_mfma_f32_16x16x32_bf16 v[112:115], v[132:135], v[172:175], v[112:115]
	v_mfma_f32_16x16x32_bf16 v[92:95], v[108:111], v[180:183], v[92:95]
	v_mfma_f32_16x16x32_bf16 v[88:91], v[132:135], v[180:183], v[88:91]
	v_mfma_f32_16x16x32_bf16 v[76:79], v[108:111], v[200:203], v[76:79]
	v_mfma_f32_16x16x32_bf16 v[72:75], v[132:135], v[200:203], v[72:75]
	s_setprio 0
	s_setprio 1
	v_mfma_f32_16x16x32_bf16 v[128:131], v[144:147], v[160:163], v[128:131]
	v_mfma_f32_16x16x32_bf16 v[124:127], v[152:155], v[160:163], v[124:127]
	v_mfma_f32_16x16x32_bf16 v[104:107], v[144:147], v[168:171], v[104:107]
	v_mfma_f32_16x16x32_bf16 v[96:99], v[152:155], v[168:171], v[96:99]
	v_mfma_f32_16x16x32_bf16 v[84:87], v[144:147], v[176:179], v[84:87]
	v_mfma_f32_16x16x32_bf16 v[80:83], v[152:155], v[176:179], v[80:83]
	v_mfma_f32_16x16x32_bf16 v[68:71], v[144:147], v[196:199], v[68:71]
	v_mfma_f32_16x16x32_bf16 v[64:67], v[152:155], v[196:199], v[64:67]
	v_mfma_f32_16x16x32_bf16 v[128:131], v[148:151], v[164:167], v[128:131]
	v_mfma_f32_16x16x32_bf16 v[124:127], v[156:159], v[164:167], v[124:127]
	v_mfma_f32_16x16x32_bf16 v[104:107], v[148:151], v[172:175], v[104:107]
	v_mfma_f32_16x16x32_bf16 v[96:99], v[156:159], v[172:175], v[96:99]
	v_mfma_f32_16x16x32_bf16 v[84:87], v[148:151], v[180:183], v[84:87]
	v_mfma_f32_16x16x32_bf16 v[80:83], v[156:159], v[180:183], v[80:83]
	v_mfma_f32_16x16x32_bf16 v[68:71], v[148:151], v[200:203], v[68:71]
	v_mfma_f32_16x16x32_bf16 v[64:67], v[156:159], v[200:203], v[64:67]
	s_setprio 0
	s_barrier
	s_add_i32 s34, s58, s40
	v_lshl_add_u64 v[204:205], v[204:205], 0, s[12:13]
	s_mov_b32 m0, s34
	ds_read_b128 v[160:163], v234 offset:49152
	ds_read_b128 v[164:167], v234 offset:50176
	ds_read_b128 v[168:171], v234 offset:51200
	ds_read_b128 v[172:175], v234 offset:52224
	ds_read_b128 v[176:179], v234 offset:53248
	ds_read_b128 v[180:183], v234 offset:54272
	ds_read_b128 v[196:199], v234 offset:55296
	ds_read_b128 v[200:203], v234 offset:56320
	global_load_lds_dwordx4 v[204:205], off
	s_add_i32 m0, s34, 0x2000
	s_add_u32 s30, s30, 0x20080
	v_lshl_add_u64 v[204:205], v[206:207], 0, s[12:13]
	s_addc_u32 s31, s31, 0
	s_add_i32 s34, s59, s40
	global_load_lds_dwordx4 v[204:205], off
	v_lshl_add_u64 v[204:205], s[30:31], 0, v[186:187]
	s_mov_b32 m0, s34
	s_nop 0
	global_load_lds_dwordx4 v[204:205], off
	v_lshl_add_u64 v[204:205], s[30:31], 0, v[190:191]
	s_add_i32 m0, s34, 0x2000
	s_nop 0
	global_load_lds_dwordx4 v[204:205], off
	v_lshl_add_u64 v[204:205], v[208:209], 0, s[12:13]
	s_mov_b32 m0, s47
	s_nop 0
	global_load_lds_dwordx4 v[204:205], off
	v_lshl_add_u64 v[204:205], v[210:211], 0, s[12:13]
	s_mov_b32 m0, s48
	s_nop 0
	global_load_lds_dwordx4 v[204:205], off
	s_waitcnt vmcnt(8)
	s_waitcnt lgkmcnt(0)
	s_setprio 1
	s_waitcnt lgkmcnt(0)
	v_mfma_f32_16x16x32_bf16 v[60:63], v[100:103], v[160:163], v[60:63]
	v_mfma_f32_16x16x32_bf16 v[56:59], v[120:123], v[160:163], v[56:59]
	v_mfma_f32_16x16x32_bf16 v[44:47], v[100:103], v[168:171], v[44:47]
	v_mfma_f32_16x16x32_bf16 v[40:43], v[120:123], v[168:171], v[40:43]
	s_barrier
	v_mfma_f32_16x16x32_bf16 v[28:31], v[100:103], v[176:179], v[28:31]
	v_mfma_f32_16x16x32_bf16 v[24:27], v[120:123], v[176:179], v[24:27]
	v_mfma_f32_16x16x32_bf16 v[12:15], v[100:103], v[196:199], v[12:15]
	v_mfma_f32_16x16x32_bf16 v[8:11], v[120:123], v[196:199], v[8:11]
	v_mfma_f32_16x16x32_bf16 v[60:63], v[108:111], v[164:167], v[60:63]
	v_mfma_f32_16x16x32_bf16 v[56:59], v[132:135], v[164:167], v[56:59]
	v_mfma_f32_16x16x32_bf16 v[44:47], v[108:111], v[172:175], v[44:47]
	v_mfma_f32_16x16x32_bf16 v[40:43], v[132:135], v[172:175], v[40:43]
	v_mfma_f32_16x16x32_bf16 v[28:31], v[108:111], v[180:183], v[28:31]
	v_mfma_f32_16x16x32_bf16 v[24:27], v[132:135], v[180:183], v[24:27]
	v_mfma_f32_16x16x32_bf16 v[12:15], v[108:111], v[200:203], v[12:15]
	v_mfma_f32_16x16x32_bf16 v[8:11], v[132:135], v[200:203], v[8:11]
	s_setprio 0
	s_setprio 1
	v_mfma_f32_16x16x32_bf16 v[52:55], v[144:147], v[160:163], v[52:55]
	v_mfma_f32_16x16x32_bf16 v[48:51], v[152:155], v[160:163], v[48:51]
	v_mfma_f32_16x16x32_bf16 v[36:39], v[144:147], v[168:171], v[36:39]
	v_mfma_f32_16x16x32_bf16 v[32:35], v[152:155], v[168:171], v[32:35]
	v_mfma_f32_16x16x32_bf16 v[20:23], v[144:147], v[176:179], v[20:23]
	v_mfma_f32_16x16x32_bf16 v[16:19], v[152:155], v[176:179], v[16:19]
	v_mfma_f32_16x16x32_bf16 v[4:7], v[144:147], v[196:199], v[4:7]
	v_mfma_f32_16x16x32_bf16 v[0:3], v[152:155], v[196:199], v[0:3]
	v_mfma_f32_16x16x32_bf16 v[52:55], v[148:151], v[164:167], v[52:55]
	v_mfma_f32_16x16x32_bf16 v[48:51], v[156:159], v[164:167], v[48:51]
	v_mfma_f32_16x16x32_bf16 v[36:39], v[148:151], v[172:175], v[36:39]
	v_mfma_f32_16x16x32_bf16 v[32:35], v[156:159], v[172:175], v[32:35]
	v_mfma_f32_16x16x32_bf16 v[20:23], v[148:151], v[180:183], v[20:23]
	v_mfma_f32_16x16x32_bf16 v[16:19], v[156:159], v[180:183], v[16:19]
	v_mfma_f32_16x16x32_bf16 v[4:7], v[148:151], v[200:203], v[4:7]
	v_mfma_f32_16x16x32_bf16 v[0:3], v[156:159], v[200:203], v[0:3]
	s_setprio 0
	s_barrier
	s_add_i32 s57, s57, 2
	s_add_u32 s28, s28, 0x100
	s_addc_u32 s29, s29, 0
	s_add_u32 s55, s55, 0x100
	s_addc_u32 s56, s56, 0
	s_cmp_gt_u32 s57, 5
	s_cbranch_scc0 .LBB0_981
	s_and_b64 vcc, exec, s[14:15]
	s_cbranch_vccz .LBB0_984
	s_barrier

;     __device__ __forceinline__ const char* aptr(const Unit& u) const { return (u.kind == 1 ? A1 : A0) + (size_t)u.pm * tstep; }
;     __device__ __forceinline__ const char* bptr(const Unit& u) const { return (u.kind == 1 ? B1 : B0) + (size_t)u.pn * tstep; }
; #define PG8_STAGE(bufoff, gbase, voff) do { _Pragma("unroll") for (int _i = 0; _i < 2; ++_i) \
;         __builtin_amdgcn_global_load_lds((const unsigned*)((const char*)(gbase) + (voff)[_i]), (LAS unsigned*)(lds + (bufoff) + ldsw + _i * 8192), 16, 0, 0); } while (0)
; #define PG8_LDA(dst, b, h) do { _Pragma("unroll") for (int m = 0; m < 4; ++m) _Pragma("unroll") for (int k = 0; k < 2; ++k) dst[m][k] = *(const LAS bf16x8*)(lds + PG8_SA(b, h) + aoff + m * 2048 + k * 1024); } while (0)
; #define PG8_LDB(dst, b, h) do { _Pragma("unroll") for (int n = 0; n < 2; ++n) _Pragma("unroll") for (int k = 0; k < 2; ++k) dst[n][k] = *(const LAS bf16x8*)(lds + PG8_SB(b, h) + boff + n * 2048 + k * 1024); } while (0)
; #define PG8_WAIT_V(n) asm volatile("s_waitcnt vmcnt(" #n ")" ::: "memory")
; template <class Epi, bool ALIGN_EPI, bool SP2>
; __device__ __forceinline__ void gemm_phase(LAS unsigned char* lds, const int K, const Sched& S, const Epi& E) {
;     ...
;     for (;;) {
;         const bool has_next = S.next(ui + 1, nxt);
;         const char* nA = has_next ? S.aptr(nxt) : cA; const char* nB = has_next ? S.bptr(nxt) : cB;
;         for (int t = 0; t < nt; t += 2) {
;             const bool last = (t == nt - 2);
;             const char* a1 = cA + (size_t)(t + 1) * kstep;
;             const char* a2 = last ? nA : cA + (size_t)(t + 2) * kstep; const char* b2 = last ? nB : cB + (size_t)(t + 2) * kstep;
;             const char* a3 = a2 + kstep; const char* b3 = b2 + kstep;
;             if constexpr (SP2) {
;             PG8_LDB(B0, 0, 0); PG8_LDB(B1, 0, 1); PG8_SCHED; PG8_LDA(At, 0, 0); PG8_STAGE(PG8_SA(1, 1), a1 + hstep, voffA);
;             PG8_WAIT_V(8); PG8_WAIT_L(0); PG8_BAR; PG8_MMA(0, 0, At, B0); PG8_MMA(0, 1, At, B1); PG8_BAR; PG8_SCHED;
;     ...
; #pragma unroll
;         for (int a = 0; a < 2; ++a)
; #pragma unroll
;             for (int b = 0; b < 2; ++b)
; #pragma unroll
;                 for (int m = 0; m < 4; ++m)
; #pragma unroll
;                     for (int n = 0; n < 2; ++n) acc[a][b][m][n] = (f32x4){0.f, 0.f, 0.f, 0.f};
;         cur = nxt; cA = nA; cB = nB; ++ui;
.LBB0_1087:
	s_ashr_i32 s31, s30, 31
	s_lshl_b64 s[36:37], s[30:31], 19
	s_add_u32 s36, s48, s36
	s_addc_u32 s37, s49, s37
	s_and_b64 s[40:41], s[38:39], exec
	s_cselect_b32 s31, s37, s43
	s_cselect_b32 s72, s36, s42
	s_ashr_i32 s35, s34, 31
	s_lshl_b64 s[40:41], s[34:35], 19
	s_add_u32 s40, s50, s40
	s_addc_u32 s41, s51, s41
	s_and_b64 s[46:47], s[38:39], exec
	s_cselect_b32 s35, s41, s45
	s_cselect_b32 s73, s40, s44
	s_add_u32 s42, s42, 0x40080
	s_addc_u32 s43, s43, 0
	s_add_u32 s74, s44, 0x100
	v_mov_b64_e32 v[0:1], 0
	v_mov_b64_e32 v[2:3], 0
	v_mov_b64_e32 v[4:5], 0
	v_mov_b64_e32 v[6:7], 0
	v_mov_b64_e32 v[8:9], 0
	v_mov_b64_e32 v[10:11], 0
	v_mov_b64_e32 v[12:13], 0
	v_mov_b64_e32 v[14:15], 0
	v_mov_b64_e32 v[16:17], 0
	v_mov_b64_e32 v[18:19], 0
	v_mov_b64_e32 v[20:21], 0
	v_mov_b64_e32 v[22:23], 0
	v_mov_b64_e32 v[24:25], 0
	v_mov_b64_e32 v[26:27], 0
	v_mov_b64_e32 v[28:29], 0
	v_mov_b64_e32 v[30:31], 0
	v_mov_b64_e32 v[32:33], 0
	v_mov_b64_e32 v[34:35], 0
	v_mov_b64_e32 v[36:37], 0
	v_mov_b64_e32 v[38:39], 0
	v_mov_b64_e32 v[40:41], 0
	v_mov_b64_e32 v[42:43], 0
	v_mov_b64_e32 v[44:45], 0
	v_mov_b64_e32 v[46:47], 0
	v_mov_b64_e32 v[48:49], 0
	v_mov_b64_e32 v[50:51], 0
	v_mov_b64_e32 v[52:53], 0
	v_mov_b64_e32 v[54:55], 0
	v_mov_b64_e32 v[56:57], 0
	v_mov_b64_e32 v[58:59], 0
	v_mov_b64_e32 v[60:61], 0
	v_mov_b64_e32 v[62:63], 0
	v_mov_b64_e32 v[64:65], 0
	v_mov_b64_e32 v[66:67], 0
	v_mov_b64_e32 v[68:69], 0
	v_mov_b64_e32 v[70:71], 0
	v_mov_b64_e32 v[72:73], 0
	v_mov_b64_e32 v[74:75], 0
	v_mov_b64_e32 v[76:77], 0
	v_mov_b64_e32 v[78:79], 0
	v_mov_b64_e32 v[80:81], 0
	v_mov_b64_e32 v[82:83], 0
	v_mov_b64_e32 v[84:85], 0
	v_mov_b64_e32 v[86:87], 0
	v_mov_b64_e32 v[88:89], 0
	v_mov_b64_e32 v[90:91], 0
	v_mov_b64_e32 v[92:93], 0
	v_mov_b64_e32 v[94:95], 0
	v_mov_b64_e32 v[96:97], 0
	v_mov_b64_e32 v[98:99], 0
	v_mov_b64_e32 v[100:101], 0
	v_mov_b64_e32 v[102:103], 0
	v_mov_b64_e32 v[104:105], 0
	v_mov_b64_e32 v[106:107], 0
	v_mov_b64_e32 v[108:109], 0
	v_mov_b64_e32 v[110:111], 0
	v_mov_b64_e32 v[112:113], 0
	v_mov_b64_e32 v[114:115], 0
	v_mov_b64_e32 v[116:117], 0
	v_mov_b64_e32 v[118:119], 0
	v_mov_b64_e32 v[120:121], 0
	v_mov_b64_e32 v[122:123], 0
	v_mov_b64_e32 v[124:125], 0
	v_mov_b64_e32 v[126:127], 0
	s_addc_u32 s75, s45, 0
	s_mov_b32 s76, -2
.LBB0_1088:
	ds_read_b128 v[146:149], v143
	ds_read_b128 v[150:153], v143 offset:1024
	ds_read_b128 v[154:157], v143 offset:2048
	ds_read_b128 v[158:161], v143 offset:3072
	ds_read_b128 v[162:165], v144
	ds_read_b128 v[166:169], v144 offset:1024
	ds_read_b128 v[170:173], v144 offset:2048
	ds_read_b128 v[174:177], v144 offset:3072
	s_add_u32 s44, s42, 0xfffc0080
	s_addc_u32 s45, s43, -1
	s_cmp_eq_u32 s76, 12
	s_cselect_b32 s47, s31, s45
	s_cselect_b32 s46, s72, s44
	s_cselect_b32 s45, s35, s75
	s_cselect_b32 s44, s73, s74
	v_lshl_add_u64 v[210:211], s[42:43], 0, v[136:137]
	s_add_i32 m0, s54, 0xc000
	ds_read_b128 v[178:181], v145
	ds_read_b128 v[182:185], v145 offset:1024
	ds_read_b128 v[186:189], v145 offset:2048
	ds_read_b128 v[190:193], v145 offset:3072
	ds_read_b128 v[194:197], v145 offset:4096
	ds_read_b128 v[198:201], v145 offset:5120
	ds_read_b128 v[202:205], v145 offset:6144
	ds_read_b128 v[206:209], v145 offset:7168
	global_load_lds_dwordx4 v[210:211], off
	v_lshl_add_u64 v[210:211], s[42:43], 0, v[138:139]
	s_add_i32 m0, s54, 0xe000
	s_nop 0
	global_load_lds_dwordx4 v[210:211], off
	s_waitcnt vmcnt(8)
	s_waitcnt lgkmcnt(0)
	s_setprio 1
	s_waitcnt lgkmcnt(0)
	v_mfma_f32_16x16x32_bf16 v[124:127], v[146:149], v[178:181], v[124:127]
	v_mfma_f32_16x16x32_bf16 v[120:123], v[154:157], v[178:181], v[120:123]
	v_mfma_f32_16x16x32_bf16 v[108:111], v[146:149], v[186:189], v[108:111]
	v_mfma_f32_16x16x32_bf16 v[104:107], v[154:157], v[186:189], v[104:107]
	s_barrier
	v_mfma_f32_16x16x32_bf16 v[92:95], v[146:149], v[194:197], v[92:95]
	v_mfma_f32_16x16x32_bf16 v[88:91], v[154:157], v[194:197], v[88:91]
	v_mfma_f32_16x16x32_bf16 v[76:79], v[146:149], v[202:205], v[76:79]
	v_mfma_f32_16x16x32_bf16 v[72:75], v[154:157], v[202:205], v[72:75]
	v_mfma_f32_16x16x32_bf16 v[124:127], v[150:153], v[182:185], v[124:127]
	v_mfma_f32_16x16x32_bf16 v[120:123], v[158:161], v[182:185], v[120:123]
	v_mfma_f32_16x16x32_bf16 v[108:111], v[150:153], v[190:193], v[108:111]
	v_mfma_f32_16x16x32_bf16 v[104:107], v[158:161], v[190:193], v[104:107]
	v_mfma_f32_16x16x32_bf16 v[92:95], v[150:153], v[198:201], v[92:95]
	v_mfma_f32_16x16x32_bf16 v[88:91], v[158:161], v[198:201], v[88:91]
	v_mfma_f32_16x16x32_bf16 v[76:79], v[150:153], v[206:209], v[76:79]
	v_mfma_f32_16x16x32_bf16 v[72:75], v[158:161], v[206:209], v[72:75]
	s_setprio 0
	s_setprio 1
	v_mfma_f32_16x16x32_bf16 v[116:119], v[162:165], v[178:181], v[116:119]
	v_mfma_f32_16x16x32_bf16 v[112:115], v[170:173], v[178:181], v[112:115]
	v_mfma_f32_16x16x32_bf16 v[100:103], v[162:165], v[186:189], v[100:103]
	v_mfma_f32_16x16x32_bf16 v[96:99], v[170:173], v[186:189], v[96:99]
	v_mfma_f32_16x16x32_bf16 v[84:87], v[162:165], v[194:197], v[84:87]
	v_mfma_f32_16x16x32_bf16 v[80:83], v[170:173], v[194:197], v[80:83]
	v_mfma_f32_16x16x32_bf16 v[68:71], v[162:165], v[202:205], v[68:71]
	v_mfma_f32_16x16x32_bf16 v[64:67], v[170:173], v[202:205], v[64:67]
	v_mfma_f32_16x16x32_bf16 v[116:119], v[166:169], v[182:185], v[116:119]
	v_mfma_f32_16x16x32_bf16 v[112:115], v[174:177], v[182:185], v[112:115]
	v_mfma_f32_16x16x32_bf16 v[100:103], v[166:169], v[190:193], v[100:103]
	v_mfma_f32_16x16x32_bf16 v[96:99], v[174:177], v[190:193], v[96:99]
	v_mfma_f32_16x16x32_bf16 v[84:87], v[166:169], v[198:201], v[84:87]
	v_mfma_f32_16x16x32_bf16 v[80:83], v[174:177], v[198:201], v[80:83]
	v_mfma_f32_16x16x32_bf16 v[68:71], v[166:169], v[206:209], v[68:71]
	v_mfma_f32_16x16x32_bf16 v[64:67], v[174:177], v[206:209], v[64:67]
	s_setprio 0
	s_barrier
; #define PG8_STAGE(bufoff, gbase, voff) do { _Pragma("unroll") for (int _i = 0; _i < 2; ++_i) \
;         __builtin_amdgcn_global_load_lds((const unsigned*)((const char*)(gbase) + (voff)[_i]), (LAS unsigned*)(lds + (bufoff) + ldsw + _i * 8192), 16, 0, 0); } while (0)
; #define PG8_LDA(dst, b, h) do { _Pragma("unroll") for (int m = 0; m < 4; ++m) _Pragma("unroll") for (int k = 0; k < 2; ++k) dst[m][k] = *(const LAS bf16x8*)(lds + PG8_SA(b, h) + aoff + m * 2048 + k * 1024); } while (0)
; #define PG8_LDB(dst, b, h) do { _Pragma("unroll") for (int n = 0; n < 2; ++n) _Pragma("unroll") for (int k = 0; k < 2; ++k) dst[n][k] = *(const LAS bf16x8*)(lds + PG8_SB(b, h) + boff + n * 2048 + k * 1024); } while (0)
; #define PG8_MMA(ai, bj, At, Bt) do { __builtin_amdgcn_s_setprio(1); _Pragma("unroll") for (int m = 0; m < 4; ++m) _Pragma("unroll") for (int n = 0; n < 2; ++n) _Pragma("unroll") for (int k = 0; k < 2; ++k) \
;         acc[ai][bj][m][n] = __builtin_amdgcn_mfma_f32_16x16x32_bf16(Bt[n][k], At[m][k], acc[ai][bj][m][n], 0, 0, 0); __builtin_amdgcn_s_setprio(0); } while (0)
; #define PG8_WAIT_V(n) asm volatile("s_waitcnt vmcnt(" #n ")" ::: "memory")
; #define PG8_WAIT_L(n) asm volatile("s_waitcnt lgkmcnt(" #n ")" ::: "memory")
; #define PG8_BAR __builtin_amdgcn_s_barrier()
; template <class Epi, bool ALIGN_EPI, bool SP2>
; __device__ __forceinline__ void gemm_phase(LAS unsigned char* lds, const int K, const Sched& S, const Epi& E) {
;     ...
;             PG8_WAIT_V(8); PG8_WAIT_L(0); PG8_BAR; PG8_MMA(0, 0, At, B0); PG8_MMA(0, 1, At, B1); PG8_BAR; PG8_SCHED;
;             PG8_LDA(At, 0, 1); PG8_STAGE(PG8_SB(0, 0), b2, voffB); PG8_STAGE(PG8_SB(0, 1), b2 + hstep, voffB); PG8_STAGE(PG8_SA(0, 0), a2, voffA);
;             PG8_WAIT_V(8); PG8_WAIT_L(0); PG8_BAR; PG8_MMA(1, 0, At, B0); PG8_MMA(1, 1, At, B1); PG8_BAR; PG8_SCHED;
;             PG8_LDB(B0, 1, 0); PG8_LDB(B1, 1, 1); PG8_SCHED; PG8_LDA(At, 1, 0); PG8_STAGE(PG8_SA(0, 1), a2 + hstep, voffA);
;             PG8_WAIT_V(8); PG8_WAIT_L(0); PG8_BAR; PG8_MMA(0, 0, At, B0); PG8_MMA(0, 1, At, B1); PG8_BAR; PG8_SCHED;
;             PG8_LDA(At, 1, 1); PG8_STAGE(PG8_SB(1, 0), b3, voffB); PG8_STAGE(PG8_SB(1, 1), b3 + hstep, voffB); PG8_STAGE(PG8_SA(1, 0), a3, voffA);
;             PG8_WAIT_V(8); PG8_WAIT_L(0); PG8_BAR; PG8_MMA(1, 0, At, B0); PG8_MMA(1, 1, At, B1); PG8_BAR; PG8_SCHED;
	s_add_i32 s77, s62, s53
	v_lshl_add_u64 v[210:211], s[44:45], 0, v[132:133]
	s_mov_b32 m0, s77
	ds_read_b128 v[178:181], v145 offset:16384
	ds_read_b128 v[182:185], v145 offset:17408
	ds_read_b128 v[186:189], v145 offset:18432
	ds_read_b128 v[190:193], v145 offset:19456
	ds_read_b128 v[194:197], v145 offset:20480
	ds_read_b128 v[198:201], v145 offset:21504
	ds_read_b128 v[202:205], v145 offset:22528
	ds_read_b128 v[206:209], v145 offset:23552
	global_load_lds_dwordx4 v[210:211], off
	s_add_i32 m0, s77, 0x2000
	s_add_u32 s78, s44, 0x40000
	v_lshl_add_u64 v[212:213], s[44:45], 0, v[128:129]
	s_addc_u32 s79, s45, 0
	s_add_i32 s77, s63, s53
	global_load_lds_dwordx4 v[212:213], off
	v_lshl_add_u64 v[214:215], s[78:79], 0, v[132:133]
	s_mov_b32 m0, s77
	v_lshl_add_u64 v[216:217], s[46:47], 0, v[130:131]
	global_load_lds_dwordx4 v[214:215], off
	v_lshl_add_u64 v[214:215], s[78:79], 0, v[128:129]
	s_add_i32 m0, s77, 0x2000
	s_nop 0
	global_load_lds_dwordx4 v[214:215], off
	v_lshl_add_u64 v[214:215], s[46:47], 0, v[134:135]
	s_mov_b32 m0, s54
	s_nop 0
	global_load_lds_dwordx4 v[214:215], off
	s_mov_b32 m0, s55
	s_nop 0
	global_load_lds_dwordx4 v[216:217], off
	s_waitcnt vmcnt(8)
	s_waitcnt lgkmcnt(0)
	s_setprio 1
	s_waitcnt lgkmcnt(0)
	v_mfma_f32_16x16x32_bf16 v[60:63], v[146:149], v[178:181], v[60:63]
	v_mfma_f32_16x16x32_bf16 v[56:59], v[154:157], v[178:181], v[56:59]
	v_mfma_f32_16x16x32_bf16 v[44:47], v[146:149], v[186:189], v[44:47]
	v_mfma_f32_16x16x32_bf16 v[40:43], v[154:157], v[186:189], v[40:43]
	s_barrier
	v_mfma_f32_16x16x32_bf16 v[28:31], v[146:149], v[194:197], v[28:31]
	v_mfma_f32_16x16x32_bf16 v[24:27], v[154:157], v[194:197], v[24:27]
	v_mfma_f32_16x16x32_bf16 v[12:15], v[146:149], v[202:205], v[12:15]
	v_mfma_f32_16x16x32_bf16 v[8:11], v[154:157], v[202:205], v[8:11]
	v_mfma_f32_16x16x32_bf16 v[60:63], v[150:153], v[182:185], v[60:63]
	v_mfma_f32_16x16x32_bf16 v[56:59], v[158:161], v[182:185], v[56:59]
	v_mfma_f32_16x16x32_bf16 v[44:47], v[150:153], v[190:193], v[44:47]
	v_mfma_f32_16x16x32_bf16 v[40:43], v[158:161], v[190:193], v[40:43]
	v_mfma_f32_16x16x32_bf16 v[28:31], v[150:153], v[198:201], v[28:31]
	v_mfma_f32_16x16x32_bf16 v[24:27], v[158:161], v[198:201], v[24:27]
	v_mfma_f32_16x16x32_bf16 v[12:15], v[150:153], v[206:209], v[12:15]
	v_mfma_f32_16x16x32_bf16 v[8:11], v[158:161], v[206:209], v[8:11]
	s_setprio 0
	s_setprio 1
	v_mfma_f32_16x16x32_bf16 v[52:55], v[162:165], v[178:181], v[52:55]
	v_mfma_f32_16x16x32_bf16 v[48:51], v[170:173], v[178:181], v[48:51]
	v_mfma_f32_16x16x32_bf16 v[36:39], v[162:165], v[186:189], v[36:39]
	v_mfma_f32_16x16x32_bf16 v[32:35], v[170:173], v[186:189], v[32:35]
	v_mfma_f32_16x16x32_bf16 v[20:23], v[162:165], v[194:197], v[20:23]
	v_mfma_f32_16x16x32_bf16 v[16:19], v[170:173], v[194:197], v[16:19]
	v_mfma_f32_16x16x32_bf16 v[4:7], v[162:165], v[202:205], v[4:7]
	v_mfma_f32_16x16x32_bf16 v[0:3], v[170:173], v[202:205], v[0:3]
	v_mfma_f32_16x16x32_bf16 v[52:55], v[166:169], v[182:185], v[52:55]
	v_mfma_f32_16x16x32_bf16 v[48:51], v[174:177], v[182:185], v[48:51]
	v_mfma_f32_16x16x32_bf16 v[36:39], v[166:169], v[190:193], v[36:39]
	v_mfma_f32_16x16x32_bf16 v[32:35], v[174:177], v[190:193], v[32:35]
	v_mfma_f32_16x16x32_bf16 v[20:23], v[166:169], v[198:201], v[20:23]
	v_mfma_f32_16x16x32_bf16 v[16:19], v[174:177], v[198:201], v[16:19]
	v_mfma_f32_16x16x32_bf16 v[4:7], v[166:169], v[206:209], v[4:7]
	v_mfma_f32_16x16x32_bf16 v[0:3], v[174:177], v[206:209], v[0:3]
	s_setprio 0
	s_barrier
	s_add_i32 s77, 0, 0x18000
	s_add_i32 s78, 0, 0x1c000
	v_add_u32_e32 v158, s77, v142
	v_add_u32_e32 v174, s78, v142
	ds_read_b128 v[146:149], v158
	ds_read_b128 v[150:153], v158 offset:1024
	ds_read_b128 v[154:157], v158 offset:2048
	ds_read_b128 v[158:161], v158 offset:3072
	ds_read_b128 v[162:165], v174
	ds_read_b128 v[166:169], v174 offset:1024
	ds_read_b128 v[170:173], v174 offset:2048
	ds_read_b128 v[174:177], v174 offset:3072
	s_add_u32 s46, s46, 0x40000
	s_addc_u32 s47, s47, 0
	s_mov_b32 m0, s56
	v_lshl_add_u64 v[218:219], s[46:47], 0, v[134:135]
	ds_read_b128 v[178:181], v145 offset:32768
	ds_read_b128 v[182:185], v145 offset:33792
	ds_read_b128 v[186:189], v145 offset:34816
	ds_read_b128 v[190:193], v145 offset:35840
	ds_read_b128 v[194:197], v145 offset:36864
	ds_read_b128 v[198:201], v145 offset:37888
	ds_read_b128 v[202:205], v145 offset:38912
	ds_read_b128 v[206:209], v145 offset:39936
	global_load_lds_dwordx4 v[218:219], off
	v_lshl_add_u64 v[218:219], s[46:47], 0, v[130:131]
	s_mov_b32 m0, s57
	s_nop 0
	global_load_lds_dwordx4 v[218:219], off
	s_waitcnt vmcnt(8)
	s_waitcnt lgkmcnt(0)
	s_setprio 1
	s_waitcnt lgkmcnt(0)
	v_mfma_f32_16x16x32_bf16 v[124:127], v[146:149], v[178:181], v[124:127]
	v_mfma_f32_16x16x32_bf16 v[120:123], v[154:157], v[178:181], v[120:123]
	v_mfma_f32_16x16x32_bf16 v[108:111], v[146:149], v[186:189], v[108:111]
	v_mfma_f32_16x16x32_bf16 v[104:107], v[154:157], v[186:189], v[104:107]
	s_barrier
; #define PG8_STAGE(bufoff, gbase, voff) do { _Pragma("unroll") for (int _i = 0; _i < 2; ++_i) \
;         __builtin_amdgcn_global_load_lds((const unsigned*)((const char*)(gbase) + (voff)[_i]), (LAS unsigned*)(lds + (bufoff) + ldsw + _i * 8192), 16, 0, 0); } while (0)
; #define PG8_LDA(dst, b, h) do { _Pragma("unroll") for (int m = 0; m < 4; ++m) _Pragma("unroll") for (int k = 0; k < 2; ++k) dst[m][k] = *(const LAS bf16x8*)(lds + PG8_SA(b, h) + aoff + m * 2048 + k * 1024); } while (0)
; template <class Epi, bool ALIGN_EPI, bool SP2>
; __device__ __forceinline__ void gemm_phase(LAS unsigned char* lds, const int K, const Sched& S, const Epi& E) {
;     ...
;             PG8_WAIT_V(8); PG8_WAIT_L(0); PG8_BAR; PG8_MMA(0, 0, At, B0); PG8_MMA(0, 1, At, B1); PG8_BAR; PG8_SCHED;
;             PG8_LDA(At, 1, 1); PG8_STAGE(PG8_SB(1, 0), b3, voffB); PG8_STAGE(PG8_SB(1, 1), b3 + hstep, voffB); PG8_STAGE(PG8_SA(1, 0), a3, voffA);
;             PG8_WAIT_V(8); PG8_WAIT_L(0); PG8_BAR; PG8_MMA(1, 0, At, B0); PG8_MMA(1, 1, At, B1); PG8_BAR; PG8_SCHED;
;             } else {
;             PG8_LDB(B0, 0, 0); PG8_SCHED; PG8_LDA(At, 0, 0); PG8_STAGE(PG8_SA(1, 1), a1 + hstep, voffA);
;             PG8_WAIT_L(8); PG8_BAR; PG8_WAIT_L(0); PG8_MMA(0, 0, At, B0); PG8_BAR; PG8_SCHED;
;             PG8_LDB(B1, 0, 1); PG8_STAGE(PG8_SB(0, 0), b2, voffB);
;             PG8_BAR; PG8_WAIT_L(0); PG8_MMA(0, 1, At, B1); PG8_BAR;
;             PG8_LDA(At, 0, 1); PG8_STAGE(PG8_SA(0, 0), a2, voffA);
;             PG8_BAR; PG8_WAIT_L(0); PG8_MMA(1, 0, At, B0); PG8_BAR; PG8_SCHED;
;             PG8_STAGE(PG8_SB(0, 1), b2 + hstep, voffB);
;             PG8_WAIT_V(6); PG8_BAR; PG8_MMA(1, 1, At, B1); PG8_BAR;
;             PG8_LDB(B0, 1, 0); PG8_SCHED; PG8_LDA(At, 1, 0); PG8_STAGE(PG8_SA(0, 1), a2 + hstep, voffA);
;             PG8_WAIT_L(8); PG8_BAR; PG8_WAIT_L(0); PG8_MMA(0, 0, At, B0); PG8_BAR; PG8_SCHED;
;             PG8_LDB(B1, 1, 1); PG8_STAGE(PG8_SB(1, 0), b3, voffB);
;             PG8_BAR; PG8_WAIT_L(0); PG8_MMA(0, 1, At, B1); PG8_BAR;
;             PG8_LDA(At, 1, 1); PG8_STAGE(PG8_SA(1, 0), a3, voffA);
;             PG8_BAR; PG8_WAIT_L(0); PG8_MMA(1, 0, At, B0); PG8_BAR; PG8_SCHED;
;             PG8_STAGE(PG8_SB(1, 1), b3 + hstep, voffB);
;             PG8_WAIT_V(6); PG8_BAR; PG8_MMA(1, 1, At, B1); PG8_BAR;
;             }
;         }
;         if constexpr (ALIGN_EPI) { if (wr == 0) PG8_BAR; }
	v_mfma_f32_16x16x32_bf16 v[92:95], v[146:149], v[194:197], v[92:95]
	v_mfma_f32_16x16x32_bf16 v[88:91], v[154:157], v[194:197], v[88:91]
	v_mfma_f32_16x16x32_bf16 v[76:79], v[146:149], v[202:205], v[76:79]
	v_mfma_f32_16x16x32_bf16 v[72:75], v[154:157], v[202:205], v[72:75]
	v_mfma_f32_16x16x32_bf16 v[124:127], v[150:153], v[182:185], v[124:127]
	v_mfma_f32_16x16x32_bf16 v[120:123], v[158:161], v[182:185], v[120:123]
	v_mfma_f32_16x16x32_bf16 v[108:111], v[150:153], v[190:193], v[108:111]
	v_mfma_f32_16x16x32_bf16 v[104:107], v[158:161], v[190:193], v[104:107]
	v_mfma_f32_16x16x32_bf16 v[92:95], v[150:153], v[198:201], v[92:95]
	v_mfma_f32_16x16x32_bf16 v[88:91], v[158:161], v[198:201], v[88:91]
	v_mfma_f32_16x16x32_bf16 v[76:79], v[150:153], v[206:209], v[76:79]
	v_mfma_f32_16x16x32_bf16 v[72:75], v[158:161], v[206:209], v[72:75]
	s_setprio 0
	s_setprio 1
	v_mfma_f32_16x16x32_bf16 v[116:119], v[162:165], v[178:181], v[116:119]
	v_mfma_f32_16x16x32_bf16 v[112:115], v[170:173], v[178:181], v[112:115]
	v_mfma_f32_16x16x32_bf16 v[100:103], v[162:165], v[186:189], v[100:103]
	v_mfma_f32_16x16x32_bf16 v[96:99], v[170:173], v[186:189], v[96:99]
	v_mfma_f32_16x16x32_bf16 v[84:87], v[162:165], v[194:197], v[84:87]
	v_mfma_f32_16x16x32_bf16 v[80:83], v[170:173], v[194:197], v[80:83]
	v_mfma_f32_16x16x32_bf16 v[68:71], v[162:165], v[202:205], v[68:71]
	v_mfma_f32_16x16x32_bf16 v[64:67], v[170:173], v[202:205], v[64:67]
	v_mfma_f32_16x16x32_bf16 v[116:119], v[166:169], v[182:185], v[116:119]
	v_mfma_f32_16x16x32_bf16 v[112:115], v[174:177], v[182:185], v[112:115]
	v_mfma_f32_16x16x32_bf16 v[100:103], v[166:169], v[190:193], v[100:103]
	v_mfma_f32_16x16x32_bf16 v[96:99], v[174:177], v[190:193], v[96:99]
	v_mfma_f32_16x16x32_bf16 v[84:87], v[166:169], v[198:201], v[84:87]
	v_mfma_f32_16x16x32_bf16 v[80:83], v[174:177], v[198:201], v[80:83]
	v_mfma_f32_16x16x32_bf16 v[68:71], v[166:169], v[206:209], v[68:71]
	v_mfma_f32_16x16x32_bf16 v[64:67], v[174:177], v[206:209], v[64:67]
	s_setprio 0
	s_barrier
	s_add_i32 s46, s77, s53
	v_lshl_add_u64 v[210:211], v[210:211], 0, s[14:15]
	s_mov_b32 m0, s46
	ds_read_b128 v[178:181], v145 offset:49152
	ds_read_b128 v[182:185], v145 offset:50176
	ds_read_b128 v[186:189], v145 offset:51200
	ds_read_b128 v[190:193], v145 offset:52224
	ds_read_b128 v[194:197], v145 offset:53248
	ds_read_b128 v[198:201], v145 offset:54272
	ds_read_b128 v[202:205], v145 offset:55296
	ds_read_b128 v[206:209], v145 offset:56320
	global_load_lds_dwordx4 v[210:211], off
	s_add_i32 m0, s46, 0x2000
	s_add_u32 s44, s44, 0x40080
	v_lshl_add_u64 v[210:211], v[212:213], 0, s[14:15]
	s_addc_u32 s45, s45, 0
	s_add_i32 s46, s78, s53
	global_load_lds_dwordx4 v[210:211], off
	v_lshl_add_u64 v[210:211], s[44:45], 0, v[132:133]
	s_mov_b32 m0, s46
	s_nop 0
	global_load_lds_dwordx4 v[210:211], off
	v_lshl_add_u64 v[210:211], s[44:45], 0, v[128:129]
	s_add_i32 m0, s46, 0x2000
	s_nop 0
	global_load_lds_dwordx4 v[210:211], off
	v_lshl_add_u64 v[210:211], v[214:215], 0, s[14:15]
	s_mov_b32 m0, s60
	s_nop 0
	global_load_lds_dwordx4 v[210:211], off
	v_lshl_add_u64 v[210:211], v[216:217], 0, s[14:15]
	s_mov_b32 m0, s61
	s_nop 0
	global_load_lds_dwordx4 v[210:211], off
	s_waitcnt vmcnt(8)
	s_waitcnt lgkmcnt(0)
	s_setprio 1
	s_waitcnt lgkmcnt(0)
	v_mfma_f32_16x16x32_bf16 v[60:63], v[146:149], v[178:181], v[60:63]
	v_mfma_f32_16x16x32_bf16 v[56:59], v[154:157], v[178:181], v[56:59]
	v_mfma_f32_16x16x32_bf16 v[44:47], v[146:149], v[186:189], v[44:47]
	v_mfma_f32_16x16x32_bf16 v[40:43], v[154:157], v[186:189], v[40:43]
	s_barrier
	v_mfma_f32_16x16x32_bf16 v[28:31], v[146:149], v[194:197], v[28:31]
	v_mfma_f32_16x16x32_bf16 v[24:27], v[154:157], v[194:197], v[24:27]
	v_mfma_f32_16x16x32_bf16 v[12:15], v[146:149], v[202:205], v[12:15]
	v_mfma_f32_16x16x32_bf16 v[8:11], v[154:157], v[202:205], v[8:11]
	v_mfma_f32_16x16x32_bf16 v[60:63], v[150:153], v[182:185], v[60:63]
	v_mfma_f32_16x16x32_bf16 v[56:59], v[158:161], v[182:185], v[56:59]
	v_mfma_f32_16x16x32_bf16 v[44:47], v[150:153], v[190:193], v[44:47]
	v_mfma_f32_16x16x32_bf16 v[40:43], v[158:161], v[190:193], v[40:43]
	v_mfma_f32_16x16x32_bf16 v[28:31], v[150:153], v[198:201], v[28:31]
	v_mfma_f32_16x16x32_bf16 v[24:27], v[158:161], v[198:201], v[24:27]
	v_mfma_f32_16x16x32_bf16 v[12:15], v[150:153], v[206:209], v[12:15]
	v_mfma_f32_16x16x32_bf16 v[8:11], v[158:161], v[206:209], v[8:11]
	s_setprio 0
	s_setprio 1
	v_mfma_f32_16x16x32_bf16 v[52:55], v[162:165], v[178:181], v[52:55]
	v_mfma_f32_16x16x32_bf16 v[48:51], v[170:173], v[178:181], v[48:51]
	v_mfma_f32_16x16x32_bf16 v[36:39], v[162:165], v[186:189], v[36:39]
	v_mfma_f32_16x16x32_bf16 v[32:35], v[170:173], v[186:189], v[32:35]
	v_mfma_f32_16x16x32_bf16 v[20:23], v[162:165], v[194:197], v[20:23]
	v_mfma_f32_16x16x32_bf16 v[16:19], v[170:173], v[194:197], v[16:19]
	v_mfma_f32_16x16x32_bf16 v[4:7], v[162:165], v[202:205], v[4:7]
	v_mfma_f32_16x16x32_bf16 v[0:3], v[170:173], v[202:205], v[0:3]
	v_mfma_f32_16x16x32_bf16 v[52:55], v[166:169], v[182:185], v[52:55]
	v_mfma_f32_16x16x32_bf16 v[48:51], v[174:177], v[182:185], v[48:51]
	v_mfma_f32_16x16x32_bf16 v[36:39], v[166:169], v[190:193], v[36:39]
	v_mfma_f32_16x16x32_bf16 v[32:35], v[174:177], v[190:193], v[32:35]
	v_mfma_f32_16x16x32_bf16 v[20:23], v[166:169], v[198:201], v[20:23]
	v_mfma_f32_16x16x32_bf16 v[16:19], v[174:177], v[198:201], v[16:19]
	v_mfma_f32_16x16x32_bf16 v[4:7], v[166:169], v[206:209], v[4:7]
	v_mfma_f32_16x16x32_bf16 v[0:3], v[174:177], v[206:209], v[0:3]
	s_setprio 0
	s_barrier
	s_add_i32 s76, s76, 2
	s_add_u32 s42, s42, 0x100
	s_addc_u32 s43, s43, 0
	s_add_u32 s74, s74, 0x100
	s_addc_u32 s75, s75, 0
	s_cmp_gt_u32 s76, 13
	s_cbranch_scc0 .LBB0_1088
	s_and_b64 vcc, exec, s[16:17]
	s_cbranch_vccz .LBB0_1091
	s_barrier

;     __device__ __forceinline__ const char* aptr(const Unit& u) const { return (u.kind == 1 ? A1 : A0) + (size_t)u.pm * tstep; }
;     __device__ __forceinline__ const char* bptr(const Unit& u) const { return (u.kind == 1 ? B1 : B0) + (size_t)u.pn * tstep; }
; #define PG8_STAGE(bufoff, gbase, voff) do { _Pragma("unroll") for (int _i = 0; _i < 2; ++_i) \
;         __builtin_amdgcn_global_load_lds((const unsigned*)((const char*)(gbase) + (voff)[_i]), (LAS unsigned*)(lds + (bufoff) + ldsw + _i * 8192), 16, 0, 0); } while (0)
; #define PG8_LDA(dst, b, h) do { _Pragma("unroll") for (int m = 0; m < 4; ++m) _Pragma("unroll") for (int k = 0; k < 2; ++k) dst[m][k] = *(const LAS bf16x8*)(lds + PG8_SA(b, h) + aoff + m * 2048 + k * 1024); } while (0)
; #define PG8_LDB(dst, b, h) do { _Pragma("unroll") for (int n = 0; n < 2; ++n) _Pragma("unroll") for (int k = 0; k < 2; ++k) dst[n][k] = *(const LAS bf16x8*)(lds + PG8_SB(b, h) + boff + n * 2048 + k * 1024); } while (0)
; #define PG8_WAIT_V(n) asm volatile("s_waitcnt vmcnt(" #n ")" ::: "memory")
; template <class Epi, bool ALIGN_EPI, bool SP2>
; __device__ __forceinline__ void gemm_phase(LAS unsigned char* lds, const int K, const Sched& S, const Epi& E) {
;     ...
;     for (;;) {
;         const bool has_next = S.next(ui + 1, nxt);
;         const char* nA = has_next ? S.aptr(nxt) : cA; const char* nB = has_next ? S.bptr(nxt) : cB;
;         for (int t = 0; t < nt; t += 2) {
;             const bool last = (t == nt - 2);
;             const char* a1 = cA + (size_t)(t + 1) * kstep;
;             const char* a2 = last ? nA : cA + (size_t)(t + 2) * kstep; const char* b2 = last ? nB : cB + (size_t)(t + 2) * kstep;
;             const char* a3 = a2 + kstep; const char* b3 = b2 + kstep;
;             if constexpr (SP2) {
;             PG8_LDB(B0, 0, 0); PG8_LDB(B1, 0, 1); PG8_SCHED; PG8_LDA(At, 0, 0); PG8_STAGE(PG8_SA(1, 1), a1 + hstep, voffA);
;             PG8_WAIT_V(8); PG8_WAIT_L(0); PG8_BAR; PG8_MMA(0, 0, At, B0); PG8_MMA(0, 1, At, B1); PG8_BAR; PG8_SCHED;
;     ...
; #pragma unroll
;         for (int a = 0; a < 2; ++a)
; #pragma unroll
;             for (int b = 0; b < 2; ++b)
; #pragma unroll
;                 for (int m = 0; m < 4; ++m)
; #pragma unroll
;                     for (int n = 0; n < 2; ++n) acc[a][b][m][n] = (f32x4){0.f, 0.f, 0.f, 0.f};
;         cur = nxt; cA = nA; cB = nB; ++ui;
.LBB0_1178:
	s_ashr_i32 s13, s12, 31
	s_lshl_b64 s[16:17], s[12:13], 21
	s_add_u32 s16, s28, s16
	s_addc_u32 s17, s29, s17
	s_and_b64 s[20:21], s[18:19], exec
	s_cselect_b32 s13, s17, s23
	s_cselect_b32 s46, s16, s22
	s_ashr_i32 s15, s14, 31
	s_lshl_b64 s[20:21], s[14:15], 21
	s_add_u32 s20, s30, s20
	s_addc_u32 s21, s31, s21
	s_and_b64 s[26:27], s[18:19], exec
	s_cselect_b32 s15, s21, s25
	s_cselect_b32 s47, s20, s24
	s_add_u32 s22, s22, 0x100080
	s_addc_u32 s23, s23, 0
	s_add_u32 s48, s24, 0x100
	v_mov_b64_e32 v[0:1], 0
	v_mov_b64_e32 v[2:3], 0
	v_mov_b64_e32 v[4:5], 0
	v_mov_b64_e32 v[6:7], 0
	v_mov_b64_e32 v[8:9], 0
	v_mov_b64_e32 v[10:11], 0
	v_mov_b64_e32 v[12:13], 0
	v_mov_b64_e32 v[14:15], 0
	v_mov_b64_e32 v[16:17], 0
	v_mov_b64_e32 v[18:19], 0
	v_mov_b64_e32 v[20:21], 0
	v_mov_b64_e32 v[22:23], 0
	v_mov_b64_e32 v[24:25], 0
	v_mov_b64_e32 v[26:27], 0
	v_mov_b64_e32 v[28:29], 0
	v_mov_b64_e32 v[30:31], 0
	v_mov_b64_e32 v[32:33], 0
	v_mov_b64_e32 v[34:35], 0
	v_mov_b64_e32 v[36:37], 0
	v_mov_b64_e32 v[38:39], 0
	v_mov_b64_e32 v[40:41], 0
	v_mov_b64_e32 v[42:43], 0
	v_mov_b64_e32 v[44:45], 0
	v_mov_b64_e32 v[46:47], 0
	v_mov_b64_e32 v[48:49], 0
	v_mov_b64_e32 v[50:51], 0
	v_mov_b64_e32 v[52:53], 0
	v_mov_b64_e32 v[54:55], 0
	v_mov_b64_e32 v[56:57], 0
	v_mov_b64_e32 v[58:59], 0
	v_mov_b64_e32 v[60:61], 0
	v_mov_b64_e32 v[62:63], 0
	v_mov_b64_e32 v[64:65], 0
	v_mov_b64_e32 v[66:67], 0
	v_mov_b64_e32 v[68:69], 0
	v_mov_b64_e32 v[70:71], 0
	v_mov_b64_e32 v[72:73], 0
	v_mov_b64_e32 v[74:75], 0
	v_mov_b64_e32 v[76:77], 0
	v_mov_b64_e32 v[78:79], 0
	v_mov_b64_e32 v[80:81], 0
	v_mov_b64_e32 v[82:83], 0
	v_mov_b64_e32 v[84:85], 0
	v_mov_b64_e32 v[86:87], 0
	v_mov_b64_e32 v[88:89], 0
	v_mov_b64_e32 v[90:91], 0
	v_mov_b64_e32 v[92:93], 0
	v_mov_b64_e32 v[94:95], 0
	v_mov_b64_e32 v[96:97], 0
	v_mov_b64_e32 v[98:99], 0
	v_mov_b64_e32 v[100:101], 0
	v_mov_b64_e32 v[102:103], 0
	v_mov_b64_e32 v[104:105], 0
	v_mov_b64_e32 v[106:107], 0
	v_mov_b64_e32 v[108:109], 0
	v_mov_b64_e32 v[110:111], 0
	v_mov_b64_e32 v[112:113], 0
	v_mov_b64_e32 v[114:115], 0
	v_mov_b64_e32 v[116:117], 0
	v_mov_b64_e32 v[118:119], 0
	v_mov_b64_e32 v[120:121], 0
	v_mov_b64_e32 v[122:123], 0
	v_mov_b64_e32 v[124:125], 0
	v_mov_b64_e32 v[126:127], 0
	s_addc_u32 s49, s25, 0
	s_mov_b32 s50, -2
.LBB0_1179:
	ds_read_b128 v[128:131], v203
	ds_read_b128 v[132:135], v203 offset:1024
	ds_read_b128 v[136:139], v203 offset:2048
	ds_read_b128 v[140:143], v203 offset:3072
	ds_read_b128 v[144:147], v204
	ds_read_b128 v[148:151], v204 offset:1024
	ds_read_b128 v[152:155], v204 offset:2048
	ds_read_b128 v[156:159], v204 offset:3072
	s_add_u32 s24, s22, 0xfff00080
	s_addc_u32 s25, s23, -1
	s_cmp_eq_u32 s50, 60
	s_cselect_b32 s27, s13, s25
	s_cselect_b32 s26, s46, s24
	s_cselect_b32 s25, s15, s49
	s_cselect_b32 s24, s47, s48
	v_lshl_add_u64 v[212:213], s[22:23], 0, v[184:185]
	s_add_i32 m0, s35, 0xc000
	ds_read_b128 v[160:163], v205
	ds_read_b128 v[164:167], v205 offset:1024
	ds_read_b128 v[168:171], v205 offset:2048
	ds_read_b128 v[172:175], v205 offset:3072
	ds_read_b128 v[188:191], v205 offset:4096
	ds_read_b128 v[192:195], v205 offset:5120
	ds_read_b128 v[196:199], v205 offset:6144
	ds_read_b128 v[208:211], v205 offset:7168
	global_load_lds_dwordx4 v[212:213], off
	v_lshl_add_u64 v[212:213], s[22:23], 0, v[186:187]
	s_add_i32 m0, s35, 0xe000
	s_nop 0
	global_load_lds_dwordx4 v[212:213], off
	s_waitcnt vmcnt(8)
	s_waitcnt lgkmcnt(0)
	s_setprio 1
	s_waitcnt lgkmcnt(0)
	v_mfma_f32_16x16x32_bf16 v[124:127], v[128:131], v[160:163], v[124:127]
	v_mfma_f32_16x16x32_bf16 v[120:123], v[136:139], v[160:163], v[120:123]
	v_mfma_f32_16x16x32_bf16 v[112:115], v[128:131], v[168:171], v[112:115]
	v_mfma_f32_16x16x32_bf16 v[104:107], v[136:139], v[168:171], v[104:107]
	s_barrier
	v_mfma_f32_16x16x32_bf16 v[96:99], v[128:131], v[188:191], v[96:99]
	v_mfma_f32_16x16x32_bf16 v[88:91], v[136:139], v[188:191], v[88:91]
	v_mfma_f32_16x16x32_bf16 v[80:83], v[128:131], v[196:199], v[80:83]
	v_mfma_f32_16x16x32_bf16 v[72:75], v[136:139], v[196:199], v[72:75]
	v_mfma_f32_16x16x32_bf16 v[124:127], v[132:135], v[164:167], v[124:127]
	v_mfma_f32_16x16x32_bf16 v[120:123], v[140:143], v[164:167], v[120:123]
	v_mfma_f32_16x16x32_bf16 v[112:115], v[132:135], v[172:175], v[112:115]
	v_mfma_f32_16x16x32_bf16 v[104:107], v[140:143], v[172:175], v[104:107]
	v_mfma_f32_16x16x32_bf16 v[96:99], v[132:135], v[192:195], v[96:99]
	v_mfma_f32_16x16x32_bf16 v[88:91], v[140:143], v[192:195], v[88:91]
	v_mfma_f32_16x16x32_bf16 v[80:83], v[132:135], v[208:211], v[80:83]
	v_mfma_f32_16x16x32_bf16 v[72:75], v[140:143], v[208:211], v[72:75]
	s_setprio 0
	s_setprio 1
	v_mfma_f32_16x16x32_bf16 v[116:119], v[144:147], v[160:163], v[116:119]
	v_mfma_f32_16x16x32_bf16 v[108:111], v[152:155], v[160:163], v[108:111]
	v_mfma_f32_16x16x32_bf16 v[100:103], v[144:147], v[168:171], v[100:103]
	v_mfma_f32_16x16x32_bf16 v[92:95], v[152:155], v[168:171], v[92:95]
	v_mfma_f32_16x16x32_bf16 v[84:87], v[144:147], v[188:191], v[84:87]
	v_mfma_f32_16x16x32_bf16 v[76:79], v[152:155], v[188:191], v[76:79]
	v_mfma_f32_16x16x32_bf16 v[68:71], v[144:147], v[196:199], v[68:71]
	v_mfma_f32_16x16x32_bf16 v[64:67], v[152:155], v[196:199], v[64:67]
	v_mfma_f32_16x16x32_bf16 v[116:119], v[148:151], v[164:167], v[116:119]
	v_mfma_f32_16x16x32_bf16 v[108:111], v[156:159], v[164:167], v[108:111]
	v_mfma_f32_16x16x32_bf16 v[100:103], v[148:151], v[172:175], v[100:103]
	v_mfma_f32_16x16x32_bf16 v[92:95], v[156:159], v[172:175], v[92:95]
	v_mfma_f32_16x16x32_bf16 v[84:87], v[148:151], v[192:195], v[84:87]
	v_mfma_f32_16x16x32_bf16 v[76:79], v[156:159], v[192:195], v[76:79]
	v_mfma_f32_16x16x32_bf16 v[68:71], v[148:151], v[208:211], v[68:71]
	v_mfma_f32_16x16x32_bf16 v[64:67], v[156:159], v[208:211], v[64:67]
	s_setprio 0
	s_barrier
; #define PG8_STAGE(bufoff, gbase, voff) do { _Pragma("unroll") for (int _i = 0; _i < 2; ++_i) \
;         __builtin_amdgcn_global_load_lds((const unsigned*)((const char*)(gbase) + (voff)[_i]), (LAS unsigned*)(lds + (bufoff) + ldsw + _i * 8192), 16, 0, 0); } while (0)
; #define PG8_LDA(dst, b, h) do { _Pragma("unroll") for (int m = 0; m < 4; ++m) _Pragma("unroll") for (int k = 0; k < 2; ++k) dst[m][k] = *(const LAS bf16x8*)(lds + PG8_SA(b, h) + aoff + m * 2048 + k * 1024); } while (0)
; #define PG8_LDB(dst, b, h) do { _Pragma("unroll") for (int n = 0; n < 2; ++n) _Pragma("unroll") for (int k = 0; k < 2; ++k) dst[n][k] = *(const LAS bf16x8*)(lds + PG8_SB(b, h) + boff + n * 2048 + k * 1024); } while (0)
; #define PG8_MMA(ai, bj, At, Bt) do { __builtin_amdgcn_s_setprio(1); _Pragma("unroll") for (int m = 0; m < 4; ++m) _Pragma("unroll") for (int n = 0; n < 2; ++n) _Pragma("unroll") for (int k = 0; k < 2; ++k) \
;         acc[ai][bj][m][n] = __builtin_amdgcn_mfma_f32_16x16x32_bf16(Bt[n][k], At[m][k], acc[ai][bj][m][n], 0, 0, 0); __builtin_amdgcn_s_setprio(0); } while (0)
; #define PG8_WAIT_V(n) asm volatile("s_waitcnt vmcnt(" #n ")" ::: "memory")
; #define PG8_WAIT_L(n) asm volatile("s_waitcnt lgkmcnt(" #n ")" ::: "memory")
; #define PG8_BAR __builtin_amdgcn_s_barrier()
; #define PG8_SCHED __builtin_amdgcn_sched_barrier(0)
; template <class Epi, bool ALIGN_EPI, bool SP2>
; __device__ __forceinline__ void gemm_phase(LAS unsigned char* lds, const int K, const Sched& S, const Epi& E) {
;     ...
;             PG8_LDA(At, 0, 1); PG8_STAGE(PG8_SB(0, 0), b2, voffB); PG8_STAGE(PG8_SB(0, 1), b2 + hstep, voffB); PG8_STAGE(PG8_SA(0, 0), a2, voffA);
;             PG8_WAIT_V(8); PG8_WAIT_L(0); PG8_BAR; PG8_MMA(1, 0, At, B0); PG8_MMA(1, 1, At, B1); PG8_BAR; PG8_SCHED;
;             PG8_LDB(B0, 1, 0); PG8_LDB(B1, 1, 1); PG8_SCHED; PG8_LDA(At, 1, 0); PG8_STAGE(PG8_SA(0, 1), a2 + hstep, voffA);
;             PG8_WAIT_V(8); PG8_WAIT_L(0); PG8_BAR; PG8_MMA(0, 0, At, B0); PG8_MMA(0, 1, At, B1); PG8_BAR; PG8_SCHED;
	s_add_i32 s51, s43, s34
	v_lshl_add_u64 v[212:213], s[24:25], 0, v[180:181]
	s_mov_b32 m0, s51
	ds_read_b128 v[160:163], v205 offset:16384
	ds_read_b128 v[164:167], v205 offset:17408
	ds_read_b128 v[168:171], v205 offset:18432
	ds_read_b128 v[172:175], v205 offset:19456
	ds_read_b128 v[188:191], v205 offset:20480
	ds_read_b128 v[192:195], v205 offset:21504
	ds_read_b128 v[196:199], v205 offset:22528
	ds_read_b128 v[208:211], v205 offset:23552
	global_load_lds_dwordx4 v[212:213], off
	s_add_i32 m0, s51, 0x2000
	s_add_u32 s54, s24, 0x100000
	v_lshl_add_u64 v[214:215], s[24:25], 0, v[176:177]
	s_addc_u32 s55, s25, 0
	s_add_i32 s51, s44, s34
	global_load_lds_dwordx4 v[214:215], off
	v_lshl_add_u64 v[216:217], s[54:55], 0, v[180:181]
	s_mov_b32 m0, s51
	v_lshl_add_u64 v[218:219], s[26:27], 0, v[178:179]
	global_load_lds_dwordx4 v[216:217], off
	v_lshl_add_u64 v[216:217], s[54:55], 0, v[176:177]
	s_add_i32 m0, s51, 0x2000
	s_nop 0
	global_load_lds_dwordx4 v[216:217], off
	v_lshl_add_u64 v[216:217], s[26:27], 0, v[182:183]
	s_mov_b32 m0, s35
	s_nop 0
	global_load_lds_dwordx4 v[216:217], off
	s_mov_b32 m0, s36
	s_nop 0
	global_load_lds_dwordx4 v[218:219], off
	s_waitcnt vmcnt(8)
	s_waitcnt lgkmcnt(0)
	s_setprio 1
	s_waitcnt lgkmcnt(0)
	v_mfma_f32_16x16x32_bf16 v[60:63], v[128:131], v[160:163], v[60:63]
	v_mfma_f32_16x16x32_bf16 v[56:59], v[136:139], v[160:163], v[56:59]
	v_mfma_f32_16x16x32_bf16 v[48:51], v[128:131], v[168:171], v[48:51]
	v_mfma_f32_16x16x32_bf16 v[40:43], v[136:139], v[168:171], v[40:43]
	s_barrier
	v_mfma_f32_16x16x32_bf16 v[32:35], v[128:131], v[188:191], v[32:35]
	v_mfma_f32_16x16x32_bf16 v[24:27], v[136:139], v[188:191], v[24:27]
	v_mfma_f32_16x16x32_bf16 v[16:19], v[128:131], v[196:199], v[16:19]
	v_mfma_f32_16x16x32_bf16 v[8:11], v[136:139], v[196:199], v[8:11]
	v_mfma_f32_16x16x32_bf16 v[60:63], v[132:135], v[164:167], v[60:63]
	v_mfma_f32_16x16x32_bf16 v[56:59], v[140:143], v[164:167], v[56:59]
	v_mfma_f32_16x16x32_bf16 v[48:51], v[132:135], v[172:175], v[48:51]
	v_mfma_f32_16x16x32_bf16 v[40:43], v[140:143], v[172:175], v[40:43]
	v_mfma_f32_16x16x32_bf16 v[32:35], v[132:135], v[192:195], v[32:35]
	v_mfma_f32_16x16x32_bf16 v[24:27], v[140:143], v[192:195], v[24:27]
	v_mfma_f32_16x16x32_bf16 v[16:19], v[132:135], v[208:211], v[16:19]
	v_mfma_f32_16x16x32_bf16 v[8:11], v[140:143], v[208:211], v[8:11]
	s_setprio 0
	s_setprio 1
	v_mfma_f32_16x16x32_bf16 v[52:55], v[144:147], v[160:163], v[52:55]
	v_mfma_f32_16x16x32_bf16 v[44:47], v[152:155], v[160:163], v[44:47]
	v_mfma_f32_16x16x32_bf16 v[36:39], v[144:147], v[168:171], v[36:39]
	v_mfma_f32_16x16x32_bf16 v[28:31], v[152:155], v[168:171], v[28:31]
	v_mfma_f32_16x16x32_bf16 v[20:23], v[144:147], v[188:191], v[20:23]
	v_mfma_f32_16x16x32_bf16 v[12:15], v[152:155], v[188:191], v[12:15]
	v_mfma_f32_16x16x32_bf16 v[4:7], v[144:147], v[196:199], v[4:7]
	v_mfma_f32_16x16x32_bf16 v[0:3], v[152:155], v[196:199], v[0:3]
	v_mfma_f32_16x16x32_bf16 v[52:55], v[148:151], v[164:167], v[52:55]
	v_mfma_f32_16x16x32_bf16 v[44:47], v[156:159], v[164:167], v[44:47]
	v_mfma_f32_16x16x32_bf16 v[36:39], v[148:151], v[172:175], v[36:39]
	v_mfma_f32_16x16x32_bf16 v[28:31], v[156:159], v[172:175], v[28:31]
	v_mfma_f32_16x16x32_bf16 v[20:23], v[148:151], v[192:195], v[20:23]
	v_mfma_f32_16x16x32_bf16 v[12:15], v[156:159], v[192:195], v[12:15]
	v_mfma_f32_16x16x32_bf16 v[4:7], v[148:151], v[208:211], v[4:7]
	v_mfma_f32_16x16x32_bf16 v[0:3], v[156:159], v[208:211], v[0:3]
	s_setprio 0
	s_barrier
	s_add_i32 s51, 0, 0x18000
	s_add_i32 s53, 0, 0x1c000
	v_add_u32_e32 v140, s51, v202
	v_add_u32_e32 v156, s53, v202
	ds_read_b128 v[128:131], v140
	ds_read_b128 v[132:135], v140 offset:1024
	ds_read_b128 v[136:139], v140 offset:2048
	ds_read_b128 v[140:143], v140 offset:3072
	ds_read_b128 v[144:147], v156
	ds_read_b128 v[148:151], v156 offset:1024
	ds_read_b128 v[152:155], v156 offset:2048
	ds_read_b128 v[156:159], v156 offset:3072
	s_add_u32 s26, s26, 0x100000
	s_addc_u32 s27, s27, 0
	s_mov_b32 m0, s37
	v_lshl_add_u64 v[220:221], s[26:27], 0, v[182:183]
	ds_read_b128 v[160:163], v205 offset:32768
	ds_read_b128 v[164:167], v205 offset:33792
	ds_read_b128 v[168:171], v205 offset:34816
	ds_read_b128 v[172:175], v205 offset:35840
	ds_read_b128 v[188:191], v205 offset:36864
	ds_read_b128 v[192:195], v205 offset:37888
	ds_read_b128 v[196:199], v205 offset:38912
	ds_read_b128 v[208:211], v205 offset:39936
	global_load_lds_dwordx4 v[220:221], off
	v_lshl_add_u64 v[220:221], s[26:27], 0, v[178:179]
	s_mov_b32 m0, s38
	s_nop 0
	global_load_lds_dwordx4 v[220:221], off
	s_waitcnt vmcnt(8)
	s_waitcnt lgkmcnt(0)
	s_setprio 1
	s_waitcnt lgkmcnt(0)
	v_mfma_f32_16x16x32_bf16 v[124:127], v[128:131], v[160:163], v[124:127]
	v_mfma_f32_16x16x32_bf16 v[120:123], v[136:139], v[160:163], v[120:123]
	v_mfma_f32_16x16x32_bf16 v[112:115], v[128:131], v[168:171], v[112:115]
	v_mfma_f32_16x16x32_bf16 v[104:107], v[136:139], v[168:171], v[104:107]
	s_barrier
; #define PG8_STAGE(bufoff, gbase, voff) do { _Pragma("unroll") for (int _i = 0; _i < 2; ++_i) \
;         __builtin_amdgcn_global_load_lds((const unsigned*)((const char*)(gbase) + (voff)[_i]), (LAS unsigned*)(lds + (bufoff) + ldsw + _i * 8192), 16, 0, 0); } while (0)
; #define PG8_LDA(dst, b, h) do { _Pragma("unroll") for (int m = 0; m < 4; ++m) _Pragma("unroll") for (int k = 0; k < 2; ++k) dst[m][k] = *(const LAS bf16x8*)(lds + PG8_SA(b, h) + aoff + m * 2048 + k * 1024); } while (0)
; #define PG8_MMA(ai, bj, At, Bt) do { __builtin_amdgcn_s_setprio(1); _Pragma("unroll") for (int m = 0; m < 4; ++m) _Pragma("unroll") for (int n = 0; n < 2; ++n) _Pragma("unroll") for (int k = 0; k < 2; ++k) \
;         acc[ai][bj][m][n] = __builtin_amdgcn_mfma_f32_16x16x32_bf16(Bt[n][k], At[m][k], acc[ai][bj][m][n], 0, 0, 0); __builtin_amdgcn_s_setprio(0); } while (0)
; #define PG8_WAIT_V(n) asm volatile("s_waitcnt vmcnt(" #n ")" ::: "memory")
; #define PG8_WAIT_L(n) asm volatile("s_waitcnt lgkmcnt(" #n ")" ::: "memory")
; #define PG8_BAR __builtin_amdgcn_s_barrier()
; #define PG8_SCHED __builtin_amdgcn_sched_barrier(0)
; template <class Epi, bool ALIGN_EPI, bool SP2>
; __device__ __forceinline__ void gemm_phase(LAS unsigned char* lds, const int K, const Sched& S, const Epi& E) {
;     ...
;         for (int t = 0; t < nt; t += 2) {
;     ...
;             PG8_WAIT_V(8); PG8_WAIT_L(0); PG8_BAR; PG8_MMA(0, 0, At, B0); PG8_MMA(0, 1, At, B1); PG8_BAR; PG8_SCHED;
;             PG8_LDA(At, 1, 1); PG8_STAGE(PG8_SB(1, 0), b3, voffB); PG8_STAGE(PG8_SB(1, 1), b3 + hstep, voffB); PG8_STAGE(PG8_SA(1, 0), a3, voffA);
;             PG8_WAIT_V(8); PG8_WAIT_L(0); PG8_BAR; PG8_MMA(1, 0, At, B0); PG8_MMA(1, 1, At, B1); PG8_BAR; PG8_SCHED;
;     ...
;         if constexpr (ALIGN_EPI) { if (wr == 0) PG8_BAR; }
	v_mfma_f32_16x16x32_bf16 v[96:99], v[128:131], v[188:191], v[96:99]
	v_mfma_f32_16x16x32_bf16 v[88:91], v[136:139], v[188:191], v[88:91]
	v_mfma_f32_16x16x32_bf16 v[80:83], v[128:131], v[196:199], v[80:83]
	v_mfma_f32_16x16x32_bf16 v[72:75], v[136:139], v[196:199], v[72:75]
	v_mfma_f32_16x16x32_bf16 v[124:127], v[132:135], v[164:167], v[124:127]
	v_mfma_f32_16x16x32_bf16 v[120:123], v[140:143], v[164:167], v[120:123]
	v_mfma_f32_16x16x32_bf16 v[112:115], v[132:135], v[172:175], v[112:115]
	v_mfma_f32_16x16x32_bf16 v[104:107], v[140:143], v[172:175], v[104:107]
	v_mfma_f32_16x16x32_bf16 v[96:99], v[132:135], v[192:195], v[96:99]
	v_mfma_f32_16x16x32_bf16 v[88:91], v[140:143], v[192:195], v[88:91]
	v_mfma_f32_16x16x32_bf16 v[80:83], v[132:135], v[208:211], v[80:83]
	v_mfma_f32_16x16x32_bf16 v[72:75], v[140:143], v[208:211], v[72:75]
	s_setprio 0
	s_setprio 1
	v_mfma_f32_16x16x32_bf16 v[116:119], v[144:147], v[160:163], v[116:119]
	v_mfma_f32_16x16x32_bf16 v[108:111], v[152:155], v[160:163], v[108:111]
	v_mfma_f32_16x16x32_bf16 v[100:103], v[144:147], v[168:171], v[100:103]
	v_mfma_f32_16x16x32_bf16 v[92:95], v[152:155], v[168:171], v[92:95]
	v_mfma_f32_16x16x32_bf16 v[84:87], v[144:147], v[188:191], v[84:87]
	v_mfma_f32_16x16x32_bf16 v[76:79], v[152:155], v[188:191], v[76:79]
	v_mfma_f32_16x16x32_bf16 v[68:71], v[144:147], v[196:199], v[68:71]
	v_mfma_f32_16x16x32_bf16 v[64:67], v[152:155], v[196:199], v[64:67]
	v_mfma_f32_16x16x32_bf16 v[116:119], v[148:151], v[164:167], v[116:119]
	v_mfma_f32_16x16x32_bf16 v[108:111], v[156:159], v[164:167], v[108:111]
	v_mfma_f32_16x16x32_bf16 v[100:103], v[148:151], v[172:175], v[100:103]
	v_mfma_f32_16x16x32_bf16 v[92:95], v[156:159], v[172:175], v[92:95]
	v_mfma_f32_16x16x32_bf16 v[84:87], v[148:151], v[192:195], v[84:87]
	v_mfma_f32_16x16x32_bf16 v[76:79], v[156:159], v[192:195], v[76:79]
	v_mfma_f32_16x16x32_bf16 v[68:71], v[148:151], v[208:211], v[68:71]
	v_mfma_f32_16x16x32_bf16 v[64:67], v[156:159], v[208:211], v[64:67]
	s_setprio 0
	s_barrier
	s_add_i32 s26, s51, s34
	v_lshl_add_u64 v[212:213], v[212:213], 0, s[8:9]
	s_mov_b32 m0, s26
	ds_read_b128 v[160:163], v205 offset:49152
	ds_read_b128 v[164:167], v205 offset:50176
	ds_read_b128 v[168:171], v205 offset:51200
	ds_read_b128 v[172:175], v205 offset:52224
	ds_read_b128 v[188:191], v205 offset:53248
	ds_read_b128 v[192:195], v205 offset:54272
	ds_read_b128 v[196:199], v205 offset:55296
	ds_read_b128 v[208:211], v205 offset:56320
	global_load_lds_dwordx4 v[212:213], off
	s_add_i32 m0, s26, 0x2000
	s_add_u32 s24, s24, 0x100080
	v_lshl_add_u64 v[212:213], v[214:215], 0, s[8:9]
	s_addc_u32 s25, s25, 0
	s_add_i32 s26, s53, s34
	global_load_lds_dwordx4 v[212:213], off
	v_lshl_add_u64 v[212:213], s[24:25], 0, v[180:181]
	s_mov_b32 m0, s26
	s_nop 0
	global_load_lds_dwordx4 v[212:213], off
	v_lshl_add_u64 v[212:213], s[24:25], 0, v[176:177]
	s_add_i32 m0, s26, 0x2000
	s_nop 0
	global_load_lds_dwordx4 v[212:213], off
	v_lshl_add_u64 v[212:213], v[216:217], 0, s[8:9]
	s_mov_b32 m0, s41
	s_nop 0
	global_load_lds_dwordx4 v[212:213], off
	v_lshl_add_u64 v[212:213], v[218:219], 0, s[8:9]
	s_mov_b32 m0, s42
	s_nop 0
	global_load_lds_dwordx4 v[212:213], off
	s_waitcnt vmcnt(8)
	s_waitcnt lgkmcnt(0)
	s_setprio 1
	s_waitcnt lgkmcnt(0)
	v_mfma_f32_16x16x32_bf16 v[60:63], v[128:131], v[160:163], v[60:63]
	v_mfma_f32_16x16x32_bf16 v[56:59], v[136:139], v[160:163], v[56:59]
	v_mfma_f32_16x16x32_bf16 v[48:51], v[128:131], v[168:171], v[48:51]
	v_mfma_f32_16x16x32_bf16 v[40:43], v[136:139], v[168:171], v[40:43]
	s_barrier
	v_mfma_f32_16x16x32_bf16 v[32:35], v[128:131], v[188:191], v[32:35]
	v_mfma_f32_16x16x32_bf16 v[24:27], v[136:139], v[188:191], v[24:27]
	v_mfma_f32_16x16x32_bf16 v[16:19], v[128:131], v[196:199], v[16:19]
	v_mfma_f32_16x16x32_bf16 v[8:11], v[136:139], v[196:199], v[8:11]
	v_mfma_f32_16x16x32_bf16 v[60:63], v[132:135], v[164:167], v[60:63]
	v_mfma_f32_16x16x32_bf16 v[56:59], v[140:143], v[164:167], v[56:59]
	v_mfma_f32_16x16x32_bf16 v[48:51], v[132:135], v[172:175], v[48:51]
	v_mfma_f32_16x16x32_bf16 v[40:43], v[140:143], v[172:175], v[40:43]
	v_mfma_f32_16x16x32_bf16 v[32:35], v[132:135], v[192:195], v[32:35]
	v_mfma_f32_16x16x32_bf16 v[24:27], v[140:143], v[192:195], v[24:27]
	v_mfma_f32_16x16x32_bf16 v[16:19], v[132:135], v[208:211], v[16:19]
	v_mfma_f32_16x16x32_bf16 v[8:11], v[140:143], v[208:211], v[8:11]
	s_setprio 0
	s_setprio 1
	v_mfma_f32_16x16x32_bf16 v[52:55], v[144:147], v[160:163], v[52:55]
	v_mfma_f32_16x16x32_bf16 v[44:47], v[152:155], v[160:163], v[44:47]
	v_mfma_f32_16x16x32_bf16 v[36:39], v[144:147], v[168:171], v[36:39]
	v_mfma_f32_16x16x32_bf16 v[28:31], v[152:155], v[168:171], v[28:31]
	v_mfma_f32_16x16x32_bf16 v[20:23], v[144:147], v[188:191], v[20:23]
	v_mfma_f32_16x16x32_bf16 v[12:15], v[152:155], v[188:191], v[12:15]
	v_mfma_f32_16x16x32_bf16 v[4:7], v[144:147], v[196:199], v[4:7]
	v_mfma_f32_16x16x32_bf16 v[0:3], v[152:155], v[196:199], v[0:3]
	v_mfma_f32_16x16x32_bf16 v[52:55], v[148:151], v[164:167], v[52:55]
	v_mfma_f32_16x16x32_bf16 v[44:47], v[156:159], v[164:167], v[44:47]
	v_mfma_f32_16x16x32_bf16 v[36:39], v[148:151], v[172:175], v[36:39]
	v_mfma_f32_16x16x32_bf16 v[28:31], v[156:159], v[172:175], v[28:31]
	v_mfma_f32_16x16x32_bf16 v[20:23], v[148:151], v[192:195], v[20:23]
	v_mfma_f32_16x16x32_bf16 v[12:15], v[156:159], v[192:195], v[12:15]
	v_mfma_f32_16x16x32_bf16 v[4:7], v[148:151], v[208:211], v[4:7]
	v_mfma_f32_16x16x32_bf16 v[0:3], v[156:159], v[208:211], v[0:3]
	s_setprio 0
	s_barrier
	s_add_i32 s50, s50, 2
	s_add_u32 s22, s22, 0x100
	s_addc_u32 s23, s23, 0
	s_add_u32 s48, s48, 0x100
	s_addc_u32 s49, s49, 0
	s_cmp_gt_u32 s50, 61
	s_cbranch_scc0 .LBB0_1179
	s_and_b64 vcc, exec, s[10:11]
	s_cbranch_vccz .LBB0_1182
	s_barrier
